# closing barrier of each K-loop compute segment moved up by 4 MFMAs
# baseline (speedup 1.0000x reference)
;     __device__ __forceinline__ const char* tile(const Unit& u, int t) const { return A + (size_t)u.pm * 2 * hstep() + (size_t)t * (BK * 2); }
;     __device__ __forceinline__ const char* tile(const Unit& u, int t) const { return U + (long)(t >> 2) * xoff + (size_t)u.pn * (1024 * 512) + (size_t)u.pm * 2 * hstep() + (size_t)(t & 3) * (BK * 2); }
; #define PG8_STAGE(bufoff, gbase, voff) do { _Pragma("unroll") for (int _i = 0; _i < 2; ++_i) \
;         __builtin_amdgcn_global_load_lds((const unsigned*)((const char*)(gbase) + (voff)[_i]), (PG8_LAS unsigned*)(lds + (bufoff) + ldsw + _i * 8192), 16, 0, 0); } while (0)
; #define PG8_LDA(dst, b, h) do { _Pragma("unroll") for (int m = 0; m < 4; ++m) _Pragma("unroll") for (int k = 0; k < 2; ++k) dst[m][k] = *(const PG8_LAS bf16x8*)(lds + PG8_SA(b, h) + aoff + m * 2048 + k * 1024); } while (0)
; #define PG8_LDB(dst, b, h) do { _Pragma("unroll") for (int n = 0; n < 2; ++n) _Pragma("unroll") for (int k = 0; k < 2; ++k) dst[n][k] = *(const PG8_LAS bf16x8*)(lds + PG8_SB(b, h) + boff + n * 2048 + k * 1024); } while (0)
; #define PG8_MMA(ai, bj, At, Bt) do { __builtin_amdgcn_s_setprio(1); _Pragma("unroll") for (int m = 0; m < 4; ++m) _Pragma("unroll") for (int n = 0; n < 2; ++n) _Pragma("unroll") for (int k = 0; k < 2; ++k) \
;         acc[ai][bj][m][n] = __builtin_amdgcn_mfma_f32_16x16x32_bf16(Bt[n][k], At[m][k], acc[ai][bj][m][n], 0, 0, 0); __builtin_amdgcn_s_setprio(0); } while (0)
; #define PG8_WAIT_V(n) asm volatile("s_waitcnt vmcnt(" #n ")" ::: "memory")
;     ...
;             const bool last = (t == nt - 2);
;             const char* a1 = AS.tile(cur, t + 1);
;             const char* a2 = last ? AS.tile(nu, 0) : AS.tile(cur, t + 2); const char* b2 = last ? nB : cB + (size_t)(t + 2) * kstep;
;             const char* a3 = last ? AS.tile(nu, 1) : AS.tile(cur, t + 3); const char* b3 = b2 + kstep;
;             PG8_LDB(B0, 0, 0); PG8_LDB(B1, 0, 1); PG8_SCHED; PG8_LDA(At, 0, 0); PG8_STAGE(PG8_SA(1, 1), a1 + hstepA, voffA);
;             PG8_WAIT_V(8); PG8_WAIT_L(0); PG8_BAR; PG8_MMA(0, 0, At, B0); PG8_MMA(0, 1, At, B1); PG8_BAR; PG8_SCHED;
;             PG8_LDA(At, 0, 1); PG8_STAGE(PG8_SB(0, 0), b2, voffB); PG8_STAGE(PG8_SB(0, 1), b2 + hstepB, voffB); PG8_STAGE(PG8_SA(0, 0), a2, voffA);
;             PG8_WAIT_V(8); PG8_WAIT_L(0); PG8_BAR; PG8_MMA(1, 0, At, B0); PG8_MMA(1, 1, At, B1); PG8_BAR; PG8_SCHED;
.LBB0_380:
	s_add_u32 s28, s1, s2
	s_addc_u32 s29, s77, s3
	s_add_u32 s48, s28, 0x100
	s_addc_u32 s49, s29, 0
	s_add_u32 s46, s82, s2
	s_addc_u32 s47, s83, s3
	s_add_u32 s28, s28, 0x180
	s_addc_u32 s29, s29, 0
	s_add_i32 s85, 0, 0x10000
	s_add_i32 s88, 0, 0x14000
	v_add_u32_e32 v158, s85, v174
	v_add_u32_e32 v186, s88, v174
	ds_read_b128 v[132:135], v158
	ds_read_b128 v[136:139], v158 offset:1024
	ds_read_b128 v[140:143], v158 offset:2048
	ds_read_b128 v[158:161], v158 offset:3072
	ds_read_b128 v[162:165], v186
	ds_read_b128 v[166:169], v186 offset:1024
	ds_read_b128 v[182:185], v186 offset:2048
	ds_read_b128 v[186:189], v186 offset:3072
	s_cmpk_eq_i32 s2, 0x700
	s_cselect_b32 s29, s81, s29
	s_cselect_b32 s28, s80, s28
	s_cselect_b32 s47, s76, s47
	s_cselect_b32 s46, s75, s46
	s_cselect_b32 s49, s79, s49
	s_cselect_b32 s48, s78, s48
	v_lshl_add_u64 v[222:223], v[128:129], 0, s[2:3]
	s_add_i32 m0, s27, 0xc000
	ds_read_b128 v[190:193], v180
	ds_read_b128 v[194:197], v180 offset:1024
	ds_read_b128 v[198:201], v180 offset:2048
	ds_read_b128 v[204:207], v180 offset:3072
	ds_read_b128 v[218:221], v180 offset:4096
	ds_read_b128 v[238:241], v180 offset:5120
	ds_read_b128 v[242:245], v180 offset:6144
	ds_read_b128 v[246:249], v180 offset:7168
	global_load_lds_dwordx4 v[222:223], off
	v_lshl_add_u64 v[222:223], v[130:131], 0, s[2:3]
	s_add_i32 m0, s27, 0xe000
	s_nop 0
	global_load_lds_dwordx4 v[222:223], off
	s_waitcnt vmcnt(8)
	s_waitcnt lgkmcnt(0)
	s_barrier
	s_setprio 1
	s_waitcnt lgkmcnt(0)
	v_mfma_f32_16x16x32_bf16 v[124:127], v[132:135], v[190:193], v[124:127]
	v_mfma_f32_16x16x32_bf16 v[120:123], v[140:143], v[190:193], v[120:123]
	v_mfma_f32_16x16x32_bf16 v[108:111], v[132:135], v[198:201], v[108:111]
	v_mfma_f32_16x16x32_bf16 v[104:107], v[140:143], v[198:201], v[104:107]
	v_mfma_f32_16x16x32_bf16 v[92:95], v[132:135], v[218:221], v[92:95]
	v_mfma_f32_16x16x32_bf16 v[88:91], v[140:143], v[218:221], v[88:91]
	v_mfma_f32_16x16x32_bf16 v[76:79], v[132:135], v[242:245], v[76:79]
	v_mfma_f32_16x16x32_bf16 v[72:75], v[140:143], v[242:245], v[72:75]
	v_mfma_f32_16x16x32_bf16 v[124:127], v[136:139], v[194:197], v[124:127]
	v_mfma_f32_16x16x32_bf16 v[120:123], v[158:161], v[194:197], v[120:123]
	v_mfma_f32_16x16x32_bf16 v[108:111], v[136:139], v[204:207], v[108:111]
	v_mfma_f32_16x16x32_bf16 v[104:107], v[158:161], v[204:207], v[104:107]
	v_mfma_f32_16x16x32_bf16 v[92:95], v[136:139], v[238:241], v[92:95]
	v_mfma_f32_16x16x32_bf16 v[88:91], v[158:161], v[238:241], v[88:91]
	v_mfma_f32_16x16x32_bf16 v[76:79], v[136:139], v[246:249], v[76:79]
	v_mfma_f32_16x16x32_bf16 v[72:75], v[158:161], v[246:249], v[72:75]
	s_setprio 0
	s_setprio 1
	v_mfma_f32_16x16x32_bf16 v[116:119], v[162:165], v[190:193], v[116:119]
	v_mfma_f32_16x16x32_bf16 v[112:115], v[182:185], v[190:193], v[112:115]
	v_mfma_f32_16x16x32_bf16 v[100:103], v[162:165], v[198:201], v[100:103]
	v_mfma_f32_16x16x32_bf16 v[96:99], v[182:185], v[198:201], v[96:99]
	v_mfma_f32_16x16x32_bf16 v[84:87], v[162:165], v[218:221], v[84:87]
	v_mfma_f32_16x16x32_bf16 v[80:83], v[182:185], v[218:221], v[80:83]
	v_mfma_f32_16x16x32_bf16 v[68:71], v[162:165], v[242:245], v[68:71]
	v_mfma_f32_16x16x32_bf16 v[64:67], v[182:185], v[242:245], v[64:67]
	v_mfma_f32_16x16x32_bf16 v[116:119], v[166:169], v[194:197], v[116:119]
	v_mfma_f32_16x16x32_bf16 v[112:115], v[186:189], v[194:197], v[112:115]
	v_mfma_f32_16x16x32_bf16 v[100:103], v[166:169], v[204:207], v[100:103]
	v_mfma_f32_16x16x32_bf16 v[96:99], v[186:189], v[204:207], v[96:99]
	s_barrier
	v_mfma_f32_16x16x32_bf16 v[84:87], v[166:169], v[238:241], v[84:87]
	v_mfma_f32_16x16x32_bf16 v[80:83], v[186:189], v[238:241], v[80:83]
	v_mfma_f32_16x16x32_bf16 v[68:71], v[166:169], v[246:249], v[68:71]
	v_mfma_f32_16x16x32_bf16 v[64:67], v[186:189], v[246:249], v[64:67]
	s_setprio 0
	s_add_i32 s85, s85, s52
	v_lshl_add_u64 v[222:223], s[46:47], 0, v[146:147]
	s_mov_b32 m0, s85
	ds_read_b128 v[190:193], v180 offset:16384
	ds_read_b128 v[194:197], v180 offset:17408
	ds_read_b128 v[198:201], v180 offset:18432
	ds_read_b128 v[204:207], v180 offset:19456
	ds_read_b128 v[218:221], v180 offset:20480
	ds_read_b128 v[238:241], v180 offset:21504
	ds_read_b128 v[242:245], v180 offset:22528
	ds_read_b128 v[246:249], v180 offset:23552
	global_load_lds_dwordx4 v[222:223], off
	s_add_i32 m0, s85, 0x2000
	s_add_u32 s86, s46, 0x40000
	v_lshl_add_u64 v[224:225], s[46:47], 0, v[150:151]
	s_addc_u32 s87, s47, 0
	s_add_i32 s85, s88, s52
	global_load_lds_dwordx4 v[224:225], off
	v_lshl_add_u64 v[250:251], s[86:87], 0, v[146:147]
	s_mov_b32 m0, s85
	s_nop 0
	global_load_lds_dwordx4 v[250:251], off
	v_lshl_add_u64 v[250:251], s[86:87], 0, v[150:151]
	s_add_i32 m0, s85, 0x2000
	s_nop 0
	global_load_lds_dwordx4 v[250:251], off
	v_lshl_add_u64 v[250:251], s[48:49], 0, v[144:145]
	s_mov_b32 m0, s27
	s_nop 0
	global_load_lds_dwordx4 v[250:251], off
	v_lshl_add_u64 v[250:251], s[48:49], 0, v[148:149]
	s_mov_b32 m0, s57
	s_nop 0
	global_load_lds_dwordx4 v[250:251], off
	s_waitcnt vmcnt(8)
	s_waitcnt lgkmcnt(0)
	s_barrier
; #define PG8_STAGE(bufoff, gbase, voff) do { _Pragma("unroll") for (int _i = 0; _i < 2; ++_i) \
;         __builtin_amdgcn_global_load_lds((const unsigned*)((const char*)(gbase) + (voff)[_i]), (PG8_LAS unsigned*)(lds + (bufoff) + ldsw + _i * 8192), 16, 0, 0); } while (0)
; #define PG8_LDA(dst, b, h) do { _Pragma("unroll") for (int m = 0; m < 4; ++m) _Pragma("unroll") for (int k = 0; k < 2; ++k) dst[m][k] = *(const PG8_LAS bf16x8*)(lds + PG8_SA(b, h) + aoff + m * 2048 + k * 1024); } while (0)
; #define PG8_LDB(dst, b, h) do { _Pragma("unroll") for (int n = 0; n < 2; ++n) _Pragma("unroll") for (int k = 0; k < 2; ++k) dst[n][k] = *(const PG8_LAS bf16x8*)(lds + PG8_SB(b, h) + boff + n * 2048 + k * 1024); } while (0)
; #define PG8_MMA(ai, bj, At, Bt) do { __builtin_amdgcn_s_setprio(1); _Pragma("unroll") for (int m = 0; m < 4; ++m) _Pragma("unroll") for (int n = 0; n < 2; ++n) _Pragma("unroll") for (int k = 0; k < 2; ++k) \
;         acc[ai][bj][m][n] = __builtin_amdgcn_mfma_f32_16x16x32_bf16(Bt[n][k], At[m][k], acc[ai][bj][m][n], 0, 0, 0); __builtin_amdgcn_s_setprio(0); } while (0)
; #define PG8_WAIT_V(n) asm volatile("s_waitcnt vmcnt(" #n ")" ::: "memory")
; #define PG8_WAIT_L(n) asm volatile("s_waitcnt lgkmcnt(" #n ")" ::: "memory")
; #define PG8_BAR __builtin_amdgcn_s_barrier()
; #define PG8_SCHED __builtin_amdgcn_sched_barrier(0)
;     ...
;             PG8_WAIT_V(8); PG8_WAIT_L(0); PG8_BAR; PG8_MMA(1, 0, At, B0); PG8_MMA(1, 1, At, B1); PG8_BAR; PG8_SCHED;
;             PG8_LDB(B0, 1, 0); PG8_LDB(B1, 1, 1); PG8_SCHED; PG8_LDA(At, 1, 0); PG8_STAGE(PG8_SA(0, 1), a2 + hstepA, voffA);
;             PG8_WAIT_V(8); PG8_WAIT_L(0); PG8_BAR; PG8_MMA(0, 0, At, B0); PG8_MMA(0, 1, At, B1); PG8_BAR; PG8_SCHED;
	s_setprio 1
	s_waitcnt lgkmcnt(0)
	v_mfma_f32_16x16x32_bf16 v[60:63], v[132:135], v[190:193], v[60:63]
	v_mfma_f32_16x16x32_bf16 v[56:59], v[140:143], v[190:193], v[56:59]
	v_mfma_f32_16x16x32_bf16 v[44:47], v[132:135], v[198:201], v[44:47]
	v_mfma_f32_16x16x32_bf16 v[40:43], v[140:143], v[198:201], v[40:43]
	v_mfma_f32_16x16x32_bf16 v[28:31], v[132:135], v[218:221], v[28:31]
	v_mfma_f32_16x16x32_bf16 v[24:27], v[140:143], v[218:221], v[24:27]
	v_mfma_f32_16x16x32_bf16 v[12:15], v[132:135], v[242:245], v[12:15]
	v_mfma_f32_16x16x32_bf16 v[8:11], v[140:143], v[242:245], v[8:11]
	v_mfma_f32_16x16x32_bf16 v[60:63], v[136:139], v[194:197], v[60:63]
	v_mfma_f32_16x16x32_bf16 v[56:59], v[158:161], v[194:197], v[56:59]
	v_mfma_f32_16x16x32_bf16 v[44:47], v[136:139], v[204:207], v[44:47]
	v_mfma_f32_16x16x32_bf16 v[40:43], v[158:161], v[204:207], v[40:43]
	v_mfma_f32_16x16x32_bf16 v[28:31], v[136:139], v[238:241], v[28:31]
	v_mfma_f32_16x16x32_bf16 v[24:27], v[158:161], v[238:241], v[24:27]
	v_mfma_f32_16x16x32_bf16 v[12:15], v[136:139], v[246:249], v[12:15]
	v_mfma_f32_16x16x32_bf16 v[8:11], v[158:161], v[246:249], v[8:11]
	s_setprio 0
	s_setprio 1
	v_mfma_f32_16x16x32_bf16 v[52:55], v[162:165], v[190:193], v[52:55]
	v_mfma_f32_16x16x32_bf16 v[48:51], v[182:185], v[190:193], v[48:51]
	v_mfma_f32_16x16x32_bf16 v[36:39], v[162:165], v[198:201], v[36:39]
	v_mfma_f32_16x16x32_bf16 v[32:35], v[182:185], v[198:201], v[32:35]
	v_mfma_f32_16x16x32_bf16 v[20:23], v[162:165], v[218:221], v[20:23]
	v_mfma_f32_16x16x32_bf16 v[16:19], v[182:185], v[218:221], v[16:19]
	v_mfma_f32_16x16x32_bf16 v[4:7], v[162:165], v[242:245], v[4:7]
	v_mfma_f32_16x16x32_bf16 v[0:3], v[182:185], v[242:245], v[0:3]
	v_mfma_f32_16x16x32_bf16 v[52:55], v[166:169], v[194:197], v[52:55]
	v_mfma_f32_16x16x32_bf16 v[48:51], v[186:189], v[194:197], v[48:51]
	v_mfma_f32_16x16x32_bf16 v[36:39], v[166:169], v[204:207], v[36:39]
	v_mfma_f32_16x16x32_bf16 v[32:35], v[186:189], v[204:207], v[32:35]
	s_barrier
	v_mfma_f32_16x16x32_bf16 v[20:23], v[166:169], v[238:241], v[20:23]
	v_mfma_f32_16x16x32_bf16 v[16:19], v[186:189], v[238:241], v[16:19]
	v_mfma_f32_16x16x32_bf16 v[4:7], v[166:169], v[246:249], v[4:7]
	v_mfma_f32_16x16x32_bf16 v[0:3], v[186:189], v[246:249], v[0:3]
	s_setprio 0
	s_add_i32 s85, 0, 0x18000
	s_add_i32 s86, 0, 0x1c000
	v_add_u32_e32 v158, s85, v174
	v_add_u32_e32 v186, s86, v174
	ds_read_b128 v[132:135], v158
	ds_read_b128 v[136:139], v158 offset:1024
	ds_read_b128 v[140:143], v158 offset:2048
	ds_read_b128 v[158:161], v158 offset:3072
	ds_read_b128 v[162:165], v186
	ds_read_b128 v[166:169], v186 offset:1024
	ds_read_b128 v[182:185], v186 offset:2048
	ds_read_b128 v[186:189], v186 offset:3072
	s_add_u32 s48, s48, 0x40000
	s_addc_u32 s49, s49, 0
	s_mov_b32 m0, s58
	v_lshl_add_u64 v[250:251], s[48:49], 0, v[144:145]
	ds_read_b128 v[190:193], v180 offset:32768
	ds_read_b128 v[194:197], v180 offset:33792
	ds_read_b128 v[198:201], v180 offset:34816
	ds_read_b128 v[204:207], v180 offset:35840
	ds_read_b128 v[218:221], v180 offset:36864
	ds_read_b128 v[238:241], v180 offset:37888
	ds_read_b128 v[242:245], v180 offset:38912
	ds_read_b128 v[246:249], v180 offset:39936
	global_load_lds_dwordx4 v[250:251], off
	v_lshl_add_u64 v[250:251], s[48:49], 0, v[148:149]
	s_mov_b32 m0, s59
	s_nop 0
	global_load_lds_dwordx4 v[250:251], off
	s_waitcnt vmcnt(8)
	s_waitcnt lgkmcnt(0)
	s_barrier
	s_setprio 1
	s_waitcnt lgkmcnt(0)
	v_mfma_f32_16x16x32_bf16 v[124:127], v[132:135], v[190:193], v[124:127]
	v_mfma_f32_16x16x32_bf16 v[120:123], v[140:143], v[190:193], v[120:123]
	v_mfma_f32_16x16x32_bf16 v[108:111], v[132:135], v[198:201], v[108:111]
	v_mfma_f32_16x16x32_bf16 v[104:107], v[140:143], v[198:201], v[104:107]
	v_mfma_f32_16x16x32_bf16 v[92:95], v[132:135], v[218:221], v[92:95]
	v_mfma_f32_16x16x32_bf16 v[88:91], v[140:143], v[218:221], v[88:91]
	v_mfma_f32_16x16x32_bf16 v[76:79], v[132:135], v[242:245], v[76:79]
	v_mfma_f32_16x16x32_bf16 v[72:75], v[140:143], v[242:245], v[72:75]
	v_mfma_f32_16x16x32_bf16 v[124:127], v[136:139], v[194:197], v[124:127]
	v_mfma_f32_16x16x32_bf16 v[120:123], v[158:161], v[194:197], v[120:123]
	v_mfma_f32_16x16x32_bf16 v[108:111], v[136:139], v[204:207], v[108:111]
	v_mfma_f32_16x16x32_bf16 v[104:107], v[158:161], v[204:207], v[104:107]
	v_mfma_f32_16x16x32_bf16 v[92:95], v[136:139], v[238:241], v[92:95]
	v_mfma_f32_16x16x32_bf16 v[88:91], v[158:161], v[238:241], v[88:91]
	v_mfma_f32_16x16x32_bf16 v[76:79], v[136:139], v[246:249], v[76:79]
	v_mfma_f32_16x16x32_bf16 v[72:75], v[158:161], v[246:249], v[72:75]
	s_setprio 0
	s_setprio 1
	v_mfma_f32_16x16x32_bf16 v[116:119], v[162:165], v[190:193], v[116:119]
	v_mfma_f32_16x16x32_bf16 v[112:115], v[182:185], v[190:193], v[112:115]
	v_mfma_f32_16x16x32_bf16 v[100:103], v[162:165], v[198:201], v[100:103]
	v_mfma_f32_16x16x32_bf16 v[96:99], v[182:185], v[198:201], v[96:99]
	v_mfma_f32_16x16x32_bf16 v[84:87], v[162:165], v[218:221], v[84:87]
	v_mfma_f32_16x16x32_bf16 v[80:83], v[182:185], v[218:221], v[80:83]
	v_mfma_f32_16x16x32_bf16 v[68:71], v[162:165], v[242:245], v[68:71]
	v_mfma_f32_16x16x32_bf16 v[64:67], v[182:185], v[242:245], v[64:67]
	v_mfma_f32_16x16x32_bf16 v[116:119], v[166:169], v[194:197], v[116:119]
	v_mfma_f32_16x16x32_bf16 v[112:115], v[186:189], v[194:197], v[112:115]
	v_mfma_f32_16x16x32_bf16 v[100:103], v[166:169], v[204:207], v[100:103]
	v_mfma_f32_16x16x32_bf16 v[96:99], v[186:189], v[204:207], v[96:99]
	s_barrier
; #define PG8_STAGE(bufoff, gbase, voff) do { _Pragma("unroll") for (int _i = 0; _i < 2; ++_i) \
;         __builtin_amdgcn_global_load_lds((const unsigned*)((const char*)(gbase) + (voff)[_i]), (PG8_LAS unsigned*)(lds + (bufoff) + ldsw + _i * 8192), 16, 0, 0); } while (0)
; #define PG8_LDA(dst, b, h) do { _Pragma("unroll") for (int m = 0; m < 4; ++m) _Pragma("unroll") for (int k = 0; k < 2; ++k) dst[m][k] = *(const PG8_LAS bf16x8*)(lds + PG8_SA(b, h) + aoff + m * 2048 + k * 1024); } while (0)
; #define PG8_MMA(ai, bj, At, Bt) do { __builtin_amdgcn_s_setprio(1); _Pragma("unroll") for (int m = 0; m < 4; ++m) _Pragma("unroll") for (int n = 0; n < 2; ++n) _Pragma("unroll") for (int k = 0; k < 2; ++k) \
;         acc[ai][bj][m][n] = __builtin_amdgcn_mfma_f32_16x16x32_bf16(Bt[n][k], At[m][k], acc[ai][bj][m][n], 0, 0, 0); __builtin_amdgcn_s_setprio(0); } while (0)
; #define PG8_WAIT_V(n) asm volatile("s_waitcnt vmcnt(" #n ")" ::: "memory")
; #define PG8_WAIT_L(n) asm volatile("s_waitcnt lgkmcnt(" #n ")" ::: "memory")
; #define PG8_BAR __builtin_amdgcn_s_barrier()
; #define PG8_SCHED __builtin_amdgcn_sched_barrier(0)
;     ...
;             PG8_LDA(At, 1, 1); PG8_STAGE(PG8_SB(1, 0), b3, voffB); PG8_STAGE(PG8_SB(1, 1), b3 + hstepB, voffB); PG8_STAGE(PG8_SA(1, 0), a3, voffA);
;             PG8_WAIT_V(8); PG8_WAIT_L(0); PG8_BAR; PG8_MMA(1, 0, At, B0); PG8_MMA(1, 1, At, B1); PG8_BAR; PG8_SCHED;
;         }
;         if (wr == 0) PG8_BAR;
;         if (!has_next && wmat && gtid * 128u < wbytes) asm volatile("global_load_dword %0, %1, off" : "+v"(warmm) : "v"(wmat + (size_t)gtid * 128u) : "memory");
;         if (!has_next && warm) warmv = *(const volatile unsigned*)(warm + ((size_t)(tid & 255) * wK + (size_t)(tid >> 8) * BK) * 2);
;         if (ui == 0) hook();
	v_mfma_f32_16x16x32_bf16 v[84:87], v[166:169], v[238:241], v[84:87]
	v_mfma_f32_16x16x32_bf16 v[80:83], v[186:189], v[238:241], v[80:83]
	v_mfma_f32_16x16x32_bf16 v[68:71], v[166:169], v[246:249], v[68:71]
	v_mfma_f32_16x16x32_bf16 v[64:67], v[186:189], v[246:249], v[64:67]
	s_setprio 0
	s_add_i32 s48, s85, s52
	v_lshl_add_u64 v[222:223], v[222:223], 0, s[90:91]
	s_mov_b32 m0, s48
	ds_read_b128 v[190:193], v180 offset:49152
	ds_read_b128 v[194:197], v180 offset:50176
	ds_read_b128 v[198:201], v180 offset:51200
	ds_read_b128 v[204:207], v180 offset:52224
	ds_read_b128 v[218:221], v180 offset:53248
	ds_read_b128 v[238:241], v180 offset:54272
	ds_read_b128 v[242:245], v180 offset:55296
	ds_read_b128 v[246:249], v180 offset:56320
	global_load_lds_dwordx4 v[222:223], off
	s_add_i32 m0, s48, 0x2000
	s_add_u32 s46, s46, 0x40080
	v_lshl_add_u64 v[222:223], v[224:225], 0, s[90:91]
	s_addc_u32 s47, s47, 0
	s_add_i32 s48, s86, s52
	global_load_lds_dwordx4 v[222:223], off
	v_lshl_add_u64 v[222:223], s[46:47], 0, v[146:147]
	s_mov_b32 m0, s48
	s_nop 0
	global_load_lds_dwordx4 v[222:223], off
	v_lshl_add_u64 v[222:223], s[46:47], 0, v[150:151]
	s_add_i32 m0, s48, 0x2000
	s_nop 0
	global_load_lds_dwordx4 v[222:223], off
	v_lshl_add_u64 v[222:223], s[28:29], 0, v[144:145]
	s_mov_b32 m0, s60
	s_nop 0
	global_load_lds_dwordx4 v[222:223], off
	v_lshl_add_u64 v[222:223], s[28:29], 0, v[148:149]
	s_mov_b32 m0, s61
	s_nop 0
	global_load_lds_dwordx4 v[222:223], off
	s_waitcnt vmcnt(8)
	s_waitcnt lgkmcnt(0)
	s_barrier
	s_setprio 1
	s_waitcnt lgkmcnt(0)
	v_mfma_f32_16x16x32_bf16 v[60:63], v[132:135], v[190:193], v[60:63]
	v_mfma_f32_16x16x32_bf16 v[56:59], v[140:143], v[190:193], v[56:59]
	v_mfma_f32_16x16x32_bf16 v[44:47], v[132:135], v[198:201], v[44:47]
	v_mfma_f32_16x16x32_bf16 v[40:43], v[140:143], v[198:201], v[40:43]
	v_mfma_f32_16x16x32_bf16 v[28:31], v[132:135], v[218:221], v[28:31]
	v_mfma_f32_16x16x32_bf16 v[24:27], v[140:143], v[218:221], v[24:27]
	v_mfma_f32_16x16x32_bf16 v[12:15], v[132:135], v[242:245], v[12:15]
	v_mfma_f32_16x16x32_bf16 v[8:11], v[140:143], v[242:245], v[8:11]
	v_mfma_f32_16x16x32_bf16 v[60:63], v[136:139], v[194:197], v[60:63]
	v_mfma_f32_16x16x32_bf16 v[56:59], v[158:161], v[194:197], v[56:59]
	v_mfma_f32_16x16x32_bf16 v[44:47], v[136:139], v[204:207], v[44:47]
	v_mfma_f32_16x16x32_bf16 v[40:43], v[158:161], v[204:207], v[40:43]
	v_mfma_f32_16x16x32_bf16 v[28:31], v[136:139], v[238:241], v[28:31]
	v_mfma_f32_16x16x32_bf16 v[24:27], v[158:161], v[238:241], v[24:27]
	v_mfma_f32_16x16x32_bf16 v[12:15], v[136:139], v[246:249], v[12:15]
	v_mfma_f32_16x16x32_bf16 v[8:11], v[158:161], v[246:249], v[8:11]
	s_setprio 0
	s_setprio 1
	v_mfma_f32_16x16x32_bf16 v[52:55], v[162:165], v[190:193], v[52:55]
	v_mfma_f32_16x16x32_bf16 v[48:51], v[182:185], v[190:193], v[48:51]
	v_mfma_f32_16x16x32_bf16 v[36:39], v[162:165], v[198:201], v[36:39]
	v_mfma_f32_16x16x32_bf16 v[32:35], v[182:185], v[198:201], v[32:35]
	v_mfma_f32_16x16x32_bf16 v[20:23], v[162:165], v[218:221], v[20:23]
	v_mfma_f32_16x16x32_bf16 v[16:19], v[182:185], v[218:221], v[16:19]
	v_mfma_f32_16x16x32_bf16 v[4:7], v[162:165], v[242:245], v[4:7]
	v_mfma_f32_16x16x32_bf16 v[0:3], v[182:185], v[242:245], v[0:3]
	v_mfma_f32_16x16x32_bf16 v[52:55], v[166:169], v[194:197], v[52:55]
	v_mfma_f32_16x16x32_bf16 v[48:51], v[186:189], v[194:197], v[48:51]
	v_mfma_f32_16x16x32_bf16 v[36:39], v[166:169], v[204:207], v[36:39]
	v_mfma_f32_16x16x32_bf16 v[32:35], v[186:189], v[204:207], v[32:35]
	s_barrier
	v_mfma_f32_16x16x32_bf16 v[20:23], v[166:169], v[238:241], v[20:23]
	v_mfma_f32_16x16x32_bf16 v[16:19], v[186:189], v[238:241], v[16:19]
	v_mfma_f32_16x16x32_bf16 v[4:7], v[166:169], v[246:249], v[4:7]
	v_mfma_f32_16x16x32_bf16 v[0:3], v[186:189], v[246:249], v[0:3]
	s_setprio 0
	s_add_i32 s84, s84, 2
	s_add_u32 s2, s2, 0x100
	s_addc_u32 s3, s3, 0
	s_cmp_gt_u32 s84, 13
	s_cbranch_scc0 .LBB0_380
	s_and_b64 vcc, exec, s[30:31]
	s_cbranch_vccz .LBB0_385
	s_barrier
	s_and_b64 s[28:29], s[20:21], s[44:45]
	s_and_saveexec_b64 s[2:3], s[28:29]
	s_cbranch_execnz .LBB0_386

;     __device__ __forceinline__ const char* tile(const Unit& u, int t) const { return A + (size_t)u.pm * 2 * hstep() + (size_t)t * (BK * 2); }
;     __device__ __forceinline__ const char* tile(const Unit& u, int t) const { return U + (long)(t >> 2) * xoff + (size_t)u.pn * (1024 * 512) + (size_t)u.pm * 2 * hstep() + (size_t)(t & 3) * (BK * 2); }
; #define PG8_STAGE(bufoff, gbase, voff) do { _Pragma("unroll") for (int _i = 0; _i < 2; ++_i) \
;         __builtin_amdgcn_global_load_lds((const unsigned*)((const char*)(gbase) + (voff)[_i]), (PG8_LAS unsigned*)(lds + (bufoff) + ldsw + _i * 8192), 16, 0, 0); } while (0)
; #define PG8_LDA(dst, b, h) do { _Pragma("unroll") for (int m = 0; m < 4; ++m) _Pragma("unroll") for (int k = 0; k < 2; ++k) dst[m][k] = *(const PG8_LAS bf16x8*)(lds + PG8_SA(b, h) + aoff + m * 2048 + k * 1024); } while (0)
; #define PG8_LDB(dst, b, h) do { _Pragma("unroll") for (int n = 0; n < 2; ++n) _Pragma("unroll") for (int k = 0; k < 2; ++k) dst[n][k] = *(const PG8_LAS bf16x8*)(lds + PG8_SB(b, h) + boff + n * 2048 + k * 1024); } while (0)
; #define PG8_MMA(ai, bj, At, Bt) do { __builtin_amdgcn_s_setprio(1); _Pragma("unroll") for (int m = 0; m < 4; ++m) _Pragma("unroll") for (int n = 0; n < 2; ++n) _Pragma("unroll") for (int k = 0; k < 2; ++k) \
;         acc[ai][bj][m][n] = __builtin_amdgcn_mfma_f32_16x16x32_bf16(Bt[n][k], At[m][k], acc[ai][bj][m][n], 0, 0, 0); __builtin_amdgcn_s_setprio(0); } while (0)
; #define PG8_BAR __builtin_amdgcn_s_barrier()
;     ...
;         for (int t = 0; t < nt; t += 2) {
;             const bool last = (t == nt - 2);
;             const char* a1 = AS.tile(cur, t + 1);
;             const char* a2 = last ? AS.tile(nu, 0) : AS.tile(cur, t + 2); const char* b2 = last ? nB : cB + (size_t)(t + 2) * kstep;
;             const char* a3 = last ? AS.tile(nu, 1) : AS.tile(cur, t + 3); const char* b3 = b2 + kstep;
;             PG8_LDB(B0, 0, 0); PG8_LDB(B1, 0, 1); PG8_SCHED; PG8_LDA(At, 0, 0); PG8_STAGE(PG8_SA(1, 1), a1 + hstepA, voffA);
;             PG8_WAIT_V(8); PG8_WAIT_L(0); PG8_BAR; PG8_MMA(0, 0, At, B0); PG8_MMA(0, 1, At, B1); PG8_BAR; PG8_SCHED;
;             PG8_LDA(At, 0, 1); PG8_STAGE(PG8_SB(0, 0), b2, voffB); PG8_STAGE(PG8_SB(0, 1), b2 + hstepB, voffB); PG8_STAGE(PG8_SA(0, 0), a2, voffA);
;             PG8_WAIT_V(8); PG8_WAIT_L(0); PG8_BAR; PG8_MMA(1, 0, At, B0); PG8_MMA(1, 1, At, B1); PG8_BAR; PG8_SCHED;
.LBB0_451:
	s_add_u32 s20, s61, s18
	s_addc_u32 s21, s64, s19
	s_add_u32 s26, s20, 0x3600100
	s_addc_u32 s27, s21, 0
	s_add_u32 s24, s65, s18
	s_addc_u32 s25, s66, s19
	s_add_u32 s20, s20, 0x3600180
	s_addc_u32 s21, s21, 0
	s_add_i32 s68, 0, 0x10000
	s_add_i32 s70, 0, 0x14000
	v_add_u32_e32 v144, s68, v203
	v_add_u32_e32 v174, s70, v203
	ds_read_b128 v[132:135], v144
	ds_read_b128 v[136:139], v144 offset:1024
	ds_read_b128 v[140:143], v144 offset:2048
	ds_read_b128 v[144:147], v144 offset:3072
	ds_read_b128 v[148:151], v174
	ds_read_b128 v[152:155], v174 offset:1024
	ds_read_b128 v[170:173], v174 offset:2048
	ds_read_b128 v[174:177], v174 offset:3072
	s_cmpk_eq_i32 s18, 0x700
	s_cselect_b32 s21, s60, s21
	s_cselect_b32 s20, s59, s20
	s_cselect_b32 s25, s57, s25
	s_cselect_b32 s24, s56, s24
	s_cselect_b32 s27, s58, s27
	s_cselect_b32 s26, s3, s26
	v_lshl_add_u64 v[238:239], v[112:113], 0, s[18:19]
	s_add_i32 m0, s35, 0xc000
	ds_read_b128 v[178:181], v211
	ds_read_b128 v[182:185], v211 offset:1024
	ds_read_b128 v[186:189], v211 offset:2048
	ds_read_b128 v[190:193], v211 offset:3072
	ds_read_b128 v[194:197], v211 offset:4096
	ds_read_b128 v[198:201], v211 offset:5120
	ds_read_b128 v[218:221], v211 offset:6144
	ds_read_b128 v[222:225], v211 offset:7168
	global_load_lds_dwordx4 v[238:239], off
	v_lshl_add_u64 v[238:239], v[114:115], 0, s[18:19]
	s_add_i32 m0, s35, 0xe000
	s_nop 0
	global_load_lds_dwordx4 v[238:239], off
	s_waitcnt vmcnt(8)
	s_waitcnt lgkmcnt(0)
	s_barrier
	s_setprio 1
	s_waitcnt lgkmcnt(0)
	v_mfma_f32_16x16x32_bf16 v[120:123], v[132:135], v[178:181], v[120:123]
	v_mfma_f32_16x16x32_bf16 v[116:119], v[140:143], v[178:181], v[116:119]
	v_mfma_f32_16x16x32_bf16 v[108:111], v[132:135], v[186:189], v[108:111]
	v_mfma_f32_16x16x32_bf16 v[104:107], v[140:143], v[186:189], v[104:107]
	v_mfma_f32_16x16x32_bf16 v[92:95], v[132:135], v[194:197], v[92:95]
	v_mfma_f32_16x16x32_bf16 v[88:91], v[140:143], v[194:197], v[88:91]
	v_mfma_f32_16x16x32_bf16 v[76:79], v[132:135], v[218:221], v[76:79]
	v_mfma_f32_16x16x32_bf16 v[72:75], v[140:143], v[218:221], v[72:75]
	v_mfma_f32_16x16x32_bf16 v[120:123], v[136:139], v[182:185], v[120:123]
	v_mfma_f32_16x16x32_bf16 v[116:119], v[144:147], v[182:185], v[116:119]
	v_mfma_f32_16x16x32_bf16 v[108:111], v[136:139], v[190:193], v[108:111]
	v_mfma_f32_16x16x32_bf16 v[104:107], v[144:147], v[190:193], v[104:107]
	v_mfma_f32_16x16x32_bf16 v[92:95], v[136:139], v[198:201], v[92:95]
	v_mfma_f32_16x16x32_bf16 v[88:91], v[144:147], v[198:201], v[88:91]
	v_mfma_f32_16x16x32_bf16 v[76:79], v[136:139], v[222:225], v[76:79]
	v_mfma_f32_16x16x32_bf16 v[72:75], v[144:147], v[222:225], v[72:75]
	s_setprio 0
	s_setprio 1
	v_mfma_f32_16x16x32_bf16 v[128:131], v[148:151], v[178:181], v[128:131]
	v_mfma_f32_16x16x32_bf16 v[124:127], v[170:173], v[178:181], v[124:127]
	v_mfma_f32_16x16x32_bf16 v[100:103], v[148:151], v[186:189], v[100:103]
	v_mfma_f32_16x16x32_bf16 v[96:99], v[170:173], v[186:189], v[96:99]
	v_mfma_f32_16x16x32_bf16 v[84:87], v[148:151], v[194:197], v[84:87]
	v_mfma_f32_16x16x32_bf16 v[80:83], v[170:173], v[194:197], v[80:83]
	v_mfma_f32_16x16x32_bf16 v[68:71], v[148:151], v[218:221], v[68:71]
	v_mfma_f32_16x16x32_bf16 v[64:67], v[170:173], v[218:221], v[64:67]
	v_mfma_f32_16x16x32_bf16 v[128:131], v[152:155], v[182:185], v[128:131]
	v_mfma_f32_16x16x32_bf16 v[124:127], v[174:177], v[182:185], v[124:127]
	v_mfma_f32_16x16x32_bf16 v[100:103], v[152:155], v[190:193], v[100:103]
	v_mfma_f32_16x16x32_bf16 v[96:99], v[174:177], v[190:193], v[96:99]
	s_barrier
	v_mfma_f32_16x16x32_bf16 v[84:87], v[152:155], v[198:201], v[84:87]
	v_mfma_f32_16x16x32_bf16 v[80:83], v[174:177], v[198:201], v[80:83]
	v_mfma_f32_16x16x32_bf16 v[68:71], v[152:155], v[222:225], v[68:71]
	v_mfma_f32_16x16x32_bf16 v[64:67], v[174:177], v[222:225], v[64:67]
	s_setprio 0
	s_add_i32 s68, s68, s31
	v_lshl_add_u64 v[238:239], s[24:25], 0, v[208:209]
	s_mov_b32 m0, s68
	ds_read_b128 v[178:181], v211 offset:16384
	ds_read_b128 v[182:185], v211 offset:17408
	ds_read_b128 v[186:189], v211 offset:18432
	ds_read_b128 v[190:193], v211 offset:19456
	ds_read_b128 v[194:197], v211 offset:20480
	ds_read_b128 v[198:201], v211 offset:21504
	ds_read_b128 v[218:221], v211 offset:22528
	ds_read_b128 v[222:225], v211 offset:23552
	global_load_lds_dwordx4 v[238:239], off
	s_add_i32 m0, s68, 0x2000
	s_add_u32 s68, s24, 0x40000
	v_lshl_add_u64 v[240:241], s[24:25], 0, v[156:157]
	s_addc_u32 s69, s25, 0
	s_add_i32 s70, s70, s31
	global_load_lds_dwordx4 v[240:241], off
	v_lshl_add_u64 v[242:243], s[68:69], 0, v[208:209]
	s_mov_b32 m0, s70
	s_nop 0
	global_load_lds_dwordx4 v[242:243], off
	v_lshl_add_u64 v[242:243], s[68:69], 0, v[156:157]
	s_add_i32 m0, s70, 0x2000
	s_nop 0
	global_load_lds_dwordx4 v[242:243], off
	v_lshl_add_u64 v[242:243], s[26:27], 0, v[160:161]
	s_mov_b32 m0, s35
	s_nop 0
	global_load_lds_dwordx4 v[242:243], off
	v_lshl_add_u64 v[242:243], s[26:27], 0, v[158:159]
	s_mov_b32 m0, s44
	s_nop 0
	global_load_lds_dwordx4 v[242:243], off
	s_waitcnt vmcnt(8)
	s_waitcnt lgkmcnt(0)
	s_barrier
; #define PG8_STAGE(bufoff, gbase, voff) do { _Pragma("unroll") for (int _i = 0; _i < 2; ++_i) \
;         __builtin_amdgcn_global_load_lds((const unsigned*)((const char*)(gbase) + (voff)[_i]), (PG8_LAS unsigned*)(lds + (bufoff) + ldsw + _i * 8192), 16, 0, 0); } while (0)
; #define PG8_LDA(dst, b, h) do { _Pragma("unroll") for (int m = 0; m < 4; ++m) _Pragma("unroll") for (int k = 0; k < 2; ++k) dst[m][k] = *(const PG8_LAS bf16x8*)(lds + PG8_SA(b, h) + aoff + m * 2048 + k * 1024); } while (0)
; #define PG8_LDB(dst, b, h) do { _Pragma("unroll") for (int n = 0; n < 2; ++n) _Pragma("unroll") for (int k = 0; k < 2; ++k) dst[n][k] = *(const PG8_LAS bf16x8*)(lds + PG8_SB(b, h) + boff + n * 2048 + k * 1024); } while (0)
; #define PG8_MMA(ai, bj, At, Bt) do { __builtin_amdgcn_s_setprio(1); _Pragma("unroll") for (int m = 0; m < 4; ++m) _Pragma("unroll") for (int n = 0; n < 2; ++n) _Pragma("unroll") for (int k = 0; k < 2; ++k) \
;         acc[ai][bj][m][n] = __builtin_amdgcn_mfma_f32_16x16x32_bf16(Bt[n][k], At[m][k], acc[ai][bj][m][n], 0, 0, 0); __builtin_amdgcn_s_setprio(0); } while (0)
; #define PG8_WAIT_V(n) asm volatile("s_waitcnt vmcnt(" #n ")" ::: "memory")
; #define PG8_WAIT_L(n) asm volatile("s_waitcnt lgkmcnt(" #n ")" ::: "memory")
; #define PG8_BAR __builtin_amdgcn_s_barrier()
; #define PG8_SCHED __builtin_amdgcn_sched_barrier(0)
;     ...
;             PG8_WAIT_V(8); PG8_WAIT_L(0); PG8_BAR; PG8_MMA(1, 0, At, B0); PG8_MMA(1, 1, At, B1); PG8_BAR; PG8_SCHED;
;             PG8_LDB(B0, 1, 0); PG8_LDB(B1, 1, 1); PG8_SCHED; PG8_LDA(At, 1, 0); PG8_STAGE(PG8_SA(0, 1), a2 + hstepA, voffA);
;             PG8_WAIT_V(8); PG8_WAIT_L(0); PG8_BAR; PG8_MMA(0, 0, At, B0); PG8_MMA(0, 1, At, B1); PG8_BAR; PG8_SCHED;
	s_setprio 1
	s_waitcnt lgkmcnt(0)
	v_mfma_f32_16x16x32_bf16 v[60:63], v[132:135], v[178:181], v[60:63]
	v_mfma_f32_16x16x32_bf16 v[56:59], v[140:143], v[178:181], v[56:59]
	v_mfma_f32_16x16x32_bf16 v[44:47], v[132:135], v[186:189], v[44:47]
	v_mfma_f32_16x16x32_bf16 v[40:43], v[140:143], v[186:189], v[40:43]
	v_mfma_f32_16x16x32_bf16 v[28:31], v[132:135], v[194:197], v[28:31]
	v_mfma_f32_16x16x32_bf16 v[24:27], v[140:143], v[194:197], v[24:27]
	v_mfma_f32_16x16x32_bf16 v[12:15], v[132:135], v[218:221], v[12:15]
	v_mfma_f32_16x16x32_bf16 v[8:11], v[140:143], v[218:221], v[8:11]
	v_mfma_f32_16x16x32_bf16 v[60:63], v[136:139], v[182:185], v[60:63]
	v_mfma_f32_16x16x32_bf16 v[56:59], v[144:147], v[182:185], v[56:59]
	v_mfma_f32_16x16x32_bf16 v[44:47], v[136:139], v[190:193], v[44:47]
	v_mfma_f32_16x16x32_bf16 v[40:43], v[144:147], v[190:193], v[40:43]
	v_mfma_f32_16x16x32_bf16 v[28:31], v[136:139], v[198:201], v[28:31]
	v_mfma_f32_16x16x32_bf16 v[24:27], v[144:147], v[198:201], v[24:27]
	v_mfma_f32_16x16x32_bf16 v[12:15], v[136:139], v[222:225], v[12:15]
	v_mfma_f32_16x16x32_bf16 v[8:11], v[144:147], v[222:225], v[8:11]
	s_setprio 0
	s_setprio 1
	v_mfma_f32_16x16x32_bf16 v[52:55], v[148:151], v[178:181], v[52:55]
	v_mfma_f32_16x16x32_bf16 v[48:51], v[170:173], v[178:181], v[48:51]
	v_mfma_f32_16x16x32_bf16 v[36:39], v[148:151], v[186:189], v[36:39]
	v_mfma_f32_16x16x32_bf16 v[32:35], v[170:173], v[186:189], v[32:35]
	v_mfma_f32_16x16x32_bf16 v[20:23], v[148:151], v[194:197], v[20:23]
	v_mfma_f32_16x16x32_bf16 v[16:19], v[170:173], v[194:197], v[16:19]
	v_mfma_f32_16x16x32_bf16 v[4:7], v[148:151], v[218:221], v[4:7]
	v_mfma_f32_16x16x32_bf16 v[0:3], v[170:173], v[218:221], v[0:3]
	v_mfma_f32_16x16x32_bf16 v[52:55], v[152:155], v[182:185], v[52:55]
	v_mfma_f32_16x16x32_bf16 v[48:51], v[174:177], v[182:185], v[48:51]
	v_mfma_f32_16x16x32_bf16 v[36:39], v[152:155], v[190:193], v[36:39]
	v_mfma_f32_16x16x32_bf16 v[32:35], v[174:177], v[190:193], v[32:35]
	s_barrier
	v_mfma_f32_16x16x32_bf16 v[20:23], v[152:155], v[198:201], v[20:23]
	v_mfma_f32_16x16x32_bf16 v[16:19], v[174:177], v[198:201], v[16:19]
	v_mfma_f32_16x16x32_bf16 v[4:7], v[152:155], v[222:225], v[4:7]
	v_mfma_f32_16x16x32_bf16 v[0:3], v[174:177], v[222:225], v[0:3]
	s_setprio 0
	s_add_i32 s68, 0, 0x18000
	s_add_i32 s69, 0, 0x1c000
	v_add_u32_e32 v144, s68, v203
	v_add_u32_e32 v174, s69, v203
	ds_read_b128 v[132:135], v144
	ds_read_b128 v[136:139], v144 offset:1024
	ds_read_b128 v[140:143], v144 offset:2048
	ds_read_b128 v[144:147], v144 offset:3072
	ds_read_b128 v[148:151], v174
	ds_read_b128 v[152:155], v174 offset:1024
	ds_read_b128 v[170:173], v174 offset:2048
	ds_read_b128 v[174:177], v174 offset:3072
	s_add_u32 s26, s26, 0x40000
	s_addc_u32 s27, s27, 0
	s_mov_b32 m0, s45
	v_lshl_add_u64 v[242:243], s[26:27], 0, v[160:161]
	ds_read_b128 v[178:181], v211 offset:32768
	ds_read_b128 v[182:185], v211 offset:33792
	ds_read_b128 v[186:189], v211 offset:34816
	ds_read_b128 v[190:193], v211 offset:35840
	ds_read_b128 v[194:197], v211 offset:36864
	ds_read_b128 v[198:201], v211 offset:37888
	ds_read_b128 v[218:221], v211 offset:38912
	ds_read_b128 v[222:225], v211 offset:39936
	global_load_lds_dwordx4 v[242:243], off
	v_lshl_add_u64 v[242:243], s[26:27], 0, v[158:159]
	s_mov_b32 m0, s46
	s_nop 0
	global_load_lds_dwordx4 v[242:243], off
	s_waitcnt vmcnt(8)
	s_waitcnt lgkmcnt(0)
	s_barrier
	s_setprio 1
	s_waitcnt lgkmcnt(0)
	v_mfma_f32_16x16x32_bf16 v[120:123], v[132:135], v[178:181], v[120:123]
	v_mfma_f32_16x16x32_bf16 v[116:119], v[140:143], v[178:181], v[116:119]
	v_mfma_f32_16x16x32_bf16 v[108:111], v[132:135], v[186:189], v[108:111]
	v_mfma_f32_16x16x32_bf16 v[104:107], v[140:143], v[186:189], v[104:107]
	v_mfma_f32_16x16x32_bf16 v[92:95], v[132:135], v[194:197], v[92:95]
	v_mfma_f32_16x16x32_bf16 v[88:91], v[140:143], v[194:197], v[88:91]
	v_mfma_f32_16x16x32_bf16 v[76:79], v[132:135], v[218:221], v[76:79]
	v_mfma_f32_16x16x32_bf16 v[72:75], v[140:143], v[218:221], v[72:75]
	v_mfma_f32_16x16x32_bf16 v[120:123], v[136:139], v[182:185], v[120:123]
	v_mfma_f32_16x16x32_bf16 v[116:119], v[144:147], v[182:185], v[116:119]
	v_mfma_f32_16x16x32_bf16 v[108:111], v[136:139], v[190:193], v[108:111]
	v_mfma_f32_16x16x32_bf16 v[104:107], v[144:147], v[190:193], v[104:107]
	v_mfma_f32_16x16x32_bf16 v[92:95], v[136:139], v[198:201], v[92:95]
	v_mfma_f32_16x16x32_bf16 v[88:91], v[144:147], v[198:201], v[88:91]
	v_mfma_f32_16x16x32_bf16 v[76:79], v[136:139], v[222:225], v[76:79]
	v_mfma_f32_16x16x32_bf16 v[72:75], v[144:147], v[222:225], v[72:75]
	s_setprio 0
	s_setprio 1
	v_mfma_f32_16x16x32_bf16 v[128:131], v[148:151], v[178:181], v[128:131]
	v_mfma_f32_16x16x32_bf16 v[124:127], v[170:173], v[178:181], v[124:127]
	v_mfma_f32_16x16x32_bf16 v[100:103], v[148:151], v[186:189], v[100:103]
	v_mfma_f32_16x16x32_bf16 v[96:99], v[170:173], v[186:189], v[96:99]
	v_mfma_f32_16x16x32_bf16 v[84:87], v[148:151], v[194:197], v[84:87]
	v_mfma_f32_16x16x32_bf16 v[80:83], v[170:173], v[194:197], v[80:83]
	v_mfma_f32_16x16x32_bf16 v[68:71], v[148:151], v[218:221], v[68:71]
	v_mfma_f32_16x16x32_bf16 v[64:67], v[170:173], v[218:221], v[64:67]
	v_mfma_f32_16x16x32_bf16 v[128:131], v[152:155], v[182:185], v[128:131]
	v_mfma_f32_16x16x32_bf16 v[124:127], v[174:177], v[182:185], v[124:127]
	v_mfma_f32_16x16x32_bf16 v[100:103], v[152:155], v[190:193], v[100:103]
	v_mfma_f32_16x16x32_bf16 v[96:99], v[174:177], v[190:193], v[96:99]
	s_barrier
; #define PG8_STAGE(bufoff, gbase, voff) do { _Pragma("unroll") for (int _i = 0; _i < 2; ++_i) \
;         __builtin_amdgcn_global_load_lds((const unsigned*)((const char*)(gbase) + (voff)[_i]), (PG8_LAS unsigned*)(lds + (bufoff) + ldsw + _i * 8192), 16, 0, 0); } while (0)
; #define PG8_LDA(dst, b, h) do { _Pragma("unroll") for (int m = 0; m < 4; ++m) _Pragma("unroll") for (int k = 0; k < 2; ++k) dst[m][k] = *(const PG8_LAS bf16x8*)(lds + PG8_SA(b, h) + aoff + m * 2048 + k * 1024); } while (0)
; #define PG8_MMA(ai, bj, At, Bt) do { __builtin_amdgcn_s_setprio(1); _Pragma("unroll") for (int m = 0; m < 4; ++m) _Pragma("unroll") for (int n = 0; n < 2; ++n) _Pragma("unroll") for (int k = 0; k < 2; ++k) \
;         acc[ai][bj][m][n] = __builtin_amdgcn_mfma_f32_16x16x32_bf16(Bt[n][k], At[m][k], acc[ai][bj][m][n], 0, 0, 0); __builtin_amdgcn_s_setprio(0); } while (0)
; #define PG8_WAIT_V(n) asm volatile("s_waitcnt vmcnt(" #n ")" ::: "memory")
; #define PG8_WAIT_L(n) asm volatile("s_waitcnt lgkmcnt(" #n ")" ::: "memory")
; #define PG8_BAR __builtin_amdgcn_s_barrier()
; #define PG8_SCHED __builtin_amdgcn_sched_barrier(0)
;     ...
;             PG8_LDA(At, 1, 1); PG8_STAGE(PG8_SB(1, 0), b3, voffB); PG8_STAGE(PG8_SB(1, 1), b3 + hstepB, voffB); PG8_STAGE(PG8_SA(1, 0), a3, voffA);
;             PG8_WAIT_V(8); PG8_WAIT_L(0); PG8_BAR; PG8_MMA(1, 0, At, B0); PG8_MMA(1, 1, At, B1); PG8_BAR; PG8_SCHED;
;         }
;         if (wr == 0) PG8_BAR;
;         if (!has_next && wmat && gtid * 128u < wbytes) asm volatile("global_load_dword %0, %1, off" : "+v"(warmm) : "v"(wmat + (size_t)gtid * 128u) : "memory");
;         if (!has_next && warm) warmv = *(const volatile unsigned*)(warm + ((size_t)(tid & 255) * wK + (size_t)(tid >> 8) * BK) * 2);
;         if (ui == 0) hook();
	v_mfma_f32_16x16x32_bf16 v[84:87], v[152:155], v[198:201], v[84:87]
	v_mfma_f32_16x16x32_bf16 v[80:83], v[174:177], v[198:201], v[80:83]
	v_mfma_f32_16x16x32_bf16 v[68:71], v[152:155], v[222:225], v[68:71]
	v_mfma_f32_16x16x32_bf16 v[64:67], v[174:177], v[222:225], v[64:67]
	s_setprio 0
	s_add_i32 s26, s68, s31
	v_lshl_add_u64 v[238:239], v[238:239], 0, s[72:73]
	s_mov_b32 m0, s26
	ds_read_b128 v[178:181], v211 offset:49152
	ds_read_b128 v[182:185], v211 offset:50176
	ds_read_b128 v[186:189], v211 offset:51200
	ds_read_b128 v[190:193], v211 offset:52224
	ds_read_b128 v[194:197], v211 offset:53248
	ds_read_b128 v[198:201], v211 offset:54272
	ds_read_b128 v[218:221], v211 offset:55296
	ds_read_b128 v[222:225], v211 offset:56320
	global_load_lds_dwordx4 v[238:239], off
	s_add_i32 m0, s26, 0x2000
	s_add_u32 s24, s24, 0x40080
	v_lshl_add_u64 v[238:239], v[240:241], 0, s[72:73]
	s_addc_u32 s25, s25, 0
	s_add_i32 s26, s69, s31
	global_load_lds_dwordx4 v[238:239], off
	v_lshl_add_u64 v[238:239], s[24:25], 0, v[208:209]
	s_mov_b32 m0, s26
	s_nop 0
	global_load_lds_dwordx4 v[238:239], off
	v_lshl_add_u64 v[238:239], s[24:25], 0, v[156:157]
	s_add_i32 m0, s26, 0x2000
	s_nop 0
	global_load_lds_dwordx4 v[238:239], off
	v_lshl_add_u64 v[238:239], s[20:21], 0, v[160:161]
	s_mov_b32 m0, s47
	s_nop 0
	global_load_lds_dwordx4 v[238:239], off
	v_lshl_add_u64 v[238:239], s[20:21], 0, v[158:159]
	s_mov_b32 m0, s48
	s_nop 0
	global_load_lds_dwordx4 v[238:239], off
	s_waitcnt vmcnt(8)
	s_waitcnt lgkmcnt(0)
	s_barrier
	s_setprio 1
	s_waitcnt lgkmcnt(0)
	v_mfma_f32_16x16x32_bf16 v[60:63], v[132:135], v[178:181], v[60:63]
	v_mfma_f32_16x16x32_bf16 v[56:59], v[140:143], v[178:181], v[56:59]
	v_mfma_f32_16x16x32_bf16 v[44:47], v[132:135], v[186:189], v[44:47]
	v_mfma_f32_16x16x32_bf16 v[40:43], v[140:143], v[186:189], v[40:43]
	v_mfma_f32_16x16x32_bf16 v[28:31], v[132:135], v[194:197], v[28:31]
	v_mfma_f32_16x16x32_bf16 v[24:27], v[140:143], v[194:197], v[24:27]
	v_mfma_f32_16x16x32_bf16 v[12:15], v[132:135], v[218:221], v[12:15]
	v_mfma_f32_16x16x32_bf16 v[8:11], v[140:143], v[218:221], v[8:11]
	v_mfma_f32_16x16x32_bf16 v[60:63], v[136:139], v[182:185], v[60:63]
	v_mfma_f32_16x16x32_bf16 v[56:59], v[144:147], v[182:185], v[56:59]
	v_mfma_f32_16x16x32_bf16 v[44:47], v[136:139], v[190:193], v[44:47]
	v_mfma_f32_16x16x32_bf16 v[40:43], v[144:147], v[190:193], v[40:43]
	v_mfma_f32_16x16x32_bf16 v[28:31], v[136:139], v[198:201], v[28:31]
	v_mfma_f32_16x16x32_bf16 v[24:27], v[144:147], v[198:201], v[24:27]
	v_mfma_f32_16x16x32_bf16 v[12:15], v[136:139], v[222:225], v[12:15]
	v_mfma_f32_16x16x32_bf16 v[8:11], v[144:147], v[222:225], v[8:11]
	s_setprio 0
	s_setprio 1
	v_mfma_f32_16x16x32_bf16 v[52:55], v[148:151], v[178:181], v[52:55]
	v_mfma_f32_16x16x32_bf16 v[48:51], v[170:173], v[178:181], v[48:51]
	v_mfma_f32_16x16x32_bf16 v[36:39], v[148:151], v[186:189], v[36:39]
	v_mfma_f32_16x16x32_bf16 v[32:35], v[170:173], v[186:189], v[32:35]
	v_mfma_f32_16x16x32_bf16 v[20:23], v[148:151], v[194:197], v[20:23]
	v_mfma_f32_16x16x32_bf16 v[16:19], v[170:173], v[194:197], v[16:19]
	v_mfma_f32_16x16x32_bf16 v[4:7], v[148:151], v[218:221], v[4:7]
	v_mfma_f32_16x16x32_bf16 v[0:3], v[170:173], v[218:221], v[0:3]
	v_mfma_f32_16x16x32_bf16 v[52:55], v[152:155], v[182:185], v[52:55]
	v_mfma_f32_16x16x32_bf16 v[48:51], v[174:177], v[182:185], v[48:51]
	v_mfma_f32_16x16x32_bf16 v[36:39], v[152:155], v[190:193], v[36:39]
	v_mfma_f32_16x16x32_bf16 v[32:35], v[174:177], v[190:193], v[32:35]
	s_barrier
	v_mfma_f32_16x16x32_bf16 v[20:23], v[152:155], v[198:201], v[20:23]
	v_mfma_f32_16x16x32_bf16 v[16:19], v[174:177], v[198:201], v[16:19]
	v_mfma_f32_16x16x32_bf16 v[4:7], v[152:155], v[222:225], v[4:7]
	v_mfma_f32_16x16x32_bf16 v[0:3], v[174:177], v[222:225], v[0:3]
	s_setprio 0
	s_add_i32 s67, s67, 2
	s_add_u32 s18, s18, 0x100
	s_addc_u32 s19, s19, 0
	s_cmp_gt_u32 s67, 13
	s_cbranch_scc0 .LBB0_451
	s_and_b64 vcc, exec, s[16:17]
	s_cbranch_vccz .LBB0_473
	s_barrier
	s_nor_b64 s[20:21], s[36:37], s[40:41]
	s_and_saveexec_b64 s[18:19], s[20:21]
	s_cbranch_execnz .LBB0_474

;     __device__ __forceinline__ const char* tile(const Unit& u, int t) const { return A + (size_t)u.pm * 2 * hstep() + (size_t)t * (BK * 2); }
;     __device__ __forceinline__ const char* tile(const Unit& u, int t) const { return U + (long)(t >> 2) * xoff + (size_t)u.pn * (1024 * 512) + (size_t)u.pm * 2 * hstep() + (size_t)(t & 3) * (BK * 2); }
; #define PG8_STAGE(bufoff, gbase, voff) do { _Pragma("unroll") for (int _i = 0; _i < 2; ++_i) \
;         __builtin_amdgcn_global_load_lds((const unsigned*)((const char*)(gbase) + (voff)[_i]), (PG8_LAS unsigned*)(lds + (bufoff) + ldsw + _i * 8192), 16, 0, 0); } while (0)
; #define PG8_LDA(dst, b, h) do { _Pragma("unroll") for (int m = 0; m < 4; ++m) _Pragma("unroll") for (int k = 0; k < 2; ++k) dst[m][k] = *(const PG8_LAS bf16x8*)(lds + PG8_SA(b, h) + aoff + m * 2048 + k * 1024); } while (0)
; #define PG8_LDB(dst, b, h) do { _Pragma("unroll") for (int n = 0; n < 2; ++n) _Pragma("unroll") for (int k = 0; k < 2; ++k) dst[n][k] = *(const PG8_LAS bf16x8*)(lds + PG8_SB(b, h) + boff + n * 2048 + k * 1024); } while (0)
; #define PG8_MMA(ai, bj, At, Bt) do { __builtin_amdgcn_s_setprio(1); _Pragma("unroll") for (int m = 0; m < 4; ++m) _Pragma("unroll") for (int n = 0; n < 2; ++n) _Pragma("unroll") for (int k = 0; k < 2; ++k) \
;         acc[ai][bj][m][n] = __builtin_amdgcn_mfma_f32_16x16x32_bf16(Bt[n][k], At[m][k], acc[ai][bj][m][n], 0, 0, 0); __builtin_amdgcn_s_setprio(0); } while (0)
; #define PG8_BAR __builtin_amdgcn_s_barrier()
;     ...
;         for (int t = 0; t < nt; t += 2) {
;             const bool last = (t == nt - 2);
;             const char* a1 = AS.tile(cur, t + 1);
;             const char* a2 = last ? AS.tile(nu, 0) : AS.tile(cur, t + 2); const char* b2 = last ? nB : cB + (size_t)(t + 2) * kstep;
;             const char* a3 = last ? AS.tile(nu, 1) : AS.tile(cur, t + 3); const char* b3 = b2 + kstep;
;             PG8_LDB(B0, 0, 0); PG8_LDB(B1, 0, 1); PG8_SCHED; PG8_LDA(At, 0, 0); PG8_STAGE(PG8_SA(1, 1), a1 + hstepA, voffA);
;             PG8_WAIT_V(8); PG8_WAIT_L(0); PG8_BAR; PG8_MMA(0, 0, At, B0); PG8_MMA(0, 1, At, B1); PG8_BAR; PG8_SCHED;
;             PG8_LDA(At, 0, 1); PG8_STAGE(PG8_SB(0, 0), b2, voffB); PG8_STAGE(PG8_SB(0, 1), b2 + hstepB, voffB); PG8_STAGE(PG8_SA(0, 0), a2, voffA);
;             PG8_WAIT_V(8); PG8_WAIT_L(0); PG8_BAR; PG8_MMA(1, 0, At, B0); PG8_MMA(1, 1, At, B1); PG8_BAR; PG8_SCHED;
.LBB0_504:
	s_add_u32 s14, s52, s12
	s_addc_u32 s15, s53, s13
	s_add_u32 s18, s14, 0x400100
	s_addc_u32 s19, s15, 0
	s_add_u32 s16, s54, s12
	s_addc_u32 s17, s55, s13
	s_add_u32 s14, s14, 0x400180
	s_addc_u32 s15, s15, 0
	s_add_i32 s57, 0, 0x10000
	s_add_i32 s60, 0, 0x14000
	v_add_u32_e32 v146, s57, v149
	ds_read_b128 v[156:159], v146
	ds_read_b128 v[160:163], v146 offset:1024
	ds_read_b128 v[164:167], v146 offset:2048
	ds_read_b128 v[168:171], v146 offset:3072
	v_add_u32_e32 v146, s60, v149
	ds_read_b128 v[172:175], v146
	ds_read_b128 v[176:179], v146 offset:1024
	ds_read_b128 v[180:183], v146 offset:2048
	ds_read_b128 v[184:187], v146 offset:3072
	s_cmpk_eq_i32 s12, 0x700
	s_cselect_b32 s15, s51, s15
	s_cselect_b32 s14, s50, s14
	s_cselect_b32 s17, s48, s17
	s_cselect_b32 s16, s47, s16
	s_cselect_b32 s19, s49, s19
	s_cselect_b32 s18, s11, s18
	v_lshl_add_u64 v[146:147], v[142:143], 0, s[12:13]
	s_add_i32 m0, s26, 0xc000
	ds_read_b128 v[188:191], v152
	ds_read_b128 v[192:195], v152 offset:1024
	ds_read_b128 v[196:199], v152 offset:2048
	ds_read_b128 v[200:203], v152 offset:3072
	ds_read_b128 v[204:207], v152 offset:4096
	ds_read_b128 v[218:221], v152 offset:5120
	ds_read_b128 v[222:225], v152 offset:6144
	ds_read_b128 v[238:241], v152 offset:7168
	global_load_lds_dwordx4 v[146:147], off
	v_lshl_add_u64 v[146:147], v[144:145], 0, s[12:13]
	s_add_i32 m0, s26, 0xe000
	s_nop 0
	global_load_lds_dwordx4 v[146:147], off
	s_waitcnt vmcnt(8)
	s_waitcnt lgkmcnt(0)
	s_barrier
	s_setprio 1
	s_waitcnt lgkmcnt(0)
	v_mfma_f32_16x16x32_bf16 v[124:127], v[156:159], v[188:191], v[124:127]
	v_mfma_f32_16x16x32_bf16 v[120:123], v[164:167], v[188:191], v[120:123]
	v_mfma_f32_16x16x32_bf16 v[108:111], v[156:159], v[196:199], v[108:111]
	v_mfma_f32_16x16x32_bf16 v[104:107], v[164:167], v[196:199], v[104:107]
	v_mfma_f32_16x16x32_bf16 v[92:95], v[156:159], v[204:207], v[92:95]
	v_mfma_f32_16x16x32_bf16 v[88:91], v[164:167], v[204:207], v[88:91]
	v_mfma_f32_16x16x32_bf16 v[76:79], v[156:159], v[222:225], v[76:79]
	v_mfma_f32_16x16x32_bf16 v[72:75], v[164:167], v[222:225], v[72:75]
	v_mfma_f32_16x16x32_bf16 v[124:127], v[160:163], v[192:195], v[124:127]
	v_mfma_f32_16x16x32_bf16 v[120:123], v[168:171], v[192:195], v[120:123]
	v_mfma_f32_16x16x32_bf16 v[108:111], v[160:163], v[200:203], v[108:111]
	v_mfma_f32_16x16x32_bf16 v[104:107], v[168:171], v[200:203], v[104:107]
	v_mfma_f32_16x16x32_bf16 v[92:95], v[160:163], v[218:221], v[92:95]
	v_mfma_f32_16x16x32_bf16 v[88:91], v[168:171], v[218:221], v[88:91]
	v_mfma_f32_16x16x32_bf16 v[76:79], v[160:163], v[238:241], v[76:79]
	v_mfma_f32_16x16x32_bf16 v[72:75], v[168:171], v[238:241], v[72:75]
	s_setprio 0
	s_setprio 1
	v_mfma_f32_16x16x32_bf16 v[116:119], v[172:175], v[188:191], v[116:119]
	v_mfma_f32_16x16x32_bf16 v[112:115], v[180:183], v[188:191], v[112:115]
	v_mfma_f32_16x16x32_bf16 v[100:103], v[172:175], v[196:199], v[100:103]
	v_mfma_f32_16x16x32_bf16 v[96:99], v[180:183], v[196:199], v[96:99]
	v_mfma_f32_16x16x32_bf16 v[84:87], v[172:175], v[204:207], v[84:87]
	v_mfma_f32_16x16x32_bf16 v[80:83], v[180:183], v[204:207], v[80:83]
	v_mfma_f32_16x16x32_bf16 v[68:71], v[172:175], v[222:225], v[68:71]
	v_mfma_f32_16x16x32_bf16 v[64:67], v[180:183], v[222:225], v[64:67]
	v_mfma_f32_16x16x32_bf16 v[116:119], v[176:179], v[192:195], v[116:119]
	v_mfma_f32_16x16x32_bf16 v[112:115], v[184:187], v[192:195], v[112:115]
	v_mfma_f32_16x16x32_bf16 v[100:103], v[176:179], v[200:203], v[100:103]
	v_mfma_f32_16x16x32_bf16 v[96:99], v[184:187], v[200:203], v[96:99]
	s_barrier
	v_mfma_f32_16x16x32_bf16 v[84:87], v[176:179], v[218:221], v[84:87]
	v_mfma_f32_16x16x32_bf16 v[80:83], v[184:187], v[218:221], v[80:83]
	v_mfma_f32_16x16x32_bf16 v[68:71], v[176:179], v[238:241], v[68:71]
	v_mfma_f32_16x16x32_bf16 v[64:67], v[184:187], v[238:241], v[64:67]
	s_setprio 0
	s_add_i32 s57, s57, s25
	v_lshl_add_u64 v[146:147], s[16:17], 0, v[208:209]
	s_mov_b32 m0, s57
	ds_read_b128 v[188:191], v152 offset:16384
	ds_read_b128 v[192:195], v152 offset:17408
	ds_read_b128 v[196:199], v152 offset:18432
	ds_read_b128 v[200:203], v152 offset:19456
	ds_read_b128 v[204:207], v152 offset:20480
	ds_read_b128 v[218:221], v152 offset:21504
	ds_read_b128 v[222:225], v152 offset:22528
	ds_read_b128 v[238:241], v152 offset:23552
	global_load_lds_dwordx4 v[146:147], off
	s_add_i32 m0, s57, 0x2000
	s_add_u32 s58, s16, 0x40000
	v_lshl_add_u64 v[242:243], s[16:17], 0, v[128:129]
	s_addc_u32 s59, s17, 0
	s_add_i32 s57, s60, s25
	global_load_lds_dwordx4 v[242:243], off
	v_lshl_add_u64 v[244:245], s[58:59], 0, v[208:209]
	s_mov_b32 m0, s57
	s_nop 0
	global_load_lds_dwordx4 v[244:245], off
	v_lshl_add_u64 v[244:245], s[58:59], 0, v[128:129]
	s_add_i32 m0, s57, 0x2000
	s_nop 0
	global_load_lds_dwordx4 v[244:245], off
	v_lshl_add_u64 v[244:245], s[18:19], 0, v[132:133]
	s_mov_b32 m0, s26
	s_nop 0
	global_load_lds_dwordx4 v[244:245], off
	v_lshl_add_u64 v[244:245], s[18:19], 0, v[130:131]
	s_mov_b32 m0, s27
	s_nop 0
	global_load_lds_dwordx4 v[244:245], off
	s_waitcnt vmcnt(8)
	s_waitcnt lgkmcnt(0)
	s_barrier
; #define PG8_STAGE(bufoff, gbase, voff) do { _Pragma("unroll") for (int _i = 0; _i < 2; ++_i) \
;         __builtin_amdgcn_global_load_lds((const unsigned*)((const char*)(gbase) + (voff)[_i]), (PG8_LAS unsigned*)(lds + (bufoff) + ldsw + _i * 8192), 16, 0, 0); } while (0)
; #define PG8_LDA(dst, b, h) do { _Pragma("unroll") for (int m = 0; m < 4; ++m) _Pragma("unroll") for (int k = 0; k < 2; ++k) dst[m][k] = *(const PG8_LAS bf16x8*)(lds + PG8_SA(b, h) + aoff + m * 2048 + k * 1024); } while (0)
; #define PG8_LDB(dst, b, h) do { _Pragma("unroll") for (int n = 0; n < 2; ++n) _Pragma("unroll") for (int k = 0; k < 2; ++k) dst[n][k] = *(const PG8_LAS bf16x8*)(lds + PG8_SB(b, h) + boff + n * 2048 + k * 1024); } while (0)
; #define PG8_MMA(ai, bj, At, Bt) do { __builtin_amdgcn_s_setprio(1); _Pragma("unroll") for (int m = 0; m < 4; ++m) _Pragma("unroll") for (int n = 0; n < 2; ++n) _Pragma("unroll") for (int k = 0; k < 2; ++k) \
;         acc[ai][bj][m][n] = __builtin_amdgcn_mfma_f32_16x16x32_bf16(Bt[n][k], At[m][k], acc[ai][bj][m][n], 0, 0, 0); __builtin_amdgcn_s_setprio(0); } while (0)
; #define PG8_WAIT_V(n) asm volatile("s_waitcnt vmcnt(" #n ")" ::: "memory")
; #define PG8_WAIT_L(n) asm volatile("s_waitcnt lgkmcnt(" #n ")" ::: "memory")
; #define PG8_BAR __builtin_amdgcn_s_barrier()
; #define PG8_SCHED __builtin_amdgcn_sched_barrier(0)
;     ...
;             PG8_WAIT_V(8); PG8_WAIT_L(0); PG8_BAR; PG8_MMA(1, 0, At, B0); PG8_MMA(1, 1, At, B1); PG8_BAR; PG8_SCHED;
;             PG8_LDB(B0, 1, 0); PG8_LDB(B1, 1, 1); PG8_SCHED; PG8_LDA(At, 1, 0); PG8_STAGE(PG8_SA(0, 1), a2 + hstepA, voffA);
;             PG8_WAIT_V(8); PG8_WAIT_L(0); PG8_BAR; PG8_MMA(0, 0, At, B0); PG8_MMA(0, 1, At, B1); PG8_BAR; PG8_SCHED;
	s_setprio 1
	s_waitcnt lgkmcnt(0)
	v_mfma_f32_16x16x32_bf16 v[60:63], v[156:159], v[188:191], v[60:63]
	v_mfma_f32_16x16x32_bf16 v[56:59], v[164:167], v[188:191], v[56:59]
	v_mfma_f32_16x16x32_bf16 v[44:47], v[156:159], v[196:199], v[44:47]
	v_mfma_f32_16x16x32_bf16 v[40:43], v[164:167], v[196:199], v[40:43]
	v_mfma_f32_16x16x32_bf16 v[28:31], v[156:159], v[204:207], v[28:31]
	v_mfma_f32_16x16x32_bf16 v[24:27], v[164:167], v[204:207], v[24:27]
	v_mfma_f32_16x16x32_bf16 v[12:15], v[156:159], v[222:225], v[12:15]
	v_mfma_f32_16x16x32_bf16 v[8:11], v[164:167], v[222:225], v[8:11]
	v_mfma_f32_16x16x32_bf16 v[60:63], v[160:163], v[192:195], v[60:63]
	v_mfma_f32_16x16x32_bf16 v[56:59], v[168:171], v[192:195], v[56:59]
	v_mfma_f32_16x16x32_bf16 v[44:47], v[160:163], v[200:203], v[44:47]
	v_mfma_f32_16x16x32_bf16 v[40:43], v[168:171], v[200:203], v[40:43]
	v_mfma_f32_16x16x32_bf16 v[28:31], v[160:163], v[218:221], v[28:31]
	v_mfma_f32_16x16x32_bf16 v[24:27], v[168:171], v[218:221], v[24:27]
	v_mfma_f32_16x16x32_bf16 v[12:15], v[160:163], v[238:241], v[12:15]
	v_mfma_f32_16x16x32_bf16 v[8:11], v[168:171], v[238:241], v[8:11]
	s_setprio 0
	s_setprio 1
	v_mfma_f32_16x16x32_bf16 v[52:55], v[172:175], v[188:191], v[52:55]
	v_mfma_f32_16x16x32_bf16 v[48:51], v[180:183], v[188:191], v[48:51]
	v_mfma_f32_16x16x32_bf16 v[36:39], v[172:175], v[196:199], v[36:39]
	v_mfma_f32_16x16x32_bf16 v[32:35], v[180:183], v[196:199], v[32:35]
	v_mfma_f32_16x16x32_bf16 v[20:23], v[172:175], v[204:207], v[20:23]
	v_mfma_f32_16x16x32_bf16 v[16:19], v[180:183], v[204:207], v[16:19]
	v_mfma_f32_16x16x32_bf16 v[4:7], v[172:175], v[222:225], v[4:7]
	v_mfma_f32_16x16x32_bf16 v[0:3], v[180:183], v[222:225], v[0:3]
	v_mfma_f32_16x16x32_bf16 v[52:55], v[176:179], v[192:195], v[52:55]
	v_mfma_f32_16x16x32_bf16 v[48:51], v[184:187], v[192:195], v[48:51]
	v_mfma_f32_16x16x32_bf16 v[36:39], v[176:179], v[200:203], v[36:39]
	v_mfma_f32_16x16x32_bf16 v[32:35], v[184:187], v[200:203], v[32:35]
	s_barrier
	v_mfma_f32_16x16x32_bf16 v[20:23], v[176:179], v[218:221], v[20:23]
	v_mfma_f32_16x16x32_bf16 v[16:19], v[184:187], v[218:221], v[16:19]
	v_mfma_f32_16x16x32_bf16 v[4:7], v[176:179], v[238:241], v[4:7]
	v_mfma_f32_16x16x32_bf16 v[0:3], v[184:187], v[238:241], v[0:3]
	s_setprio 0
	s_add_i32 s57, 0, 0x18000
	v_add_u32_e32 v155, s57, v149
	s_add_i32 s58, 0, 0x1c000
	ds_read_b128 v[156:159], v155
	ds_read_b128 v[160:163], v155 offset:1024
	ds_read_b128 v[164:167], v155 offset:2048
	ds_read_b128 v[168:171], v155 offset:3072
	v_add_u32_e32 v155, s58, v149
	ds_read_b128 v[172:175], v155
	ds_read_b128 v[176:179], v155 offset:1024
	ds_read_b128 v[180:183], v155 offset:2048
	ds_read_b128 v[184:187], v155 offset:3072
	s_add_u32 s18, s18, 0x40000
	s_addc_u32 s19, s19, 0
	s_mov_b32 m0, s28
	v_lshl_add_u64 v[244:245], s[18:19], 0, v[132:133]
	ds_read_b128 v[188:191], v152 offset:32768
	ds_read_b128 v[192:195], v152 offset:33792
	ds_read_b128 v[196:199], v152 offset:34816
	ds_read_b128 v[200:203], v152 offset:35840
	ds_read_b128 v[204:207], v152 offset:36864
	ds_read_b128 v[218:221], v152 offset:37888
	ds_read_b128 v[222:225], v152 offset:38912
	ds_read_b128 v[238:241], v152 offset:39936
	global_load_lds_dwordx4 v[244:245], off
	v_lshl_add_u64 v[244:245], s[18:19], 0, v[130:131]
	s_mov_b32 m0, s29
	s_nop 0
	global_load_lds_dwordx4 v[244:245], off
	s_waitcnt vmcnt(8)
	s_waitcnt lgkmcnt(0)
	s_barrier
	s_setprio 1
	s_waitcnt lgkmcnt(0)
	v_mfma_f32_16x16x32_bf16 v[124:127], v[156:159], v[188:191], v[124:127]
	v_mfma_f32_16x16x32_bf16 v[120:123], v[164:167], v[188:191], v[120:123]
	v_mfma_f32_16x16x32_bf16 v[108:111], v[156:159], v[196:199], v[108:111]
	v_mfma_f32_16x16x32_bf16 v[104:107], v[164:167], v[196:199], v[104:107]
	v_mfma_f32_16x16x32_bf16 v[92:95], v[156:159], v[204:207], v[92:95]
	v_mfma_f32_16x16x32_bf16 v[88:91], v[164:167], v[204:207], v[88:91]
	v_mfma_f32_16x16x32_bf16 v[76:79], v[156:159], v[222:225], v[76:79]
	v_mfma_f32_16x16x32_bf16 v[72:75], v[164:167], v[222:225], v[72:75]
	v_mfma_f32_16x16x32_bf16 v[124:127], v[160:163], v[192:195], v[124:127]
	v_mfma_f32_16x16x32_bf16 v[120:123], v[168:171], v[192:195], v[120:123]
	v_mfma_f32_16x16x32_bf16 v[108:111], v[160:163], v[200:203], v[108:111]
	v_mfma_f32_16x16x32_bf16 v[104:107], v[168:171], v[200:203], v[104:107]
	v_mfma_f32_16x16x32_bf16 v[92:95], v[160:163], v[218:221], v[92:95]
	v_mfma_f32_16x16x32_bf16 v[88:91], v[168:171], v[218:221], v[88:91]
	v_mfma_f32_16x16x32_bf16 v[76:79], v[160:163], v[238:241], v[76:79]
	v_mfma_f32_16x16x32_bf16 v[72:75], v[168:171], v[238:241], v[72:75]
	s_setprio 0
	s_setprio 1
	v_mfma_f32_16x16x32_bf16 v[116:119], v[172:175], v[188:191], v[116:119]
	v_mfma_f32_16x16x32_bf16 v[112:115], v[180:183], v[188:191], v[112:115]
	v_mfma_f32_16x16x32_bf16 v[100:103], v[172:175], v[196:199], v[100:103]
	v_mfma_f32_16x16x32_bf16 v[96:99], v[180:183], v[196:199], v[96:99]
	v_mfma_f32_16x16x32_bf16 v[84:87], v[172:175], v[204:207], v[84:87]
	v_mfma_f32_16x16x32_bf16 v[80:83], v[180:183], v[204:207], v[80:83]
	v_mfma_f32_16x16x32_bf16 v[68:71], v[172:175], v[222:225], v[68:71]
	v_mfma_f32_16x16x32_bf16 v[64:67], v[180:183], v[222:225], v[64:67]
	v_mfma_f32_16x16x32_bf16 v[116:119], v[176:179], v[192:195], v[116:119]
	v_mfma_f32_16x16x32_bf16 v[112:115], v[184:187], v[192:195], v[112:115]
	v_mfma_f32_16x16x32_bf16 v[100:103], v[176:179], v[200:203], v[100:103]
	v_mfma_f32_16x16x32_bf16 v[96:99], v[184:187], v[200:203], v[96:99]
	s_barrier
; #define PG8_STAGE(bufoff, gbase, voff) do { _Pragma("unroll") for (int _i = 0; _i < 2; ++_i) \
;         __builtin_amdgcn_global_load_lds((const unsigned*)((const char*)(gbase) + (voff)[_i]), (PG8_LAS unsigned*)(lds + (bufoff) + ldsw + _i * 8192), 16, 0, 0); } while (0)
; #define PG8_LDA(dst, b, h) do { _Pragma("unroll") for (int m = 0; m < 4; ++m) _Pragma("unroll") for (int k = 0; k < 2; ++k) dst[m][k] = *(const PG8_LAS bf16x8*)(lds + PG8_SA(b, h) + aoff + m * 2048 + k * 1024); } while (0)
; #define PG8_MMA(ai, bj, At, Bt) do { __builtin_amdgcn_s_setprio(1); _Pragma("unroll") for (int m = 0; m < 4; ++m) _Pragma("unroll") for (int n = 0; n < 2; ++n) _Pragma("unroll") for (int k = 0; k < 2; ++k) \
;         acc[ai][bj][m][n] = __builtin_amdgcn_mfma_f32_16x16x32_bf16(Bt[n][k], At[m][k], acc[ai][bj][m][n], 0, 0, 0); __builtin_amdgcn_s_setprio(0); } while (0)
; #define PG8_WAIT_V(n) asm volatile("s_waitcnt vmcnt(" #n ")" ::: "memory")
; #define PG8_WAIT_L(n) asm volatile("s_waitcnt lgkmcnt(" #n ")" ::: "memory")
; #define PG8_BAR __builtin_amdgcn_s_barrier()
; #define PG8_SCHED __builtin_amdgcn_sched_barrier(0)
;     ...
;             PG8_LDA(At, 1, 1); PG8_STAGE(PG8_SB(1, 0), b3, voffB); PG8_STAGE(PG8_SB(1, 1), b3 + hstepB, voffB); PG8_STAGE(PG8_SA(1, 0), a3, voffA);
;             PG8_WAIT_V(8); PG8_WAIT_L(0); PG8_BAR; PG8_MMA(1, 0, At, B0); PG8_MMA(1, 1, At, B1); PG8_BAR; PG8_SCHED;
;         }
;         if (wr == 0) PG8_BAR;
;         if (!has_next && wmat && gtid * 128u < wbytes) asm volatile("global_load_dword %0, %1, off" : "+v"(warmm) : "v"(wmat + (size_t)gtid * 128u) : "memory");
;         if (!has_next && warm) warmv = *(const volatile unsigned*)(warm + ((size_t)(tid & 255) * wK + (size_t)(tid >> 8) * BK) * 2);
;         if (ui == 0) hook();
	v_mfma_f32_16x16x32_bf16 v[84:87], v[176:179], v[218:221], v[84:87]
	v_mfma_f32_16x16x32_bf16 v[80:83], v[184:187], v[218:221], v[80:83]
	v_mfma_f32_16x16x32_bf16 v[68:71], v[176:179], v[238:241], v[68:71]
	v_mfma_f32_16x16x32_bf16 v[64:67], v[184:187], v[238:241], v[64:67]
	s_setprio 0
	s_add_i32 s18, s57, s25
	v_lshl_add_u64 v[146:147], v[146:147], 0, s[64:65]
	s_mov_b32 m0, s18
	ds_read_b128 v[188:191], v152 offset:49152
	ds_read_b128 v[192:195], v152 offset:50176
	ds_read_b128 v[196:199], v152 offset:51200
	ds_read_b128 v[200:203], v152 offset:52224
	ds_read_b128 v[204:207], v152 offset:53248
	ds_read_b128 v[218:221], v152 offset:54272
	ds_read_b128 v[222:225], v152 offset:55296
	ds_read_b128 v[238:241], v152 offset:56320
	global_load_lds_dwordx4 v[146:147], off
	s_add_i32 m0, s18, 0x2000
	s_add_u32 s16, s16, 0x40080
	v_lshl_add_u64 v[146:147], v[242:243], 0, s[64:65]
	s_addc_u32 s17, s17, 0
	s_add_i32 s18, s58, s25
	global_load_lds_dwordx4 v[146:147], off
	v_lshl_add_u64 v[146:147], s[16:17], 0, v[208:209]
	s_mov_b32 m0, s18
	s_nop 0
	global_load_lds_dwordx4 v[146:147], off
	v_lshl_add_u64 v[146:147], s[16:17], 0, v[128:129]
	s_add_i32 m0, s18, 0x2000
	s_nop 0
	global_load_lds_dwordx4 v[146:147], off
	v_lshl_add_u64 v[146:147], s[14:15], 0, v[132:133]
	s_mov_b32 m0, s30
	s_nop 0
	global_load_lds_dwordx4 v[146:147], off
	v_lshl_add_u64 v[146:147], s[14:15], 0, v[130:131]
	s_mov_b32 m0, s31
	s_nop 0
	global_load_lds_dwordx4 v[146:147], off
	s_waitcnt vmcnt(8)
	s_waitcnt lgkmcnt(0)
	s_barrier
	s_setprio 1
	s_waitcnt lgkmcnt(0)
	v_mfma_f32_16x16x32_bf16 v[60:63], v[156:159], v[188:191], v[60:63]
	v_mfma_f32_16x16x32_bf16 v[56:59], v[164:167], v[188:191], v[56:59]
	v_mfma_f32_16x16x32_bf16 v[44:47], v[156:159], v[196:199], v[44:47]
	v_mfma_f32_16x16x32_bf16 v[40:43], v[164:167], v[196:199], v[40:43]
	v_mfma_f32_16x16x32_bf16 v[28:31], v[156:159], v[204:207], v[28:31]
	v_mfma_f32_16x16x32_bf16 v[24:27], v[164:167], v[204:207], v[24:27]
	v_mfma_f32_16x16x32_bf16 v[12:15], v[156:159], v[222:225], v[12:15]
	v_mfma_f32_16x16x32_bf16 v[8:11], v[164:167], v[222:225], v[8:11]
	v_mfma_f32_16x16x32_bf16 v[60:63], v[160:163], v[192:195], v[60:63]
	v_mfma_f32_16x16x32_bf16 v[56:59], v[168:171], v[192:195], v[56:59]
	v_mfma_f32_16x16x32_bf16 v[44:47], v[160:163], v[200:203], v[44:47]
	v_mfma_f32_16x16x32_bf16 v[40:43], v[168:171], v[200:203], v[40:43]
	v_mfma_f32_16x16x32_bf16 v[28:31], v[160:163], v[218:221], v[28:31]
	v_mfma_f32_16x16x32_bf16 v[24:27], v[168:171], v[218:221], v[24:27]
	v_mfma_f32_16x16x32_bf16 v[12:15], v[160:163], v[238:241], v[12:15]
	v_mfma_f32_16x16x32_bf16 v[8:11], v[168:171], v[238:241], v[8:11]
	s_setprio 0
	s_setprio 1
	v_mfma_f32_16x16x32_bf16 v[52:55], v[172:175], v[188:191], v[52:55]
	v_mfma_f32_16x16x32_bf16 v[48:51], v[180:183], v[188:191], v[48:51]
	v_mfma_f32_16x16x32_bf16 v[36:39], v[172:175], v[196:199], v[36:39]
	v_mfma_f32_16x16x32_bf16 v[32:35], v[180:183], v[196:199], v[32:35]
	v_mfma_f32_16x16x32_bf16 v[20:23], v[172:175], v[204:207], v[20:23]
	v_mfma_f32_16x16x32_bf16 v[16:19], v[180:183], v[204:207], v[16:19]
	v_mfma_f32_16x16x32_bf16 v[4:7], v[172:175], v[222:225], v[4:7]
	v_mfma_f32_16x16x32_bf16 v[0:3], v[180:183], v[222:225], v[0:3]
	v_mfma_f32_16x16x32_bf16 v[52:55], v[176:179], v[192:195], v[52:55]
	v_mfma_f32_16x16x32_bf16 v[48:51], v[184:187], v[192:195], v[48:51]
	v_mfma_f32_16x16x32_bf16 v[36:39], v[176:179], v[200:203], v[36:39]
	v_mfma_f32_16x16x32_bf16 v[32:35], v[184:187], v[200:203], v[32:35]
	s_barrier
	v_mfma_f32_16x16x32_bf16 v[20:23], v[176:179], v[218:221], v[20:23]
	v_mfma_f32_16x16x32_bf16 v[16:19], v[184:187], v[218:221], v[16:19]
	v_mfma_f32_16x16x32_bf16 v[4:7], v[176:179], v[238:241], v[4:7]
	v_mfma_f32_16x16x32_bf16 v[0:3], v[184:187], v[238:241], v[0:3]
	s_setprio 0
	s_add_i32 s56, s56, 2
	s_add_u32 s12, s12, 0x100
	s_addc_u32 s13, s13, 0
	s_cmp_gt_u32 s56, 13
	s_cbranch_scc0 .LBB0_504
	s_and_b64 vcc, exec, s[6:7]
	s_cbranch_vccz .LBB0_515
	s_barrier
	s_nor_b64 s[14:15], s[36:37], s[38:39]
	s_and_saveexec_b64 s[12:13], s[14:15]
	s_cbranch_execnz .LBB0_516

;     __device__ __forceinline__ const char* tile(const Unit& u, int t) const { return A + (size_t)u.pm * 2 * hstep() + (size_t)t * (BK * 2); }
;     __device__ __forceinline__ const char* tile(const Unit& u, int t) const { return U + (long)(t >> 2) * xoff + (size_t)u.pn * (1024 * 512) + (size_t)u.pm * 2 * hstep() + (size_t)(t & 3) * (BK * 2); }
; #define PG8_STAGE(bufoff, gbase, voff) do { _Pragma("unroll") for (int _i = 0; _i < 2; ++_i) \
;         __builtin_amdgcn_global_load_lds((const unsigned*)((const char*)(gbase) + (voff)[_i]), (PG8_LAS unsigned*)(lds + (bufoff) + ldsw + _i * 8192), 16, 0, 0); } while (0)
; #define PG8_LDA(dst, b, h) do { _Pragma("unroll") for (int m = 0; m < 4; ++m) _Pragma("unroll") for (int k = 0; k < 2; ++k) dst[m][k] = *(const PG8_LAS bf16x8*)(lds + PG8_SA(b, h) + aoff + m * 2048 + k * 1024); } while (0)
; #define PG8_LDB(dst, b, h) do { _Pragma("unroll") for (int n = 0; n < 2; ++n) _Pragma("unroll") for (int k = 0; k < 2; ++k) dst[n][k] = *(const PG8_LAS bf16x8*)(lds + PG8_SB(b, h) + boff + n * 2048 + k * 1024); } while (0)
; #define PG8_MMA(ai, bj, At, Bt) do { __builtin_amdgcn_s_setprio(1); _Pragma("unroll") for (int m = 0; m < 4; ++m) _Pragma("unroll") for (int n = 0; n < 2; ++n) _Pragma("unroll") for (int k = 0; k < 2; ++k) \
;         acc[ai][bj][m][n] = __builtin_amdgcn_mfma_f32_16x16x32_bf16(Bt[n][k], At[m][k], acc[ai][bj][m][n], 0, 0, 0); __builtin_amdgcn_s_setprio(0); } while (0)
; #define PG8_BAR __builtin_amdgcn_s_barrier()
;     ...
;         for (int t = 0; t < nt; t += 2) {
;             const bool last = (t == nt - 2);
;             const char* a1 = AS.tile(cur, t + 1);
;             const char* a2 = last ? AS.tile(nu, 0) : AS.tile(cur, t + 2); const char* b2 = last ? nB : cB + (size_t)(t + 2) * kstep;
;             const char* a3 = last ? AS.tile(nu, 1) : AS.tile(cur, t + 3); const char* b3 = b2 + kstep;
;             PG8_LDB(B0, 0, 0); PG8_LDB(B1, 0, 1); PG8_SCHED; PG8_LDA(At, 0, 0); PG8_STAGE(PG8_SA(1, 1), a1 + hstepA, voffA);
;             PG8_WAIT_V(8); PG8_WAIT_L(0); PG8_BAR; PG8_MMA(0, 0, At, B0); PG8_MMA(0, 1, At, B1); PG8_BAR; PG8_SCHED;
;             PG8_LDA(At, 0, 1); PG8_STAGE(PG8_SB(0, 0), b2, voffB); PG8_STAGE(PG8_SB(0, 1), b2 + hstepB, voffB); PG8_STAGE(PG8_SA(0, 0), a2, voffA);
;             PG8_WAIT_V(8); PG8_WAIT_L(0); PG8_BAR; PG8_MMA(1, 0, At, B0); PG8_MMA(1, 1, At, B1); PG8_BAR; PG8_SCHED;
.LBB0_534:
	s_add_i32 s68, s2, 2
	s_add_u32 s3, s82, s64
	s_addc_u32 s20, s83, s65
	s_add_u32 s69, s3, 0x100
	s_addc_u32 s21, s20, 0
	s_add_u32 s70, s82, s66
	s_addc_u32 s71, s83, s67
	s_add_u32 s72, s3, 0x180
	s_addc_u32 s3, s20, 0
	s_add_i32 s73, 0, 0x10000
	s_add_i32 s74, 0, 0x14000
	v_add_u32_e32 v108, s73, v212
	v_add_u32_e32 v152, s74, v212
	ds_read_b128 v[76:79], v108
	ds_read_b128 v[88:91], v108 offset:1024
	ds_read_b128 v[100:103], v108 offset:2048
	ds_read_b128 v[108:111], v108 offset:3072
	ds_read_b128 v[124:127], v152
	ds_read_b128 v[128:131], v152 offset:1024
	ds_read_b128 v[144:147], v152 offset:2048
	ds_read_b128 v[152:155], v152 offset:3072
	s_cmp_eq_u32 s51, s2
	s_cselect_b32 s2, s60, s72
	s_cselect_b32 s3, s61, s3
	s_cselect_b32 s71, s41, s71
	s_cselect_b32 s70, s40, s70
	s_cselect_b32 s21, s59, s21
	s_cselect_b32 s20, s1, s69
	v_lshl_add_u64 v[222:223], s[82:83], 0, v[64:65]
	s_add_i32 m0, s35, 0xc000
	ds_read_b128 v[156:159], v241
	ds_read_b128 v[168:171], v241 offset:1024
	ds_read_b128 v[172:175], v241 offset:2048
	ds_read_b128 v[176:179], v241 offset:3072
	ds_read_b128 v[180:183], v241 offset:4096
	ds_read_b128 v[184:187], v241 offset:5120
	ds_read_b128 v[188:191], v241 offset:6144
	ds_read_b128 v[218:221], v241 offset:7168
	global_load_lds_dwordx4 v[222:223], off
	v_lshl_add_u64 v[222:223], s[82:83], 0, v[66:67]
	s_add_i32 m0, s35, 0xe000
	s_nop 0
	global_load_lds_dwordx4 v[222:223], off
	s_waitcnt vmcnt(8)
	s_waitcnt lgkmcnt(0)
	s_barrier
	s_setprio 1
	s_waitcnt lgkmcnt(0)
	v_mfma_f32_16x16x32_bf16 v[164:167], v[76:79], v[156:159], v[164:167]
	v_mfma_f32_16x16x32_bf16 v[160:163], v[100:103], v[156:159], v[160:163]
	v_mfma_f32_16x16x32_bf16 v[136:139], v[76:79], v[172:175], v[136:139]
	v_mfma_f32_16x16x32_bf16 v[132:135], v[100:103], v[172:175], v[132:135]
	v_mfma_f32_16x16x32_bf16 v[112:115], v[76:79], v[180:183], v[112:115]
	v_mfma_f32_16x16x32_bf16 v[104:107], v[100:103], v[180:183], v[104:107]
	v_mfma_f32_16x16x32_bf16 v[84:87], v[76:79], v[188:191], v[84:87]
	v_mfma_f32_16x16x32_bf16 v[80:83], v[100:103], v[188:191], v[80:83]
	v_mfma_f32_16x16x32_bf16 v[164:167], v[88:91], v[168:171], v[164:167]
	v_mfma_f32_16x16x32_bf16 v[160:163], v[108:111], v[168:171], v[160:163]
	v_mfma_f32_16x16x32_bf16 v[136:139], v[88:91], v[176:179], v[136:139]
	v_mfma_f32_16x16x32_bf16 v[132:135], v[108:111], v[176:179], v[132:135]
	v_mfma_f32_16x16x32_bf16 v[112:115], v[88:91], v[184:187], v[112:115]
	v_mfma_f32_16x16x32_bf16 v[104:107], v[108:111], v[184:187], v[104:107]
	v_mfma_f32_16x16x32_bf16 v[84:87], v[88:91], v[218:221], v[84:87]
	v_mfma_f32_16x16x32_bf16 v[80:83], v[108:111], v[218:221], v[80:83]
	s_setprio 0
	s_setprio 1
	v_mfma_f32_16x16x32_bf16 v[148:151], v[124:127], v[156:159], v[148:151]
	v_mfma_f32_16x16x32_bf16 v[140:143], v[144:147], v[156:159], v[140:143]
	v_mfma_f32_16x16x32_bf16 v[120:123], v[124:127], v[172:175], v[120:123]
	v_mfma_f32_16x16x32_bf16 v[116:119], v[144:147], v[172:175], v[116:119]
	v_mfma_f32_16x16x32_bf16 v[96:99], v[124:127], v[180:183], v[96:99]
	v_mfma_f32_16x16x32_bf16 v[92:95], v[144:147], v[180:183], v[92:95]
	v_mfma_f32_16x16x32_bf16 v[72:75], v[124:127], v[188:191], v[72:75]
	v_mfma_f32_16x16x32_bf16 v[68:71], v[144:147], v[188:191], v[68:71]
	v_mfma_f32_16x16x32_bf16 v[148:151], v[128:131], v[168:171], v[148:151]
	v_mfma_f32_16x16x32_bf16 v[140:143], v[152:155], v[168:171], v[140:143]
	v_mfma_f32_16x16x32_bf16 v[120:123], v[128:131], v[176:179], v[120:123]
	v_mfma_f32_16x16x32_bf16 v[116:119], v[152:155], v[176:179], v[116:119]
	s_barrier
	v_mfma_f32_16x16x32_bf16 v[96:99], v[128:131], v[184:187], v[96:99]
	v_mfma_f32_16x16x32_bf16 v[92:95], v[152:155], v[184:187], v[92:95]
	v_mfma_f32_16x16x32_bf16 v[72:75], v[128:131], v[218:221], v[72:75]
	v_mfma_f32_16x16x32_bf16 v[68:71], v[152:155], v[218:221], v[68:71]
	s_setprio 0
	s_add_i32 s69, s73, s25
	v_lshl_add_u64 v[222:223], s[70:71], 0, v[196:197]
	s_mov_b32 m0, s69
	ds_read_b128 v[156:159], v241 offset:16384
	ds_read_b128 v[168:171], v241 offset:17408
	ds_read_b128 v[172:175], v241 offset:18432
	ds_read_b128 v[176:179], v241 offset:19456
	ds_read_b128 v[180:183], v241 offset:20480
	ds_read_b128 v[184:187], v241 offset:21504
	ds_read_b128 v[188:191], v241 offset:22528
	ds_read_b128 v[218:221], v241 offset:23552
	global_load_lds_dwordx4 v[222:223], off
	s_add_i32 m0, s69, 0x2000
	v_lshl_add_u64 v[224:225], s[70:71], 0, v[192:193]
	s_add_u32 s70, s70, s24
	s_addc_u32 s71, s71, 0
	s_add_i32 s69, s74, s25
	global_load_lds_dwordx4 v[224:225], off
	v_lshl_add_u64 v[244:245], s[70:71], 0, v[196:197]
	s_mov_b32 m0, s69
	v_lshl_add_u64 v[246:247], s[70:71], 0, v[192:193]
	global_load_lds_dwordx4 v[244:245], off
	s_add_i32 m0, s69, 0x2000
	v_lshl_add_u64 v[248:249], s[20:21], 0, v[198:199]
	global_load_lds_dwordx4 v[246:247], off
	s_mov_b32 m0, s35
	s_nop 0
	global_load_lds_dwordx4 v[248:249], off
	v_lshl_add_u64 v[248:249], s[20:21], 0, v[194:195]
	s_mov_b32 m0, s44
	s_nop 0
	global_load_lds_dwordx4 v[248:249], off
	s_waitcnt vmcnt(8)
	s_waitcnt lgkmcnt(0)
	s_barrier
; #define PG8_STAGE(bufoff, gbase, voff) do { _Pragma("unroll") for (int _i = 0; _i < 2; ++_i) \
;         __builtin_amdgcn_global_load_lds((const unsigned*)((const char*)(gbase) + (voff)[_i]), (PG8_LAS unsigned*)(lds + (bufoff) + ldsw + _i * 8192), 16, 0, 0); } while (0)
; #define PG8_LDA(dst, b, h) do { _Pragma("unroll") for (int m = 0; m < 4; ++m) _Pragma("unroll") for (int k = 0; k < 2; ++k) dst[m][k] = *(const PG8_LAS bf16x8*)(lds + PG8_SA(b, h) + aoff + m * 2048 + k * 1024); } while (0)
; #define PG8_LDB(dst, b, h) do { _Pragma("unroll") for (int n = 0; n < 2; ++n) _Pragma("unroll") for (int k = 0; k < 2; ++k) dst[n][k] = *(const PG8_LAS bf16x8*)(lds + PG8_SB(b, h) + boff + n * 2048 + k * 1024); } while (0)
; #define PG8_MMA(ai, bj, At, Bt) do { __builtin_amdgcn_s_setprio(1); _Pragma("unroll") for (int m = 0; m < 4; ++m) _Pragma("unroll") for (int n = 0; n < 2; ++n) _Pragma("unroll") for (int k = 0; k < 2; ++k) \
;         acc[ai][bj][m][n] = __builtin_amdgcn_mfma_f32_16x16x32_bf16(Bt[n][k], At[m][k], acc[ai][bj][m][n], 0, 0, 0); __builtin_amdgcn_s_setprio(0); } while (0)
; #define PG8_WAIT_V(n) asm volatile("s_waitcnt vmcnt(" #n ")" ::: "memory")
; #define PG8_WAIT_L(n) asm volatile("s_waitcnt lgkmcnt(" #n ")" ::: "memory")
; #define PG8_BAR __builtin_amdgcn_s_barrier()
; #define PG8_SCHED __builtin_amdgcn_sched_barrier(0)
;     ...
;             PG8_WAIT_V(8); PG8_WAIT_L(0); PG8_BAR; PG8_MMA(1, 0, At, B0); PG8_MMA(1, 1, At, B1); PG8_BAR; PG8_SCHED;
;             PG8_LDB(B0, 1, 0); PG8_LDB(B1, 1, 1); PG8_SCHED; PG8_LDA(At, 1, 0); PG8_STAGE(PG8_SA(0, 1), a2 + hstepA, voffA);
;             PG8_WAIT_V(8); PG8_WAIT_L(0); PG8_BAR; PG8_MMA(0, 0, At, B0); PG8_MMA(0, 1, At, B1); PG8_BAR; PG8_SCHED;
	s_setprio 1
	s_waitcnt lgkmcnt(0)
	v_mfma_f32_16x16x32_bf16 v[60:63], v[76:79], v[156:159], v[60:63]
	v_mfma_f32_16x16x32_bf16 v[56:59], v[100:103], v[156:159], v[56:59]
	v_mfma_f32_16x16x32_bf16 v[44:47], v[76:79], v[172:175], v[44:47]
	v_mfma_f32_16x16x32_bf16 v[40:43], v[100:103], v[172:175], v[40:43]
	v_mfma_f32_16x16x32_bf16 v[28:31], v[76:79], v[180:183], v[28:31]
	v_mfma_f32_16x16x32_bf16 v[24:27], v[100:103], v[180:183], v[24:27]
	v_mfma_f32_16x16x32_bf16 v[12:15], v[76:79], v[188:191], v[12:15]
	v_mfma_f32_16x16x32_bf16 v[8:11], v[100:103], v[188:191], v[8:11]
	v_mfma_f32_16x16x32_bf16 v[60:63], v[88:91], v[168:171], v[60:63]
	v_mfma_f32_16x16x32_bf16 v[56:59], v[108:111], v[168:171], v[56:59]
	v_mfma_f32_16x16x32_bf16 v[44:47], v[88:91], v[176:179], v[44:47]
	v_mfma_f32_16x16x32_bf16 v[40:43], v[108:111], v[176:179], v[40:43]
	v_mfma_f32_16x16x32_bf16 v[28:31], v[88:91], v[184:187], v[28:31]
	v_mfma_f32_16x16x32_bf16 v[24:27], v[108:111], v[184:187], v[24:27]
	v_mfma_f32_16x16x32_bf16 v[12:15], v[88:91], v[218:221], v[12:15]
	v_mfma_f32_16x16x32_bf16 v[8:11], v[108:111], v[218:221], v[8:11]
	s_setprio 0
	s_setprio 1
	v_mfma_f32_16x16x32_bf16 v[52:55], v[124:127], v[156:159], v[52:55]
	v_mfma_f32_16x16x32_bf16 v[48:51], v[144:147], v[156:159], v[48:51]
	v_mfma_f32_16x16x32_bf16 v[36:39], v[124:127], v[172:175], v[36:39]
	v_mfma_f32_16x16x32_bf16 v[32:35], v[144:147], v[172:175], v[32:35]
	v_mfma_f32_16x16x32_bf16 v[20:23], v[124:127], v[180:183], v[20:23]
	v_mfma_f32_16x16x32_bf16 v[16:19], v[144:147], v[180:183], v[16:19]
	v_mfma_f32_16x16x32_bf16 v[4:7], v[124:127], v[188:191], v[4:7]
	v_mfma_f32_16x16x32_bf16 v[0:3], v[144:147], v[188:191], v[0:3]
	v_mfma_f32_16x16x32_bf16 v[52:55], v[128:131], v[168:171], v[52:55]
	v_mfma_f32_16x16x32_bf16 v[48:51], v[152:155], v[168:171], v[48:51]
	v_mfma_f32_16x16x32_bf16 v[36:39], v[128:131], v[176:179], v[36:39]
	v_mfma_f32_16x16x32_bf16 v[32:35], v[152:155], v[176:179], v[32:35]
	s_barrier
	v_mfma_f32_16x16x32_bf16 v[20:23], v[128:131], v[184:187], v[20:23]
	v_mfma_f32_16x16x32_bf16 v[16:19], v[152:155], v[184:187], v[16:19]
	v_mfma_f32_16x16x32_bf16 v[4:7], v[128:131], v[218:221], v[4:7]
	v_mfma_f32_16x16x32_bf16 v[0:3], v[152:155], v[218:221], v[0:3]
	s_setprio 0
	s_add_i32 s69, 0, 0x18000
	s_add_i32 s70, 0, 0x1c000
	v_add_u32_e32 v108, s69, v212
	v_add_u32_e32 v152, s70, v212
	ds_read_b128 v[76:79], v108
	ds_read_b128 v[88:91], v108 offset:1024
	ds_read_b128 v[100:103], v108 offset:2048
	ds_read_b128 v[108:111], v108 offset:3072
	ds_read_b128 v[124:127], v152
	ds_read_b128 v[128:131], v152 offset:1024
	ds_read_b128 v[144:147], v152 offset:2048
	ds_read_b128 v[152:155], v152 offset:3072
	s_add_u32 s20, s20, s24
	s_addc_u32 s21, s21, 0
	s_mov_b32 m0, s45
	v_lshl_add_u64 v[248:249], s[20:21], 0, v[198:199]
	ds_read_b128 v[156:159], v241 offset:32768
	ds_read_b128 v[168:171], v241 offset:33792
	ds_read_b128 v[172:175], v241 offset:34816
	ds_read_b128 v[176:179], v241 offset:35840
	ds_read_b128 v[180:183], v241 offset:36864
	ds_read_b128 v[184:187], v241 offset:37888
	ds_read_b128 v[188:191], v241 offset:38912
	ds_read_b128 v[218:221], v241 offset:39936
	global_load_lds_dwordx4 v[248:249], off
	v_lshl_add_u64 v[248:249], s[20:21], 0, v[194:195]
	s_mov_b32 m0, s46
	s_nop 0
	global_load_lds_dwordx4 v[248:249], off
	s_waitcnt vmcnt(8)
	s_waitcnt lgkmcnt(0)
	s_barrier
	s_setprio 1
	s_waitcnt lgkmcnt(0)
	v_mfma_f32_16x16x32_bf16 v[164:167], v[76:79], v[156:159], v[164:167]
	v_mfma_f32_16x16x32_bf16 v[160:163], v[100:103], v[156:159], v[160:163]
	v_mfma_f32_16x16x32_bf16 v[136:139], v[76:79], v[172:175], v[136:139]
	v_mfma_f32_16x16x32_bf16 v[132:135], v[100:103], v[172:175], v[132:135]
	v_mfma_f32_16x16x32_bf16 v[112:115], v[76:79], v[180:183], v[112:115]
	v_mfma_f32_16x16x32_bf16 v[104:107], v[100:103], v[180:183], v[104:107]
	v_mfma_f32_16x16x32_bf16 v[84:87], v[76:79], v[188:191], v[84:87]
	v_mfma_f32_16x16x32_bf16 v[80:83], v[100:103], v[188:191], v[80:83]
	v_mfma_f32_16x16x32_bf16 v[164:167], v[88:91], v[168:171], v[164:167]
	v_mfma_f32_16x16x32_bf16 v[160:163], v[108:111], v[168:171], v[160:163]
	v_mfma_f32_16x16x32_bf16 v[136:139], v[88:91], v[176:179], v[136:139]
	v_mfma_f32_16x16x32_bf16 v[132:135], v[108:111], v[176:179], v[132:135]
	v_mfma_f32_16x16x32_bf16 v[112:115], v[88:91], v[184:187], v[112:115]
	v_mfma_f32_16x16x32_bf16 v[104:107], v[108:111], v[184:187], v[104:107]
	v_mfma_f32_16x16x32_bf16 v[84:87], v[88:91], v[218:221], v[84:87]
	v_mfma_f32_16x16x32_bf16 v[80:83], v[108:111], v[218:221], v[80:83]
	s_setprio 0
	s_setprio 1
	v_mfma_f32_16x16x32_bf16 v[148:151], v[124:127], v[156:159], v[148:151]
	v_mfma_f32_16x16x32_bf16 v[140:143], v[144:147], v[156:159], v[140:143]
	v_mfma_f32_16x16x32_bf16 v[120:123], v[124:127], v[172:175], v[120:123]
	v_mfma_f32_16x16x32_bf16 v[116:119], v[144:147], v[172:175], v[116:119]
	v_mfma_f32_16x16x32_bf16 v[96:99], v[124:127], v[180:183], v[96:99]
	v_mfma_f32_16x16x32_bf16 v[92:95], v[144:147], v[180:183], v[92:95]
	v_mfma_f32_16x16x32_bf16 v[72:75], v[124:127], v[188:191], v[72:75]
	v_mfma_f32_16x16x32_bf16 v[68:71], v[144:147], v[188:191], v[68:71]
	v_mfma_f32_16x16x32_bf16 v[148:151], v[128:131], v[168:171], v[148:151]
	v_mfma_f32_16x16x32_bf16 v[140:143], v[152:155], v[168:171], v[140:143]
	v_mfma_f32_16x16x32_bf16 v[120:123], v[128:131], v[176:179], v[120:123]
	v_mfma_f32_16x16x32_bf16 v[116:119], v[152:155], v[176:179], v[116:119]
	s_barrier
; #define PG8_STAGE(bufoff, gbase, voff) do { _Pragma("unroll") for (int _i = 0; _i < 2; ++_i) \
;         __builtin_amdgcn_global_load_lds((const unsigned*)((const char*)(gbase) + (voff)[_i]), (PG8_LAS unsigned*)(lds + (bufoff) + ldsw + _i * 8192), 16, 0, 0); } while (0)
; #define PG8_LDA(dst, b, h) do { _Pragma("unroll") for (int m = 0; m < 4; ++m) _Pragma("unroll") for (int k = 0; k < 2; ++k) dst[m][k] = *(const PG8_LAS bf16x8*)(lds + PG8_SA(b, h) + aoff + m * 2048 + k * 1024); } while (0)
; #define PG8_MMA(ai, bj, At, Bt) do { __builtin_amdgcn_s_setprio(1); _Pragma("unroll") for (int m = 0; m < 4; ++m) _Pragma("unroll") for (int n = 0; n < 2; ++n) _Pragma("unroll") for (int k = 0; k < 2; ++k) \
;         acc[ai][bj][m][n] = __builtin_amdgcn_mfma_f32_16x16x32_bf16(Bt[n][k], At[m][k], acc[ai][bj][m][n], 0, 0, 0); __builtin_amdgcn_s_setprio(0); } while (0)
; #define PG8_WAIT_V(n) asm volatile("s_waitcnt vmcnt(" #n ")" ::: "memory")
; #define PG8_WAIT_L(n) asm volatile("s_waitcnt lgkmcnt(" #n ")" ::: "memory")
; #define PG8_BAR __builtin_amdgcn_s_barrier()
; #define PG8_SCHED __builtin_amdgcn_sched_barrier(0)
;     ...
;             PG8_LDA(At, 1, 1); PG8_STAGE(PG8_SB(1, 0), b3, voffB); PG8_STAGE(PG8_SB(1, 1), b3 + hstepB, voffB); PG8_STAGE(PG8_SA(1, 0), a3, voffA);
;             PG8_WAIT_V(8); PG8_WAIT_L(0); PG8_BAR; PG8_MMA(1, 0, At, B0); PG8_MMA(1, 1, At, B1); PG8_BAR; PG8_SCHED;
;         }
;         if (wr == 0) PG8_BAR;
;         if (!has_next && wmat && gtid * 128u < wbytes) asm volatile("global_load_dword %0, %1, off" : "+v"(warmm) : "v"(wmat + (size_t)gtid * 128u) : "memory");
;         if (!has_next && warm) warmv = *(const volatile unsigned*)(warm + ((size_t)(tid & 255) * wK + (size_t)(tid >> 8) * BK) * 2);
;         if (ui == 0) hook();
	v_mfma_f32_16x16x32_bf16 v[96:99], v[128:131], v[184:187], v[96:99]
	v_mfma_f32_16x16x32_bf16 v[92:95], v[152:155], v[184:187], v[92:95]
	v_mfma_f32_16x16x32_bf16 v[72:75], v[128:131], v[218:221], v[72:75]
	v_mfma_f32_16x16x32_bf16 v[68:71], v[152:155], v[218:221], v[68:71]
	s_setprio 0
	s_add_i32 s20, s69, s25
	v_lshl_add_u64 v[222:223], v[222:223], 0, s[76:77]
	s_mov_b32 m0, s20
	ds_read_b128 v[156:159], v241 offset:49152
	ds_read_b128 v[168:171], v241 offset:50176
	ds_read_b128 v[172:175], v241 offset:51200
	ds_read_b128 v[176:179], v241 offset:52224
	ds_read_b128 v[180:183], v241 offset:53248
	ds_read_b128 v[184:187], v241 offset:54272
	ds_read_b128 v[188:191], v241 offset:55296
	ds_read_b128 v[218:221], v241 offset:56320
	global_load_lds_dwordx4 v[222:223], off
	v_lshl_add_u64 v[222:223], v[224:225], 0, s[76:77]
	s_add_i32 m0, s20, 0x2000
	s_add_i32 s20, s70, s25
	global_load_lds_dwordx4 v[222:223], off
	v_lshl_add_u64 v[222:223], v[244:245], 0, s[76:77]
	s_mov_b32 m0, s20
	s_nop 0
	global_load_lds_dwordx4 v[222:223], off
	v_lshl_add_u64 v[222:223], v[246:247], 0, s[76:77]
	s_add_i32 m0, s20, 0x2000
	s_nop 0
	global_load_lds_dwordx4 v[222:223], off
	v_lshl_add_u64 v[222:223], s[2:3], 0, v[198:199]
	s_mov_b32 m0, s47
	s_nop 0
	global_load_lds_dwordx4 v[222:223], off
	v_lshl_add_u64 v[222:223], s[2:3], 0, v[194:195]
	s_mov_b32 m0, s48
	s_nop 0
	global_load_lds_dwordx4 v[222:223], off
	s_waitcnt vmcnt(8)
	s_waitcnt lgkmcnt(0)
	s_barrier
	s_setprio 1
	s_waitcnt lgkmcnt(0)
	v_mfma_f32_16x16x32_bf16 v[60:63], v[76:79], v[156:159], v[60:63]
	v_mfma_f32_16x16x32_bf16 v[56:59], v[100:103], v[156:159], v[56:59]
	v_mfma_f32_16x16x32_bf16 v[44:47], v[76:79], v[172:175], v[44:47]
	v_mfma_f32_16x16x32_bf16 v[40:43], v[100:103], v[172:175], v[40:43]
	v_mfma_f32_16x16x32_bf16 v[28:31], v[76:79], v[180:183], v[28:31]
	v_mfma_f32_16x16x32_bf16 v[24:27], v[100:103], v[180:183], v[24:27]
	v_mfma_f32_16x16x32_bf16 v[12:15], v[76:79], v[188:191], v[12:15]
	v_mfma_f32_16x16x32_bf16 v[8:11], v[100:103], v[188:191], v[8:11]
	v_mfma_f32_16x16x32_bf16 v[60:63], v[88:91], v[168:171], v[60:63]
	v_mfma_f32_16x16x32_bf16 v[56:59], v[108:111], v[168:171], v[56:59]
	v_mfma_f32_16x16x32_bf16 v[44:47], v[88:91], v[176:179], v[44:47]
	v_mfma_f32_16x16x32_bf16 v[40:43], v[108:111], v[176:179], v[40:43]
	v_mfma_f32_16x16x32_bf16 v[28:31], v[88:91], v[184:187], v[28:31]
	v_mfma_f32_16x16x32_bf16 v[24:27], v[108:111], v[184:187], v[24:27]
	v_mfma_f32_16x16x32_bf16 v[12:15], v[88:91], v[218:221], v[12:15]
	v_mfma_f32_16x16x32_bf16 v[8:11], v[108:111], v[218:221], v[8:11]
	s_setprio 0
	s_setprio 1
	v_mfma_f32_16x16x32_bf16 v[52:55], v[124:127], v[156:159], v[52:55]
	v_mfma_f32_16x16x32_bf16 v[48:51], v[144:147], v[156:159], v[48:51]
	v_mfma_f32_16x16x32_bf16 v[36:39], v[124:127], v[172:175], v[36:39]
	v_mfma_f32_16x16x32_bf16 v[32:35], v[144:147], v[172:175], v[32:35]
	v_mfma_f32_16x16x32_bf16 v[20:23], v[124:127], v[180:183], v[20:23]
	v_mfma_f32_16x16x32_bf16 v[16:19], v[144:147], v[180:183], v[16:19]
	v_mfma_f32_16x16x32_bf16 v[4:7], v[124:127], v[188:191], v[4:7]
	v_mfma_f32_16x16x32_bf16 v[0:3], v[144:147], v[188:191], v[0:3]
	v_mfma_f32_16x16x32_bf16 v[52:55], v[128:131], v[168:171], v[52:55]
	v_mfma_f32_16x16x32_bf16 v[48:51], v[152:155], v[168:171], v[48:51]
	v_mfma_f32_16x16x32_bf16 v[36:39], v[128:131], v[176:179], v[36:39]
	v_mfma_f32_16x16x32_bf16 v[32:35], v[152:155], v[176:179], v[32:35]
	s_barrier
	v_mfma_f32_16x16x32_bf16 v[20:23], v[128:131], v[184:187], v[20:23]
	v_mfma_f32_16x16x32_bf16 v[16:19], v[152:155], v[184:187], v[16:19]
	v_mfma_f32_16x16x32_bf16 v[4:7], v[128:131], v[218:221], v[4:7]
	v_mfma_f32_16x16x32_bf16 v[0:3], v[152:155], v[218:221], v[0:3]
	s_setprio 0
	s_add_u32 s64, s64, 0x100
	s_addc_u32 s65, s65, 0
	s_add_u32 s66, s66, 0x100
	s_addc_u32 s67, s67, 0
	v_lshl_add_u64 v[64:65], v[64:65], 0, s[78:79]
	v_lshl_add_u64 v[66:67], v[66:67], 0, s[78:79]
	s_cmp_ge_u32 s68, s50
	s_mov_b32 s2, s68
	s_cbranch_scc0 .LBB0_534
	s_and_b64 vcc, exec, s[12:13]
	s_cbranch_vccz .LBB0_541
	s_barrier
	s_nor_b64 s[20:21], s[14:15], s[38:39]
	s_and_saveexec_b64 s[2:3], s[20:21]
	s_cbranch_execnz .LBB0_542

;     __device__ __forceinline__ const char* tile(const Unit& u, int t) const { return A + (size_t)u.pm * 2 * hstep() + (size_t)t * (BK * 2); }
;     __device__ __forceinline__ const char* tile(const Unit& u, int t) const { return U + (long)(t >> 2) * xoff + (size_t)u.pn * (1024 * 512) + (size_t)u.pm * 2 * hstep() + (size_t)(t & 3) * (BK * 2); }
; #define PG8_STAGE(bufoff, gbase, voff) do { _Pragma("unroll") for (int _i = 0; _i < 2; ++_i) \
;         __builtin_amdgcn_global_load_lds((const unsigned*)((const char*)(gbase) + (voff)[_i]), (PG8_LAS unsigned*)(lds + (bufoff) + ldsw + _i * 8192), 16, 0, 0); } while (0)
; #define PG8_LDA(dst, b, h) do { _Pragma("unroll") for (int m = 0; m < 4; ++m) _Pragma("unroll") for (int k = 0; k < 2; ++k) dst[m][k] = *(const PG8_LAS bf16x8*)(lds + PG8_SA(b, h) + aoff + m * 2048 + k * 1024); } while (0)
; #define PG8_LDB(dst, b, h) do { _Pragma("unroll") for (int n = 0; n < 2; ++n) _Pragma("unroll") for (int k = 0; k < 2; ++k) dst[n][k] = *(const PG8_LAS bf16x8*)(lds + PG8_SB(b, h) + boff + n * 2048 + k * 1024); } while (0)
; #define PG8_MMA(ai, bj, At, Bt) do { __builtin_amdgcn_s_setprio(1); _Pragma("unroll") for (int m = 0; m < 4; ++m) _Pragma("unroll") for (int n = 0; n < 2; ++n) _Pragma("unroll") for (int k = 0; k < 2; ++k) \
;         acc[ai][bj][m][n] = __builtin_amdgcn_mfma_f32_16x16x32_bf16(Bt[n][k], At[m][k], acc[ai][bj][m][n], 0, 0, 0); __builtin_amdgcn_s_setprio(0); } while (0)
; #define PG8_BAR __builtin_amdgcn_s_barrier()
;     ...
;         for (int t = 0; t < nt; t += 2) {
;             const bool last = (t == nt - 2);
;             const char* a1 = AS.tile(cur, t + 1);
;             const char* a2 = last ? AS.tile(nu, 0) : AS.tile(cur, t + 2); const char* b2 = last ? nB : cB + (size_t)(t + 2) * kstep;
;             const char* a3 = last ? AS.tile(nu, 1) : AS.tile(cur, t + 3); const char* b3 = b2 + kstep;
;             PG8_LDB(B0, 0, 0); PG8_LDB(B1, 0, 1); PG8_SCHED; PG8_LDA(At, 0, 0); PG8_STAGE(PG8_SA(1, 1), a1 + hstepA, voffA);
;             PG8_WAIT_V(8); PG8_WAIT_L(0); PG8_BAR; PG8_MMA(0, 0, At, B0); PG8_MMA(0, 1, At, B1); PG8_BAR; PG8_SCHED;
;             PG8_LDA(At, 0, 1); PG8_STAGE(PG8_SB(0, 0), b2, voffB); PG8_STAGE(PG8_SB(0, 1), b2 + hstepB, voffB); PG8_STAGE(PG8_SA(0, 0), a2, voffA);
;             PG8_WAIT_V(8); PG8_WAIT_L(0); PG8_BAR; PG8_MMA(1, 0, At, B0); PG8_MMA(1, 1, At, B1); PG8_BAR; PG8_SCHED;
.LBB0_702:
	s_add_u32 s20, s40, s2
	s_addc_u32 s21, s41, s3
	s_add_u32 s26, s20, 0x400100
	s_addc_u32 s27, s21, 0
	s_add_u32 s24, s42, s2
	s_addc_u32 s25, s43, s3
	s_add_u32 s20, s20, 0x400180
	s_addc_u32 s21, s21, 0
	s_add_i32 s63, 0, 0x10000
	s_add_i32 s66, 0, 0x14000
	v_add_u32_e32 v156, s63, v185
	v_add_u32_e32 v172, s66, v185
	ds_read_b128 v[132:135], v156
	ds_read_b128 v[136:139], v156 offset:1024
	ds_read_b128 v[140:143], v156 offset:2048
	ds_read_b128 v[156:159], v156 offset:3072
	ds_read_b128 v[160:163], v172
	ds_read_b128 v[164:167], v172 offset:1024
	ds_read_b128 v[168:171], v172 offset:2048
	ds_read_b128 v[172:175], v172 offset:3072
	s_cmpk_eq_i32 s2, 0x700
	s_cselect_b32 s21, s31, s21
	s_cselect_b32 s20, s30, s20
	s_cselect_b32 s25, s28, s25
	s_cselect_b32 s24, s1, s24
	s_cselect_b32 s27, s29, s27
	s_cselect_b32 s26, s19, s26
	v_lshl_add_u64 v[238:239], v[128:129], 0, s[2:3]
	s_add_i32 m0, s49, 0xc000
	ds_read_b128 v[176:179], v190
	ds_read_b128 v[180:183], v190 offset:1024
	ds_read_b128 v[192:195], v190 offset:2048
	ds_read_b128 v[196:199], v190 offset:3072
	ds_read_b128 v[200:203], v190 offset:4096
	ds_read_b128 v[204:207], v190 offset:5120
	ds_read_b128 v[218:221], v190 offset:6144
	ds_read_b128 v[222:225], v190 offset:7168
	global_load_lds_dwordx4 v[238:239], off
	v_lshl_add_u64 v[238:239], v[130:131], 0, s[2:3]
	s_add_i32 m0, s49, 0xe000
	s_nop 0
	global_load_lds_dwordx4 v[238:239], off
	s_waitcnt vmcnt(8)
	s_waitcnt lgkmcnt(0)
	s_barrier
	s_setprio 1
	s_waitcnt lgkmcnt(0)
	v_mfma_f32_16x16x32_bf16 v[124:127], v[132:135], v[176:179], v[124:127]
	v_mfma_f32_16x16x32_bf16 v[120:123], v[140:143], v[176:179], v[120:123]
	v_mfma_f32_16x16x32_bf16 v[112:115], v[132:135], v[192:195], v[112:115]
	v_mfma_f32_16x16x32_bf16 v[104:107], v[140:143], v[192:195], v[104:107]
	v_mfma_f32_16x16x32_bf16 v[96:99], v[132:135], v[200:203], v[96:99]
	v_mfma_f32_16x16x32_bf16 v[88:91], v[140:143], v[200:203], v[88:91]
	v_mfma_f32_16x16x32_bf16 v[80:83], v[132:135], v[218:221], v[80:83]
	v_mfma_f32_16x16x32_bf16 v[72:75], v[140:143], v[218:221], v[72:75]
	v_mfma_f32_16x16x32_bf16 v[124:127], v[136:139], v[180:183], v[124:127]
	v_mfma_f32_16x16x32_bf16 v[120:123], v[156:159], v[180:183], v[120:123]
	v_mfma_f32_16x16x32_bf16 v[112:115], v[136:139], v[196:199], v[112:115]
	v_mfma_f32_16x16x32_bf16 v[104:107], v[156:159], v[196:199], v[104:107]
	v_mfma_f32_16x16x32_bf16 v[96:99], v[136:139], v[204:207], v[96:99]
	v_mfma_f32_16x16x32_bf16 v[88:91], v[156:159], v[204:207], v[88:91]
	v_mfma_f32_16x16x32_bf16 v[80:83], v[136:139], v[222:225], v[80:83]
	v_mfma_f32_16x16x32_bf16 v[72:75], v[156:159], v[222:225], v[72:75]
	s_setprio 0
	s_setprio 1
	v_mfma_f32_16x16x32_bf16 v[116:119], v[160:163], v[176:179], v[116:119]
	v_mfma_f32_16x16x32_bf16 v[108:111], v[168:171], v[176:179], v[108:111]
	v_mfma_f32_16x16x32_bf16 v[100:103], v[160:163], v[192:195], v[100:103]
	v_mfma_f32_16x16x32_bf16 v[92:95], v[168:171], v[192:195], v[92:95]
	v_mfma_f32_16x16x32_bf16 v[84:87], v[160:163], v[200:203], v[84:87]
	v_mfma_f32_16x16x32_bf16 v[76:79], v[168:171], v[200:203], v[76:79]
	v_mfma_f32_16x16x32_bf16 v[68:71], v[160:163], v[218:221], v[68:71]
	v_mfma_f32_16x16x32_bf16 v[64:67], v[168:171], v[218:221], v[64:67]
	v_mfma_f32_16x16x32_bf16 v[116:119], v[164:167], v[180:183], v[116:119]
	v_mfma_f32_16x16x32_bf16 v[108:111], v[172:175], v[180:183], v[108:111]
	v_mfma_f32_16x16x32_bf16 v[100:103], v[164:167], v[196:199], v[100:103]
	v_mfma_f32_16x16x32_bf16 v[92:95], v[172:175], v[196:199], v[92:95]
	s_barrier
	v_mfma_f32_16x16x32_bf16 v[84:87], v[164:167], v[204:207], v[84:87]
	v_mfma_f32_16x16x32_bf16 v[76:79], v[172:175], v[204:207], v[76:79]
	v_mfma_f32_16x16x32_bf16 v[68:71], v[164:167], v[222:225], v[68:71]
	v_mfma_f32_16x16x32_bf16 v[64:67], v[172:175], v[222:225], v[64:67]
	s_setprio 0
	s_add_i32 s63, s63, s48
	v_lshl_add_u64 v[238:239], s[24:25], 0, v[148:149]
	s_mov_b32 m0, s63
	ds_read_b128 v[176:179], v190 offset:16384
	ds_read_b128 v[180:183], v190 offset:17408
	ds_read_b128 v[192:195], v190 offset:18432
	ds_read_b128 v[196:199], v190 offset:19456
	ds_read_b128 v[200:203], v190 offset:20480
	ds_read_b128 v[204:207], v190 offset:21504
	ds_read_b128 v[218:221], v190 offset:22528
	ds_read_b128 v[222:225], v190 offset:23552
	global_load_lds_dwordx4 v[238:239], off
	s_add_i32 m0, s63, 0x2000
	s_add_u32 s64, s24, 0x40000
	v_lshl_add_u64 v[240:241], s[24:25], 0, v[144:145]
	s_addc_u32 s65, s25, 0
	s_add_i32 s63, s66, s48
	global_load_lds_dwordx4 v[240:241], off
	v_lshl_add_u64 v[242:243], s[64:65], 0, v[148:149]
	s_mov_b32 m0, s63
	s_nop 0
	global_load_lds_dwordx4 v[242:243], off
	v_lshl_add_u64 v[242:243], s[64:65], 0, v[144:145]
	s_add_i32 m0, s63, 0x2000
	s_nop 0
	global_load_lds_dwordx4 v[242:243], off
	v_lshl_add_u64 v[242:243], s[26:27], 0, v[150:151]
	s_mov_b32 m0, s49
	s_nop 0
	global_load_lds_dwordx4 v[242:243], off
	v_lshl_add_u64 v[242:243], s[26:27], 0, v[146:147]
	s_mov_b32 m0, s50
	s_nop 0
	global_load_lds_dwordx4 v[242:243], off
	s_waitcnt vmcnt(8)
	s_waitcnt lgkmcnt(0)
	s_barrier
; #define PG8_STAGE(bufoff, gbase, voff) do { _Pragma("unroll") for (int _i = 0; _i < 2; ++_i) \
;         __builtin_amdgcn_global_load_lds((const unsigned*)((const char*)(gbase) + (voff)[_i]), (PG8_LAS unsigned*)(lds + (bufoff) + ldsw + _i * 8192), 16, 0, 0); } while (0)
; #define PG8_LDA(dst, b, h) do { _Pragma("unroll") for (int m = 0; m < 4; ++m) _Pragma("unroll") for (int k = 0; k < 2; ++k) dst[m][k] = *(const PG8_LAS bf16x8*)(lds + PG8_SA(b, h) + aoff + m * 2048 + k * 1024); } while (0)
; #define PG8_LDB(dst, b, h) do { _Pragma("unroll") for (int n = 0; n < 2; ++n) _Pragma("unroll") for (int k = 0; k < 2; ++k) dst[n][k] = *(const PG8_LAS bf16x8*)(lds + PG8_SB(b, h) + boff + n * 2048 + k * 1024); } while (0)
; #define PG8_MMA(ai, bj, At, Bt) do { __builtin_amdgcn_s_setprio(1); _Pragma("unroll") for (int m = 0; m < 4; ++m) _Pragma("unroll") for (int n = 0; n < 2; ++n) _Pragma("unroll") for (int k = 0; k < 2; ++k) \
;         acc[ai][bj][m][n] = __builtin_amdgcn_mfma_f32_16x16x32_bf16(Bt[n][k], At[m][k], acc[ai][bj][m][n], 0, 0, 0); __builtin_amdgcn_s_setprio(0); } while (0)
; #define PG8_WAIT_V(n) asm volatile("s_waitcnt vmcnt(" #n ")" ::: "memory")
; #define PG8_WAIT_L(n) asm volatile("s_waitcnt lgkmcnt(" #n ")" ::: "memory")
; #define PG8_BAR __builtin_amdgcn_s_barrier()
; #define PG8_SCHED __builtin_amdgcn_sched_barrier(0)
;     ...
;             PG8_WAIT_V(8); PG8_WAIT_L(0); PG8_BAR; PG8_MMA(1, 0, At, B0); PG8_MMA(1, 1, At, B1); PG8_BAR; PG8_SCHED;
;             PG8_LDB(B0, 1, 0); PG8_LDB(B1, 1, 1); PG8_SCHED; PG8_LDA(At, 1, 0); PG8_STAGE(PG8_SA(0, 1), a2 + hstepA, voffA);
;             PG8_WAIT_V(8); PG8_WAIT_L(0); PG8_BAR; PG8_MMA(0, 0, At, B0); PG8_MMA(0, 1, At, B1); PG8_BAR; PG8_SCHED;
	s_setprio 1
	s_waitcnt lgkmcnt(0)
	v_mfma_f32_16x16x32_bf16 v[60:63], v[132:135], v[176:179], v[60:63]
	v_mfma_f32_16x16x32_bf16 v[56:59], v[140:143], v[176:179], v[56:59]
	v_mfma_f32_16x16x32_bf16 v[48:51], v[132:135], v[192:195], v[48:51]
	v_mfma_f32_16x16x32_bf16 v[40:43], v[140:143], v[192:195], v[40:43]
	v_mfma_f32_16x16x32_bf16 v[32:35], v[132:135], v[200:203], v[32:35]
	v_mfma_f32_16x16x32_bf16 v[24:27], v[140:143], v[200:203], v[24:27]
	v_mfma_f32_16x16x32_bf16 v[16:19], v[132:135], v[218:221], v[16:19]
	v_mfma_f32_16x16x32_bf16 v[8:11], v[140:143], v[218:221], v[8:11]
	v_mfma_f32_16x16x32_bf16 v[60:63], v[136:139], v[180:183], v[60:63]
	v_mfma_f32_16x16x32_bf16 v[56:59], v[156:159], v[180:183], v[56:59]
	v_mfma_f32_16x16x32_bf16 v[48:51], v[136:139], v[196:199], v[48:51]
	v_mfma_f32_16x16x32_bf16 v[40:43], v[156:159], v[196:199], v[40:43]
	v_mfma_f32_16x16x32_bf16 v[32:35], v[136:139], v[204:207], v[32:35]
	v_mfma_f32_16x16x32_bf16 v[24:27], v[156:159], v[204:207], v[24:27]
	v_mfma_f32_16x16x32_bf16 v[16:19], v[136:139], v[222:225], v[16:19]
	v_mfma_f32_16x16x32_bf16 v[8:11], v[156:159], v[222:225], v[8:11]
	s_setprio 0
	s_setprio 1
	v_mfma_f32_16x16x32_bf16 v[52:55], v[160:163], v[176:179], v[52:55]
	v_mfma_f32_16x16x32_bf16 v[44:47], v[168:171], v[176:179], v[44:47]
	v_mfma_f32_16x16x32_bf16 v[36:39], v[160:163], v[192:195], v[36:39]
	v_mfma_f32_16x16x32_bf16 v[28:31], v[168:171], v[192:195], v[28:31]
	v_mfma_f32_16x16x32_bf16 v[20:23], v[160:163], v[200:203], v[20:23]
	v_mfma_f32_16x16x32_bf16 v[12:15], v[168:171], v[200:203], v[12:15]
	v_mfma_f32_16x16x32_bf16 v[4:7], v[160:163], v[218:221], v[4:7]
	v_mfma_f32_16x16x32_bf16 v[0:3], v[168:171], v[218:221], v[0:3]
	v_mfma_f32_16x16x32_bf16 v[52:55], v[164:167], v[180:183], v[52:55]
	v_mfma_f32_16x16x32_bf16 v[44:47], v[172:175], v[180:183], v[44:47]
	v_mfma_f32_16x16x32_bf16 v[36:39], v[164:167], v[196:199], v[36:39]
	v_mfma_f32_16x16x32_bf16 v[28:31], v[172:175], v[196:199], v[28:31]
	s_barrier
	v_mfma_f32_16x16x32_bf16 v[20:23], v[164:167], v[204:207], v[20:23]
	v_mfma_f32_16x16x32_bf16 v[12:15], v[172:175], v[204:207], v[12:15]
	v_mfma_f32_16x16x32_bf16 v[4:7], v[164:167], v[222:225], v[4:7]
	v_mfma_f32_16x16x32_bf16 v[0:3], v[172:175], v[222:225], v[0:3]
	s_setprio 0
	s_add_i32 s63, 0, 0x18000
	s_add_i32 s64, 0, 0x1c000
	v_add_u32_e32 v156, s63, v185
	v_add_u32_e32 v172, s64, v185
	ds_read_b128 v[132:135], v156
	ds_read_b128 v[136:139], v156 offset:1024
	ds_read_b128 v[140:143], v156 offset:2048
	ds_read_b128 v[156:159], v156 offset:3072
	ds_read_b128 v[160:163], v172
	ds_read_b128 v[164:167], v172 offset:1024
	ds_read_b128 v[168:171], v172 offset:2048
	ds_read_b128 v[172:175], v172 offset:3072
	s_add_u32 s26, s26, 0x40000
	s_addc_u32 s27, s27, 0
	s_mov_b32 m0, s51
	v_lshl_add_u64 v[242:243], s[26:27], 0, v[150:151]
	ds_read_b128 v[176:179], v190 offset:32768
	ds_read_b128 v[180:183], v190 offset:33792
	ds_read_b128 v[192:195], v190 offset:34816
	ds_read_b128 v[196:199], v190 offset:35840
	ds_read_b128 v[200:203], v190 offset:36864
	ds_read_b128 v[204:207], v190 offset:37888
	ds_read_b128 v[218:221], v190 offset:38912
	ds_read_b128 v[222:225], v190 offset:39936
	global_load_lds_dwordx4 v[242:243], off
	v_lshl_add_u64 v[242:243], s[26:27], 0, v[146:147]
	s_mov_b32 m0, s52
	s_nop 0
	global_load_lds_dwordx4 v[242:243], off
	s_waitcnt vmcnt(8)
	s_waitcnt lgkmcnt(0)
	s_barrier
	s_setprio 1
	s_waitcnt lgkmcnt(0)
	v_mfma_f32_16x16x32_bf16 v[124:127], v[132:135], v[176:179], v[124:127]
	v_mfma_f32_16x16x32_bf16 v[120:123], v[140:143], v[176:179], v[120:123]
	v_mfma_f32_16x16x32_bf16 v[112:115], v[132:135], v[192:195], v[112:115]
	v_mfma_f32_16x16x32_bf16 v[104:107], v[140:143], v[192:195], v[104:107]
	v_mfma_f32_16x16x32_bf16 v[96:99], v[132:135], v[200:203], v[96:99]
	v_mfma_f32_16x16x32_bf16 v[88:91], v[140:143], v[200:203], v[88:91]
	v_mfma_f32_16x16x32_bf16 v[80:83], v[132:135], v[218:221], v[80:83]
	v_mfma_f32_16x16x32_bf16 v[72:75], v[140:143], v[218:221], v[72:75]
	v_mfma_f32_16x16x32_bf16 v[124:127], v[136:139], v[180:183], v[124:127]
	v_mfma_f32_16x16x32_bf16 v[120:123], v[156:159], v[180:183], v[120:123]
	v_mfma_f32_16x16x32_bf16 v[112:115], v[136:139], v[196:199], v[112:115]
	v_mfma_f32_16x16x32_bf16 v[104:107], v[156:159], v[196:199], v[104:107]
	v_mfma_f32_16x16x32_bf16 v[96:99], v[136:139], v[204:207], v[96:99]
	v_mfma_f32_16x16x32_bf16 v[88:91], v[156:159], v[204:207], v[88:91]
	v_mfma_f32_16x16x32_bf16 v[80:83], v[136:139], v[222:225], v[80:83]
	v_mfma_f32_16x16x32_bf16 v[72:75], v[156:159], v[222:225], v[72:75]
	s_setprio 0
	s_setprio 1
	v_mfma_f32_16x16x32_bf16 v[116:119], v[160:163], v[176:179], v[116:119]
	v_mfma_f32_16x16x32_bf16 v[108:111], v[168:171], v[176:179], v[108:111]
	v_mfma_f32_16x16x32_bf16 v[100:103], v[160:163], v[192:195], v[100:103]
	v_mfma_f32_16x16x32_bf16 v[92:95], v[168:171], v[192:195], v[92:95]
	v_mfma_f32_16x16x32_bf16 v[84:87], v[160:163], v[200:203], v[84:87]
	v_mfma_f32_16x16x32_bf16 v[76:79], v[168:171], v[200:203], v[76:79]
	v_mfma_f32_16x16x32_bf16 v[68:71], v[160:163], v[218:221], v[68:71]
	v_mfma_f32_16x16x32_bf16 v[64:67], v[168:171], v[218:221], v[64:67]
	v_mfma_f32_16x16x32_bf16 v[116:119], v[164:167], v[180:183], v[116:119]
	v_mfma_f32_16x16x32_bf16 v[108:111], v[172:175], v[180:183], v[108:111]
	v_mfma_f32_16x16x32_bf16 v[100:103], v[164:167], v[196:199], v[100:103]
	v_mfma_f32_16x16x32_bf16 v[92:95], v[172:175], v[196:199], v[92:95]
	s_barrier
; #define PG8_STAGE(bufoff, gbase, voff) do { _Pragma("unroll") for (int _i = 0; _i < 2; ++_i) \
;         __builtin_amdgcn_global_load_lds((const unsigned*)((const char*)(gbase) + (voff)[_i]), (PG8_LAS unsigned*)(lds + (bufoff) + ldsw + _i * 8192), 16, 0, 0); } while (0)
; #define PG8_LDA(dst, b, h) do { _Pragma("unroll") for (int m = 0; m < 4; ++m) _Pragma("unroll") for (int k = 0; k < 2; ++k) dst[m][k] = *(const PG8_LAS bf16x8*)(lds + PG8_SA(b, h) + aoff + m * 2048 + k * 1024); } while (0)
; #define PG8_MMA(ai, bj, At, Bt) do { __builtin_amdgcn_s_setprio(1); _Pragma("unroll") for (int m = 0; m < 4; ++m) _Pragma("unroll") for (int n = 0; n < 2; ++n) _Pragma("unroll") for (int k = 0; k < 2; ++k) \
;         acc[ai][bj][m][n] = __builtin_amdgcn_mfma_f32_16x16x32_bf16(Bt[n][k], At[m][k], acc[ai][bj][m][n], 0, 0, 0); __builtin_amdgcn_s_setprio(0); } while (0)
; #define PG8_WAIT_V(n) asm volatile("s_waitcnt vmcnt(" #n ")" ::: "memory")
; #define PG8_WAIT_L(n) asm volatile("s_waitcnt lgkmcnt(" #n ")" ::: "memory")
; #define PG8_BAR __builtin_amdgcn_s_barrier()
; #define PG8_SCHED __builtin_amdgcn_sched_barrier(0)
;     ...
;             PG8_LDA(At, 1, 1); PG8_STAGE(PG8_SB(1, 0), b3, voffB); PG8_STAGE(PG8_SB(1, 1), b3 + hstepB, voffB); PG8_STAGE(PG8_SA(1, 0), a3, voffA);
;             PG8_WAIT_V(8); PG8_WAIT_L(0); PG8_BAR; PG8_MMA(1, 0, At, B0); PG8_MMA(1, 1, At, B1); PG8_BAR; PG8_SCHED;
;         }
;         if (wr == 0) PG8_BAR;
;         if (!has_next && wmat && gtid * 128u < wbytes) asm volatile("global_load_dword %0, %1, off" : "+v"(warmm) : "v"(wmat + (size_t)gtid * 128u) : "memory");
;         if (!has_next && warm) warmv = *(const volatile unsigned*)(warm + ((size_t)(tid & 255) * wK + (size_t)(tid >> 8) * BK) * 2);
;         if (ui == 0) hook();
	v_mfma_f32_16x16x32_bf16 v[84:87], v[164:167], v[204:207], v[84:87]
	v_mfma_f32_16x16x32_bf16 v[76:79], v[172:175], v[204:207], v[76:79]
	v_mfma_f32_16x16x32_bf16 v[68:71], v[164:167], v[222:225], v[68:71]
	v_mfma_f32_16x16x32_bf16 v[64:67], v[172:175], v[222:225], v[64:67]
	s_setprio 0
	s_add_i32 s26, s63, s48
	v_lshl_add_u64 v[238:239], v[238:239], 0, s[68:69]
	s_mov_b32 m0, s26
	ds_read_b128 v[176:179], v190 offset:49152
	ds_read_b128 v[180:183], v190 offset:50176
	ds_read_b128 v[192:195], v190 offset:51200
	ds_read_b128 v[196:199], v190 offset:52224
	ds_read_b128 v[200:203], v190 offset:53248
	ds_read_b128 v[204:207], v190 offset:54272
	ds_read_b128 v[218:221], v190 offset:55296
	ds_read_b128 v[222:225], v190 offset:56320
	global_load_lds_dwordx4 v[238:239], off
	s_add_i32 m0, s26, 0x2000
	s_add_u32 s24, s24, 0x40080
	v_lshl_add_u64 v[238:239], v[240:241], 0, s[68:69]
	s_addc_u32 s25, s25, 0
	s_add_i32 s26, s64, s48
	global_load_lds_dwordx4 v[238:239], off
	v_lshl_add_u64 v[238:239], s[24:25], 0, v[148:149]
	s_mov_b32 m0, s26
	s_nop 0
	global_load_lds_dwordx4 v[238:239], off
	v_lshl_add_u64 v[238:239], s[24:25], 0, v[144:145]
	s_add_i32 m0, s26, 0x2000
	s_nop 0
	global_load_lds_dwordx4 v[238:239], off
	v_lshl_add_u64 v[238:239], s[20:21], 0, v[150:151]
	s_mov_b32 m0, s53
	s_nop 0
	global_load_lds_dwordx4 v[238:239], off
	v_lshl_add_u64 v[238:239], s[20:21], 0, v[146:147]
	s_mov_b32 m0, s54
	s_nop 0
	global_load_lds_dwordx4 v[238:239], off
	s_waitcnt vmcnt(8)
	s_waitcnt lgkmcnt(0)
	s_barrier
	s_setprio 1
	s_waitcnt lgkmcnt(0)
	v_mfma_f32_16x16x32_bf16 v[60:63], v[132:135], v[176:179], v[60:63]
	v_mfma_f32_16x16x32_bf16 v[56:59], v[140:143], v[176:179], v[56:59]
	v_mfma_f32_16x16x32_bf16 v[48:51], v[132:135], v[192:195], v[48:51]
	v_mfma_f32_16x16x32_bf16 v[40:43], v[140:143], v[192:195], v[40:43]
	v_mfma_f32_16x16x32_bf16 v[32:35], v[132:135], v[200:203], v[32:35]
	v_mfma_f32_16x16x32_bf16 v[24:27], v[140:143], v[200:203], v[24:27]
	v_mfma_f32_16x16x32_bf16 v[16:19], v[132:135], v[218:221], v[16:19]
	v_mfma_f32_16x16x32_bf16 v[8:11], v[140:143], v[218:221], v[8:11]
	v_mfma_f32_16x16x32_bf16 v[60:63], v[136:139], v[180:183], v[60:63]
	v_mfma_f32_16x16x32_bf16 v[56:59], v[156:159], v[180:183], v[56:59]
	v_mfma_f32_16x16x32_bf16 v[48:51], v[136:139], v[196:199], v[48:51]
	v_mfma_f32_16x16x32_bf16 v[40:43], v[156:159], v[196:199], v[40:43]
	v_mfma_f32_16x16x32_bf16 v[32:35], v[136:139], v[204:207], v[32:35]
	v_mfma_f32_16x16x32_bf16 v[24:27], v[156:159], v[204:207], v[24:27]
	v_mfma_f32_16x16x32_bf16 v[16:19], v[136:139], v[222:225], v[16:19]
	v_mfma_f32_16x16x32_bf16 v[8:11], v[156:159], v[222:225], v[8:11]
	s_setprio 0
	s_setprio 1
	v_mfma_f32_16x16x32_bf16 v[52:55], v[160:163], v[176:179], v[52:55]
	v_mfma_f32_16x16x32_bf16 v[44:47], v[168:171], v[176:179], v[44:47]
	v_mfma_f32_16x16x32_bf16 v[36:39], v[160:163], v[192:195], v[36:39]
	v_mfma_f32_16x16x32_bf16 v[28:31], v[168:171], v[192:195], v[28:31]
	v_mfma_f32_16x16x32_bf16 v[20:23], v[160:163], v[200:203], v[20:23]
	v_mfma_f32_16x16x32_bf16 v[12:15], v[168:171], v[200:203], v[12:15]
	v_mfma_f32_16x16x32_bf16 v[4:7], v[160:163], v[218:221], v[4:7]
	v_mfma_f32_16x16x32_bf16 v[0:3], v[168:171], v[218:221], v[0:3]
	v_mfma_f32_16x16x32_bf16 v[52:55], v[164:167], v[180:183], v[52:55]
	v_mfma_f32_16x16x32_bf16 v[44:47], v[172:175], v[180:183], v[44:47]
	v_mfma_f32_16x16x32_bf16 v[36:39], v[164:167], v[196:199], v[36:39]
	v_mfma_f32_16x16x32_bf16 v[28:31], v[172:175], v[196:199], v[28:31]
	s_barrier
	v_mfma_f32_16x16x32_bf16 v[20:23], v[164:167], v[204:207], v[20:23]
	v_mfma_f32_16x16x32_bf16 v[12:15], v[172:175], v[204:207], v[12:15]
	v_mfma_f32_16x16x32_bf16 v[4:7], v[164:167], v[222:225], v[4:7]
	v_mfma_f32_16x16x32_bf16 v[0:3], v[172:175], v[222:225], v[0:3]
	s_setprio 0
	s_add_i32 s62, s62, 2
	s_add_u32 s2, s2, 0x100
	s_addc_u32 s3, s3, 0
	s_cmp_gt_u32 s62, 13
	s_cbranch_scc0 .LBB0_702
	s_and_b64 vcc, exec, s[12:13]
	s_cbranch_vccz .LBB0_705
	s_barrier

;     __device__ __forceinline__ size_t hstep() const { return (size_t)HALF * K * 2; }
;     __device__ __forceinline__ const char* tile(const Unit& u, int t) const { return A + (size_t)u.pm * 2 * hstep() + (size_t)t * (BK * 2); }
;     __device__ __forceinline__ size_t hstep() const { return (size_t)HALF * 512; }
; #define PG8_STAGE(bufoff, gbase, voff) do { _Pragma("unroll") for (int _i = 0; _i < 2; ++_i) \
;         __builtin_amdgcn_global_load_lds((const unsigned*)((const char*)(gbase) + (voff)[_i]), (PG8_LAS unsigned*)(lds + (bufoff) + ldsw + _i * 8192), 16, 0, 0); } while (0)
; #define PG8_LDA(dst, b, h) do { _Pragma("unroll") for (int m = 0; m < 4; ++m) _Pragma("unroll") for (int k = 0; k < 2; ++k) dst[m][k] = *(const PG8_LAS bf16x8*)(lds + PG8_SA(b, h) + aoff + m * 2048 + k * 1024); } while (0)
; #define PG8_LDB(dst, b, h) do { _Pragma("unroll") for (int n = 0; n < 2; ++n) _Pragma("unroll") for (int k = 0; k < 2; ++k) dst[n][k] = *(const PG8_LAS bf16x8*)(lds + PG8_SB(b, h) + boff + n * 2048 + k * 1024); } while (0)
; #define PG8_WAIT_V(n) asm volatile("s_waitcnt vmcnt(" #n ")" ::: "memory")
; #define PG8_WAIT_L(n) asm volatile("s_waitcnt lgkmcnt(" #n ")" ::: "memory")
; #define PG8_BAR __builtin_amdgcn_s_barrier()
; #define PG8_SCHED __builtin_amdgcn_sched_barrier(0)
;     __device__ __forceinline__ const char* tile(const Unit& u, int t) const { return U + (long)(t >> 2) * xoff + (size_t)u.pn * (1024 * 512) + (size_t)u.pm * 2 * hstep() + (size_t)(t & 3) * (BK * 2); }
;     ...
;         for (int t = 0; t < nt; t += 2) {
;             const bool last = (t == nt - 2);
;             const char* a1 = AS.tile(cur, t + 1);
;             const char* a2 = last ? AS.tile(nu, 0) : AS.tile(cur, t + 2); const char* b2 = last ? nB : cB + (size_t)(t + 2) * kstep;
;             const char* a3 = last ? AS.tile(nu, 1) : AS.tile(cur, t + 3); const char* b3 = b2 + kstep;
;             PG8_LDB(B0, 0, 0); PG8_LDB(B1, 0, 1); PG8_SCHED; PG8_LDA(At, 0, 0); PG8_STAGE(PG8_SA(1, 1), a1 + hstepA, voffA);
;             PG8_WAIT_V(8); PG8_WAIT_L(0); PG8_BAR; PG8_MMA(0, 0, At, B0); PG8_MMA(0, 1, At, B1); PG8_BAR; PG8_SCHED;
;             PG8_LDA(At, 0, 1); PG8_STAGE(PG8_SB(0, 0), b2, voffB); PG8_STAGE(PG8_SB(0, 1), b2 + hstepB, voffB); PG8_STAGE(PG8_SA(0, 0), a2, voffA);
;             PG8_WAIT_V(8); PG8_WAIT_L(0); PG8_BAR; PG8_MMA(1, 0, At, B0); PG8_MMA(1, 1, At, B1); PG8_BAR; PG8_SCHED;
.LBB0_785:
	s_add_u32 s24, s9, s14
	s_addc_u32 s25, s47, 0
	s_xor_b32 s15, s14, 0x100
	s_add_u32 s15, s9, s15
	s_addc_u32 s20, s47, 0
	s_and_b64 s[18:19], s[16:17], exec
	s_cselect_b32 s21, s49, s20
	s_cselect_b32 s20, s48, s15
	s_add_u32 s15, s52, s14
	s_addc_u32 s18, s53, 0
	s_add_u32 s15, s15, 0x100
	s_addc_u32 s22, s18, 0
	s_and_b64 s[18:19], s[16:17], exec
	s_cselect_b32 s23, s46, s22
	s_cselect_b32 s22, s45, s15
	s_addk_i32 s14, 0x180
	s_and_b32 s14, s14, 0x180
	s_add_u32 s18, s9, s14
	s_addc_u32 s19, s47, 0
	s_and_b64 s[14:15], s[16:17], exec
	s_cselect_b32 s14, s50, s18
	s_cselect_b32 s15, s51, s19
	s_add_i32 s17, 0, 0x10000
	s_add_i32 s62, 0, 0x14000
	s_add_u32 s26, s24, 0x10080
	s_addc_u32 s27, s25, 0
	s_add_i32 s61, s17, s30
	s_add_i32 m0, s31, 0xc000
	s_add_i32 s64, s31, 0xe000
	s_add_i32 s58, s61, 0x2000
	v_add_u32_e32 v140, s17, v159
	s_add_u32 s24, s22, 0x10000
	ds_read_b128 v[162:165], v140
	ds_read_b128 v[166:169], v140 offset:1024
	ds_read_b128 v[170:173], v140 offset:2048
	ds_read_b128 v[174:177], v140 offset:3072
	v_add_u32_e32 v140, s62, v159
	s_addc_u32 s25, s23, 0
	s_add_i32 s60, s62, s30
	ds_read_b128 v[178:181], v140
	ds_read_b128 v[182:185], v140 offset:1024
	ds_read_b128 v[186:189], v140 offset:2048
	ds_read_b128 v[190:193], v140 offset:3072
	s_add_i32 s59, s60, 0x2000
	s_add_i32 s57, 0, 0x18000
	s_add_i32 s56, 0, 0x1c000
	s_add_u32 s18, s20, 0x10000
	s_addc_u32 s19, s21, 0
	s_add_i32 s55, s57, s30
	s_add_i32 s54, s55, 0x2000
	s_add_u32 s16, s22, 0x10080
	s_addc_u32 s17, s23, 0
	s_add_i32 s63, s56, s30
	s_add_i32 s62, s63, 0x2000
	v_lshl_add_u64 v[140:141], s[26:27], 0, v[128:129]
	ds_read_b128 v[194:197], v160
	ds_read_b128 v[198:201], v160 offset:1024
	ds_read_b128 v[202:205], v160 offset:2048
	ds_read_b128 v[218:221], v160 offset:3072
	ds_read_b128 v[222:225], v160 offset:4096
	ds_read_b128 v[238:241], v160 offset:5120
	ds_read_b128 v[242:245], v160 offset:6144
	ds_read_b128 v[246:249], v160 offset:7168
	global_load_lds_dwordx4 v[140:141], off
	v_lshl_add_u64 v[140:141], s[26:27], 0, v[130:131]
	s_mov_b32 m0, s64
	s_nop 0
	global_load_lds_dwordx4 v[140:141], off
	s_waitcnt vmcnt(8)
	s_waitcnt lgkmcnt(0)
	s_barrier
	s_setprio 1
	s_waitcnt lgkmcnt(0)
	v_mfma_f32_16x16x32_bf16 v[124:127], v[162:165], v[194:197], v[124:127]
	v_mfma_f32_16x16x32_bf16 v[120:123], v[170:173], v[194:197], v[120:123]
	v_mfma_f32_16x16x32_bf16 v[116:119], v[162:165], v[202:205], v[116:119]
	v_mfma_f32_16x16x32_bf16 v[108:111], v[170:173], v[202:205], v[108:111]
	v_mfma_f32_16x16x32_bf16 v[100:103], v[162:165], v[222:225], v[100:103]
	v_mfma_f32_16x16x32_bf16 v[92:95], v[170:173], v[222:225], v[92:95]
	v_mfma_f32_16x16x32_bf16 v[84:87], v[162:165], v[242:245], v[84:87]
	v_mfma_f32_16x16x32_bf16 v[76:79], v[170:173], v[242:245], v[76:79]
	v_mfma_f32_16x16x32_bf16 v[124:127], v[166:169], v[198:201], v[124:127]
	v_mfma_f32_16x16x32_bf16 v[120:123], v[174:177], v[198:201], v[120:123]
	v_mfma_f32_16x16x32_bf16 v[116:119], v[166:169], v[218:221], v[116:119]
	v_mfma_f32_16x16x32_bf16 v[108:111], v[174:177], v[218:221], v[108:111]
	v_mfma_f32_16x16x32_bf16 v[100:103], v[166:169], v[238:241], v[100:103]
	v_mfma_f32_16x16x32_bf16 v[92:95], v[174:177], v[238:241], v[92:95]
	v_mfma_f32_16x16x32_bf16 v[84:87], v[166:169], v[246:249], v[84:87]
	v_mfma_f32_16x16x32_bf16 v[76:79], v[174:177], v[246:249], v[76:79]
	s_setprio 0
	s_setprio 1
	v_mfma_f32_16x16x32_bf16 v[112:115], v[178:181], v[194:197], v[112:115]
	v_mfma_f32_16x16x32_bf16 v[104:107], v[186:189], v[194:197], v[104:107]
	v_mfma_f32_16x16x32_bf16 v[96:99], v[178:181], v[202:205], v[96:99]
	v_mfma_f32_16x16x32_bf16 v[88:91], v[186:189], v[202:205], v[88:91]
	v_mfma_f32_16x16x32_bf16 v[80:83], v[178:181], v[222:225], v[80:83]
	v_mfma_f32_16x16x32_bf16 v[72:75], v[186:189], v[222:225], v[72:75]
	v_mfma_f32_16x16x32_bf16 v[68:71], v[178:181], v[242:245], v[68:71]
	v_mfma_f32_16x16x32_bf16 v[64:67], v[186:189], v[242:245], v[64:67]
	v_mfma_f32_16x16x32_bf16 v[112:115], v[182:185], v[198:201], v[112:115]
	v_mfma_f32_16x16x32_bf16 v[104:107], v[190:193], v[198:201], v[104:107]
	v_mfma_f32_16x16x32_bf16 v[96:99], v[182:185], v[218:221], v[96:99]
	v_mfma_f32_16x16x32_bf16 v[88:91], v[190:193], v[218:221], v[88:91]
	s_barrier
	v_mfma_f32_16x16x32_bf16 v[80:83], v[182:185], v[238:241], v[80:83]
	v_mfma_f32_16x16x32_bf16 v[72:75], v[190:193], v[238:241], v[72:75]
	v_mfma_f32_16x16x32_bf16 v[68:71], v[182:185], v[246:249], v[68:71]
	v_mfma_f32_16x16x32_bf16 v[64:67], v[190:193], v[246:249], v[64:67]
	s_setprio 0
	s_mov_b32 m0, s61
	v_lshl_add_u64 v[140:141], s[22:23], 0, v[134:135]
	ds_read_b128 v[194:197], v160 offset:16384
	ds_read_b128 v[198:201], v160 offset:17408
	ds_read_b128 v[202:205], v160 offset:18432
	ds_read_b128 v[218:221], v160 offset:19456
	ds_read_b128 v[222:225], v160 offset:20480
	ds_read_b128 v[238:241], v160 offset:21504
	ds_read_b128 v[242:245], v160 offset:22528
	ds_read_b128 v[246:249], v160 offset:23552
	global_load_lds_dwordx4 v[140:141], off
	v_lshl_add_u64 v[206:207], s[22:23], 0, v[132:133]
	s_mov_b32 m0, s58
	v_lshl_add_u64 v[250:251], s[24:25], 0, v[134:135]
	global_load_lds_dwordx4 v[206:207], off
	s_mov_b32 m0, s60
	s_nop 0
	global_load_lds_dwordx4 v[250:251], off
	v_lshl_add_u64 v[250:251], s[24:25], 0, v[132:133]
	s_mov_b32 m0, s59
	s_nop 0
	global_load_lds_dwordx4 v[250:251], off
	v_lshl_add_u64 v[250:251], s[20:21], 0, v[128:129]
	s_mov_b32 m0, s31
	s_nop 0
	global_load_lds_dwordx4 v[250:251], off
	v_lshl_add_u64 v[250:251], s[20:21], 0, v[130:131]
	s_mov_b32 m0, s35
	s_nop 0
	global_load_lds_dwordx4 v[250:251], off
	s_waitcnt vmcnt(8)
	s_waitcnt lgkmcnt(0)
	s_barrier
;     __device__ __forceinline__ size_t hstep() const { return (size_t)HALF * K * 2; }
;     __device__ __forceinline__ const char* tile(const Unit& u, int t) const { return A + (size_t)u.pm * 2 * hstep() + (size_t)t * (BK * 2); }
;     __device__ __forceinline__ size_t hstep() const { return (size_t)HALF * 512; }
; #define PG8_STAGE(bufoff, gbase, voff) do { _Pragma("unroll") for (int _i = 0; _i < 2; ++_i) \
;         __builtin_amdgcn_global_load_lds((const unsigned*)((const char*)(gbase) + (voff)[_i]), (PG8_LAS unsigned*)(lds + (bufoff) + ldsw + _i * 8192), 16, 0, 0); } while (0)
; #define PG8_LDA(dst, b, h) do { _Pragma("unroll") for (int m = 0; m < 4; ++m) _Pragma("unroll") for (int k = 0; k < 2; ++k) dst[m][k] = *(const PG8_LAS bf16x8*)(lds + PG8_SA(b, h) + aoff + m * 2048 + k * 1024); } while (0)
; #define PG8_LDB(dst, b, h) do { _Pragma("unroll") for (int n = 0; n < 2; ++n) _Pragma("unroll") for (int k = 0; k < 2; ++k) dst[n][k] = *(const PG8_LAS bf16x8*)(lds + PG8_SB(b, h) + boff + n * 2048 + k * 1024); } while (0)
; #define PG8_MMA(ai, bj, At, Bt) do { __builtin_amdgcn_s_setprio(1); _Pragma("unroll") for (int m = 0; m < 4; ++m) _Pragma("unroll") for (int n = 0; n < 2; ++n) _Pragma("unroll") for (int k = 0; k < 2; ++k) \
;         acc[ai][bj][m][n] = __builtin_amdgcn_mfma_f32_16x16x32_bf16(Bt[n][k], At[m][k], acc[ai][bj][m][n], 0, 0, 0); __builtin_amdgcn_s_setprio(0); } while (0)
; #define PG8_WAIT_V(n) asm volatile("s_waitcnt vmcnt(" #n ")" ::: "memory")
; #define PG8_WAIT_L(n) asm volatile("s_waitcnt lgkmcnt(" #n ")" ::: "memory")
; #define PG8_BAR __builtin_amdgcn_s_barrier()
; #define PG8_SCHED __builtin_amdgcn_sched_barrier(0)
;     __device__ __forceinline__ const char* tile(const Unit& u, int t) const { return U + (long)(t >> 2) * xoff + (size_t)u.pn * (1024 * 512) + (size_t)u.pm * 2 * hstep() + (size_t)(t & 3) * (BK * 2); }
;     ...
;             PG8_WAIT_V(8); PG8_WAIT_L(0); PG8_BAR; PG8_MMA(1, 0, At, B0); PG8_MMA(1, 1, At, B1); PG8_BAR; PG8_SCHED;
;             PG8_LDB(B0, 1, 0); PG8_LDB(B1, 1, 1); PG8_SCHED; PG8_LDA(At, 1, 0); PG8_STAGE(PG8_SA(0, 1), a2 + hstepA, voffA);
;             PG8_WAIT_V(8); PG8_WAIT_L(0); PG8_BAR; PG8_MMA(0, 0, At, B0); PG8_MMA(0, 1, At, B1); PG8_BAR; PG8_SCHED;
	s_setprio 1
	s_waitcnt lgkmcnt(0)
	v_mfma_f32_16x16x32_bf16 v[60:63], v[162:165], v[194:197], v[60:63]
	v_mfma_f32_16x16x32_bf16 v[56:59], v[170:173], v[194:197], v[56:59]
	v_mfma_f32_16x16x32_bf16 v[52:55], v[162:165], v[202:205], v[52:55]
	v_mfma_f32_16x16x32_bf16 v[44:47], v[170:173], v[202:205], v[44:47]
	v_mfma_f32_16x16x32_bf16 v[36:39], v[162:165], v[222:225], v[36:39]
	v_mfma_f32_16x16x32_bf16 v[28:31], v[170:173], v[222:225], v[28:31]
	v_mfma_f32_16x16x32_bf16 v[20:23], v[162:165], v[242:245], v[20:23]
	v_mfma_f32_16x16x32_bf16 v[12:15], v[170:173], v[242:245], v[12:15]
	v_mfma_f32_16x16x32_bf16 v[60:63], v[166:169], v[198:201], v[60:63]
	v_mfma_f32_16x16x32_bf16 v[56:59], v[174:177], v[198:201], v[56:59]
	v_mfma_f32_16x16x32_bf16 v[52:55], v[166:169], v[218:221], v[52:55]
	v_mfma_f32_16x16x32_bf16 v[44:47], v[174:177], v[218:221], v[44:47]
	v_mfma_f32_16x16x32_bf16 v[36:39], v[166:169], v[238:241], v[36:39]
	v_mfma_f32_16x16x32_bf16 v[28:31], v[174:177], v[238:241], v[28:31]
	v_mfma_f32_16x16x32_bf16 v[20:23], v[166:169], v[246:249], v[20:23]
	v_mfma_f32_16x16x32_bf16 v[12:15], v[174:177], v[246:249], v[12:15]
	s_setprio 0
	s_setprio 1
	v_mfma_f32_16x16x32_bf16 v[48:51], v[178:181], v[194:197], v[48:51]
	v_mfma_f32_16x16x32_bf16 v[40:43], v[186:189], v[194:197], v[40:43]
	v_mfma_f32_16x16x32_bf16 v[32:35], v[178:181], v[202:205], v[32:35]
	v_mfma_f32_16x16x32_bf16 v[24:27], v[186:189], v[202:205], v[24:27]
	v_mfma_f32_16x16x32_bf16 v[16:19], v[178:181], v[222:225], v[16:19]
	v_mfma_f32_16x16x32_bf16 v[8:11], v[186:189], v[222:225], v[8:11]
	v_mfma_f32_16x16x32_bf16 v[4:7], v[178:181], v[242:245], v[4:7]
	v_mfma_f32_16x16x32_bf16 v[0:3], v[186:189], v[242:245], v[0:3]
	v_mfma_f32_16x16x32_bf16 v[48:51], v[182:185], v[198:201], v[48:51]
	v_mfma_f32_16x16x32_bf16 v[40:43], v[190:193], v[198:201], v[40:43]
	v_mfma_f32_16x16x32_bf16 v[32:35], v[182:185], v[218:221], v[32:35]
	v_mfma_f32_16x16x32_bf16 v[24:27], v[190:193], v[218:221], v[24:27]
	s_barrier
	v_mfma_f32_16x16x32_bf16 v[16:19], v[182:185], v[238:241], v[16:19]
	v_mfma_f32_16x16x32_bf16 v[8:11], v[190:193], v[238:241], v[8:11]
	v_mfma_f32_16x16x32_bf16 v[4:7], v[182:185], v[246:249], v[4:7]
	v_mfma_f32_16x16x32_bf16 v[0:3], v[190:193], v[246:249], v[0:3]
	s_setprio 0
	v_add_u32_e32 v161, s57, v159
	ds_read_b128 v[162:165], v161
	ds_read_b128 v[166:169], v161 offset:1024
	ds_read_b128 v[170:173], v161 offset:2048
	ds_read_b128 v[174:177], v161 offset:3072
	v_add_u32_e32 v161, s56, v159
	ds_read_b128 v[178:181], v161
	ds_read_b128 v[182:185], v161 offset:1024
	ds_read_b128 v[186:189], v161 offset:2048
	ds_read_b128 v[190:193], v161 offset:3072
	s_mov_b32 m0, s36
	v_lshl_add_u64 v[250:251], s[18:19], 0, v[128:129]
	ds_read_b128 v[194:197], v160 offset:32768
	ds_read_b128 v[198:201], v160 offset:33792
	ds_read_b128 v[202:205], v160 offset:34816
	ds_read_b128 v[218:221], v160 offset:35840
	ds_read_b128 v[222:225], v160 offset:36864
	ds_read_b128 v[238:241], v160 offset:37888
	ds_read_b128 v[242:245], v160 offset:38912
	ds_read_b128 v[246:249], v160 offset:39936
	global_load_lds_dwordx4 v[250:251], off
	v_lshl_add_u64 v[250:251], s[18:19], 0, v[130:131]
	s_mov_b32 m0, s37
	s_nop 0
	global_load_lds_dwordx4 v[250:251], off
	s_waitcnt vmcnt(8)
	s_waitcnt lgkmcnt(0)
	s_barrier
	s_setprio 1
	s_waitcnt lgkmcnt(0)
	v_mfma_f32_16x16x32_bf16 v[124:127], v[162:165], v[194:197], v[124:127]
	v_mfma_f32_16x16x32_bf16 v[120:123], v[170:173], v[194:197], v[120:123]
	v_mfma_f32_16x16x32_bf16 v[116:119], v[162:165], v[202:205], v[116:119]
	v_mfma_f32_16x16x32_bf16 v[108:111], v[170:173], v[202:205], v[108:111]
	v_mfma_f32_16x16x32_bf16 v[100:103], v[162:165], v[222:225], v[100:103]
	v_mfma_f32_16x16x32_bf16 v[92:95], v[170:173], v[222:225], v[92:95]
	v_mfma_f32_16x16x32_bf16 v[84:87], v[162:165], v[242:245], v[84:87]
	v_mfma_f32_16x16x32_bf16 v[76:79], v[170:173], v[242:245], v[76:79]
	v_mfma_f32_16x16x32_bf16 v[124:127], v[166:169], v[198:201], v[124:127]
	v_mfma_f32_16x16x32_bf16 v[120:123], v[174:177], v[198:201], v[120:123]
	v_mfma_f32_16x16x32_bf16 v[116:119], v[166:169], v[218:221], v[116:119]
	v_mfma_f32_16x16x32_bf16 v[108:111], v[174:177], v[218:221], v[108:111]
	v_mfma_f32_16x16x32_bf16 v[100:103], v[166:169], v[238:241], v[100:103]
	v_mfma_f32_16x16x32_bf16 v[92:95], v[174:177], v[238:241], v[92:95]
	v_mfma_f32_16x16x32_bf16 v[84:87], v[166:169], v[246:249], v[84:87]
	v_mfma_f32_16x16x32_bf16 v[76:79], v[174:177], v[246:249], v[76:79]
	s_setprio 0
	s_setprio 1
	v_mfma_f32_16x16x32_bf16 v[112:115], v[178:181], v[194:197], v[112:115]
	v_mfma_f32_16x16x32_bf16 v[104:107], v[186:189], v[194:197], v[104:107]
	v_mfma_f32_16x16x32_bf16 v[96:99], v[178:181], v[202:205], v[96:99]
	v_mfma_f32_16x16x32_bf16 v[88:91], v[186:189], v[202:205], v[88:91]
	v_mfma_f32_16x16x32_bf16 v[80:83], v[178:181], v[222:225], v[80:83]
	v_mfma_f32_16x16x32_bf16 v[72:75], v[186:189], v[222:225], v[72:75]
	v_mfma_f32_16x16x32_bf16 v[68:71], v[178:181], v[242:245], v[68:71]
	v_mfma_f32_16x16x32_bf16 v[64:67], v[186:189], v[242:245], v[64:67]
	v_mfma_f32_16x16x32_bf16 v[112:115], v[182:185], v[198:201], v[112:115]
	v_mfma_f32_16x16x32_bf16 v[104:107], v[190:193], v[198:201], v[104:107]
	v_mfma_f32_16x16x32_bf16 v[96:99], v[182:185], v[218:221], v[96:99]
	v_mfma_f32_16x16x32_bf16 v[88:91], v[190:193], v[218:221], v[88:91]
	s_barrier
; #define PG8_STAGE(bufoff, gbase, voff) do { _Pragma("unroll") for (int _i = 0; _i < 2; ++_i) \
;         __builtin_amdgcn_global_load_lds((const unsigned*)((const char*)(gbase) + (voff)[_i]), (PG8_LAS unsigned*)(lds + (bufoff) + ldsw + _i * 8192), 16, 0, 0); } while (0)
; #define PG8_LDA(dst, b, h) do { _Pragma("unroll") for (int m = 0; m < 4; ++m) _Pragma("unroll") for (int k = 0; k < 2; ++k) dst[m][k] = *(const PG8_LAS bf16x8*)(lds + PG8_SA(b, h) + aoff + m * 2048 + k * 1024); } while (0)
; #define PG8_MMA(ai, bj, At, Bt) do { __builtin_amdgcn_s_setprio(1); _Pragma("unroll") for (int m = 0; m < 4; ++m) _Pragma("unroll") for (int n = 0; n < 2; ++n) _Pragma("unroll") for (int k = 0; k < 2; ++k) \
;         acc[ai][bj][m][n] = __builtin_amdgcn_mfma_f32_16x16x32_bf16(Bt[n][k], At[m][k], acc[ai][bj][m][n], 0, 0, 0); __builtin_amdgcn_s_setprio(0); } while (0)
; #define PG8_WAIT_V(n) asm volatile("s_waitcnt vmcnt(" #n ")" ::: "memory")
; #define PG8_WAIT_L(n) asm volatile("s_waitcnt lgkmcnt(" #n ")" ::: "memory")
; #define PG8_BAR __builtin_amdgcn_s_barrier()
; #define PG8_SCHED __builtin_amdgcn_sched_barrier(0)
;     ...
;             PG8_LDA(At, 1, 1); PG8_STAGE(PG8_SB(1, 0), b3, voffB); PG8_STAGE(PG8_SB(1, 1), b3 + hstepB, voffB); PG8_STAGE(PG8_SA(1, 0), a3, voffA);
;             PG8_WAIT_V(8); PG8_WAIT_L(0); PG8_BAR; PG8_MMA(1, 0, At, B0); PG8_MMA(1, 1, At, B1); PG8_BAR; PG8_SCHED;
;         }
;         if (wr == 0) PG8_BAR;
;         if (!has_next && wmat && gtid * 128u < wbytes) asm volatile("global_load_dword %0, %1, off" : "+v"(warmm) : "v"(wmat + (size_t)gtid * 128u) : "memory");
;         if (!has_next && warm) warmv = *(const volatile unsigned*)(warm + ((size_t)(tid & 255) * wK + (size_t)(tid >> 8) * BK) * 2);
;         if (ui == 0) hook();
	v_mfma_f32_16x16x32_bf16 v[80:83], v[182:185], v[238:241], v[80:83]
	v_mfma_f32_16x16x32_bf16 v[72:75], v[190:193], v[238:241], v[72:75]
	v_mfma_f32_16x16x32_bf16 v[68:71], v[182:185], v[246:249], v[68:71]
	v_mfma_f32_16x16x32_bf16 v[64:67], v[190:193], v[246:249], v[64:67]
	s_setprio 0
	s_mov_b32 m0, s55
	v_lshl_add_u64 v[140:141], v[140:141], 0, s[66:67]
	ds_read_b128 v[194:197], v160 offset:49152
	ds_read_b128 v[198:201], v160 offset:50176
	ds_read_b128 v[202:205], v160 offset:51200
	ds_read_b128 v[218:221], v160 offset:52224
	ds_read_b128 v[222:225], v160 offset:53248
	ds_read_b128 v[238:241], v160 offset:54272
	ds_read_b128 v[242:245], v160 offset:55296
	ds_read_b128 v[246:249], v160 offset:56320
	global_load_lds_dwordx4 v[140:141], off
	v_lshl_add_u64 v[140:141], v[206:207], 0, s[66:67]
	s_mov_b32 m0, s54
	s_nop 0
	global_load_lds_dwordx4 v[140:141], off
	v_lshl_add_u64 v[140:141], s[16:17], 0, v[134:135]
	s_mov_b32 m0, s63
	s_nop 0
	global_load_lds_dwordx4 v[140:141], off
	v_lshl_add_u64 v[140:141], s[16:17], 0, v[132:133]
	s_mov_b32 m0, s62
	s_nop 0
	global_load_lds_dwordx4 v[140:141], off
	v_lshl_add_u64 v[140:141], s[14:15], 0, v[128:129]
	s_mov_b32 m0, s40
	s_nop 0
	global_load_lds_dwordx4 v[140:141], off
	v_lshl_add_u64 v[140:141], s[14:15], 0, v[130:131]
	s_mov_b32 m0, s41
	s_nop 0
	global_load_lds_dwordx4 v[140:141], off
	s_waitcnt vmcnt(8)
	s_waitcnt lgkmcnt(0)
	s_barrier
	s_setprio 1
	s_waitcnt lgkmcnt(0)
	v_mfma_f32_16x16x32_bf16 v[60:63], v[162:165], v[194:197], v[60:63]
	v_mfma_f32_16x16x32_bf16 v[56:59], v[170:173], v[194:197], v[56:59]
	v_mfma_f32_16x16x32_bf16 v[52:55], v[162:165], v[202:205], v[52:55]
	v_mfma_f32_16x16x32_bf16 v[44:47], v[170:173], v[202:205], v[44:47]
	v_mfma_f32_16x16x32_bf16 v[36:39], v[162:165], v[222:225], v[36:39]
	v_mfma_f32_16x16x32_bf16 v[28:31], v[170:173], v[222:225], v[28:31]
	v_mfma_f32_16x16x32_bf16 v[20:23], v[162:165], v[242:245], v[20:23]
	v_mfma_f32_16x16x32_bf16 v[12:15], v[170:173], v[242:245], v[12:15]
	v_mfma_f32_16x16x32_bf16 v[60:63], v[166:169], v[198:201], v[60:63]
	v_mfma_f32_16x16x32_bf16 v[56:59], v[174:177], v[198:201], v[56:59]
	v_mfma_f32_16x16x32_bf16 v[52:55], v[166:169], v[218:221], v[52:55]
	v_mfma_f32_16x16x32_bf16 v[44:47], v[174:177], v[218:221], v[44:47]
	v_mfma_f32_16x16x32_bf16 v[36:39], v[166:169], v[238:241], v[36:39]
	v_mfma_f32_16x16x32_bf16 v[28:31], v[174:177], v[238:241], v[28:31]
	v_mfma_f32_16x16x32_bf16 v[20:23], v[166:169], v[246:249], v[20:23]
	v_mfma_f32_16x16x32_bf16 v[12:15], v[174:177], v[246:249], v[12:15]
	s_setprio 0
	s_setprio 1
	v_mfma_f32_16x16x32_bf16 v[48:51], v[178:181], v[194:197], v[48:51]
	v_mfma_f32_16x16x32_bf16 v[40:43], v[186:189], v[194:197], v[40:43]
	v_mfma_f32_16x16x32_bf16 v[32:35], v[178:181], v[202:205], v[32:35]
	v_mfma_f32_16x16x32_bf16 v[24:27], v[186:189], v[202:205], v[24:27]
	v_mfma_f32_16x16x32_bf16 v[16:19], v[178:181], v[222:225], v[16:19]
	v_mfma_f32_16x16x32_bf16 v[8:11], v[186:189], v[222:225], v[8:11]
	v_mfma_f32_16x16x32_bf16 v[4:7], v[178:181], v[242:245], v[4:7]
	v_mfma_f32_16x16x32_bf16 v[0:3], v[186:189], v[242:245], v[0:3]
	v_mfma_f32_16x16x32_bf16 v[48:51], v[182:185], v[198:201], v[48:51]
	v_mfma_f32_16x16x32_bf16 v[40:43], v[190:193], v[198:201], v[40:43]
	v_mfma_f32_16x16x32_bf16 v[32:35], v[182:185], v[218:221], v[32:35]
	v_mfma_f32_16x16x32_bf16 v[24:27], v[190:193], v[218:221], v[24:27]
	s_barrier
	v_mfma_f32_16x16x32_bf16 v[16:19], v[182:185], v[238:241], v[16:19]
	v_mfma_f32_16x16x32_bf16 v[8:11], v[190:193], v[238:241], v[8:11]
	v_mfma_f32_16x16x32_bf16 v[4:7], v[182:185], v[246:249], v[4:7]
	v_mfma_f32_16x16x32_bf16 v[0:3], v[190:193], v[246:249], v[0:3]
	s_setprio 0
	s_andn2_b64 vcc, exec, s[12:13]
	s_mov_b64 s[16:17], -1
	s_mov_b64 s[12:13], 0
	s_movk_i32 s14, 0x100
	s_cbranch_vccz .LBB0_785
	s_and_b64 vcc, exec, s[4:5]
	s_cbranch_vccz .LBB0_788
	s_barrier

;     __device__ __forceinline__ size_t hstep() const { return (size_t)HALF * K * 2; }
;     __device__ __forceinline__ const char* tile(const Unit& u, int t) const { return A + (size_t)u.pm * 2 * hstep() + (size_t)t * (BK * 2); }
;     __device__ __forceinline__ size_t hstep() const { return (size_t)HALF * 512; }
; #define PG8_STAGE(bufoff, gbase, voff) do { _Pragma("unroll") for (int _i = 0; _i < 2; ++_i) \
;         __builtin_amdgcn_global_load_lds((const unsigned*)((const char*)(gbase) + (voff)[_i]), (PG8_LAS unsigned*)(lds + (bufoff) + ldsw + _i * 8192), 16, 0, 0); } while (0)
; #define PG8_LDA(dst, b, h) do { _Pragma("unroll") for (int m = 0; m < 4; ++m) _Pragma("unroll") for (int k = 0; k < 2; ++k) dst[m][k] = *(const PG8_LAS bf16x8*)(lds + PG8_SA(b, h) + aoff + m * 2048 + k * 1024); } while (0)
; #define PG8_LDB(dst, b, h) do { _Pragma("unroll") for (int n = 0; n < 2; ++n) _Pragma("unroll") for (int k = 0; k < 2; ++k) dst[n][k] = *(const PG8_LAS bf16x8*)(lds + PG8_SB(b, h) + boff + n * 2048 + k * 1024); } while (0)
; #define PG8_WAIT_V(n) asm volatile("s_waitcnt vmcnt(" #n ")" ::: "memory")
; #define PG8_WAIT_L(n) asm volatile("s_waitcnt lgkmcnt(" #n ")" ::: "memory")
; #define PG8_BAR __builtin_amdgcn_s_barrier()
; #define PG8_SCHED __builtin_amdgcn_sched_barrier(0)
;     __device__ __forceinline__ const char* tile(const Unit& u, int t) const { return U + (long)(t >> 2) * xoff + (size_t)u.pn * (1024 * 512) + (size_t)u.pm * 2 * hstep() + (size_t)(t & 3) * (BK * 2); }
;     ...
;         for (int t = 0; t < nt; t += 2) {
;             const bool last = (t == nt - 2);
;             const char* a1 = AS.tile(cur, t + 1);
;             const char* a2 = last ? AS.tile(nu, 0) : AS.tile(cur, t + 2); const char* b2 = last ? nB : cB + (size_t)(t + 2) * kstep;
;             const char* a3 = last ? AS.tile(nu, 1) : AS.tile(cur, t + 3); const char* b3 = b2 + kstep;
;             PG8_LDB(B0, 0, 0); PG8_LDB(B1, 0, 1); PG8_SCHED; PG8_LDA(At, 0, 0); PG8_STAGE(PG8_SA(1, 1), a1 + hstepA, voffA);
;             PG8_WAIT_V(8); PG8_WAIT_L(0); PG8_BAR; PG8_MMA(0, 0, At, B0); PG8_MMA(0, 1, At, B1); PG8_BAR; PG8_SCHED;
;             PG8_LDA(At, 0, 1); PG8_STAGE(PG8_SB(0, 0), b2, voffB); PG8_STAGE(PG8_SB(0, 1), b2 + hstepB, voffB); PG8_STAGE(PG8_SA(0, 0), a2, voffA);
;             PG8_WAIT_V(8); PG8_WAIT_L(0); PG8_BAR; PG8_MMA(1, 0, At, B0); PG8_MMA(1, 1, At, B1); PG8_BAR; PG8_SCHED;
.LBB0_833:
	s_add_u32 s47, s44, s16
	s_addc_u32 s48, s45, s17
	s_and_b64 s[20:21], exec, s[20:21]
	s_cselect_b32 s21, s43, s48
	s_cselect_b32 s20, s42, s47
	s_add_i32 s47, s46, -3
	s_lshr_b32 s48, s47, 2
	s_mul_i32 s48, s48, 0x6000000
	s_add_u32 s48, s1, s48
	s_addc_u32 s49, s3, 0
	s_and_b32 s50, s16, 0x100
	s_add_u32 s48, s48, s50
	s_addc_u32 s49, s49, 0
	s_add_i32 s50, 0, 0x10000
	v_add_u32_e32 v137, s50, v144
	s_add_i32 s51, 0, 0x14000
	ds_read_b128 v[148:151], v137
	ds_read_b128 v[152:155], v137 offset:1024
	ds_read_b128 v[156:159], v137 offset:2048
	ds_read_b128 v[160:163], v137 offset:3072
	v_add_u32_e32 v137, s51, v144
	ds_read_b128 v[164:167], v137
	ds_read_b128 v[168:171], v137 offset:1024
	ds_read_b128 v[172:175], v137 offset:2048
	ds_read_b128 v[176:179], v137 offset:3072
	s_add_u32 s48, s48, 0x10080
	s_addc_u32 s49, s49, 0
	v_lshl_add_u64 v[140:141], s[48:49], 0, v[128:129]
	s_add_i32 m0, s27, 0xc000
	ds_read_b128 v[180:183], v142
	ds_read_b128 v[184:187], v142 offset:1024
	ds_read_b128 v[188:191], v142 offset:2048
	ds_read_b128 v[192:195], v142 offset:3072
	ds_read_b128 v[196:199], v142 offset:4096
	ds_read_b128 v[200:203], v142 offset:5120
	ds_read_b128 v[204:207], v142 offset:6144
	ds_read_b128 v[218:221], v142 offset:7168
	global_load_lds_dwordx4 v[140:141], off
	v_lshl_add_u64 v[140:141], s[48:49], 0, v[130:131]
	s_add_i32 m0, s27, 0xe000
	s_nop 0
	global_load_lds_dwordx4 v[140:141], off
	s_waitcnt vmcnt(8)
	s_waitcnt lgkmcnt(0)
	s_barrier
	s_setprio 1
	s_waitcnt lgkmcnt(0)
	v_mfma_f32_16x16x32_bf16 v[124:127], v[148:151], v[180:183], v[124:127]
	v_mfma_f32_16x16x32_bf16 v[120:123], v[156:159], v[180:183], v[120:123]
	v_mfma_f32_16x16x32_bf16 v[108:111], v[148:151], v[188:191], v[108:111]
	v_mfma_f32_16x16x32_bf16 v[104:107], v[156:159], v[188:191], v[104:107]
	v_mfma_f32_16x16x32_bf16 v[92:95], v[148:151], v[196:199], v[92:95]
	v_mfma_f32_16x16x32_bf16 v[88:91], v[156:159], v[196:199], v[88:91]
	v_mfma_f32_16x16x32_bf16 v[76:79], v[148:151], v[204:207], v[76:79]
	v_mfma_f32_16x16x32_bf16 v[72:75], v[156:159], v[204:207], v[72:75]
	v_mfma_f32_16x16x32_bf16 v[124:127], v[152:155], v[184:187], v[124:127]
	v_mfma_f32_16x16x32_bf16 v[120:123], v[160:163], v[184:187], v[120:123]
	v_mfma_f32_16x16x32_bf16 v[108:111], v[152:155], v[192:195], v[108:111]
	v_mfma_f32_16x16x32_bf16 v[104:107], v[160:163], v[192:195], v[104:107]
	v_mfma_f32_16x16x32_bf16 v[92:95], v[152:155], v[200:203], v[92:95]
	v_mfma_f32_16x16x32_bf16 v[88:91], v[160:163], v[200:203], v[88:91]
	v_mfma_f32_16x16x32_bf16 v[76:79], v[152:155], v[218:221], v[76:79]
	v_mfma_f32_16x16x32_bf16 v[72:75], v[160:163], v[218:221], v[72:75]
	s_setprio 0
	s_setprio 1
	v_mfma_f32_16x16x32_bf16 v[116:119], v[164:167], v[180:183], v[116:119]
	v_mfma_f32_16x16x32_bf16 v[112:115], v[172:175], v[180:183], v[112:115]
	v_mfma_f32_16x16x32_bf16 v[100:103], v[164:167], v[188:191], v[100:103]
	v_mfma_f32_16x16x32_bf16 v[96:99], v[172:175], v[188:191], v[96:99]
	v_mfma_f32_16x16x32_bf16 v[84:87], v[164:167], v[196:199], v[84:87]
	v_mfma_f32_16x16x32_bf16 v[80:83], v[172:175], v[196:199], v[80:83]
	v_mfma_f32_16x16x32_bf16 v[68:71], v[164:167], v[204:207], v[68:71]
	v_mfma_f32_16x16x32_bf16 v[64:67], v[172:175], v[204:207], v[64:67]
	v_mfma_f32_16x16x32_bf16 v[116:119], v[168:171], v[184:187], v[116:119]
	v_mfma_f32_16x16x32_bf16 v[112:115], v[176:179], v[184:187], v[112:115]
	v_mfma_f32_16x16x32_bf16 v[100:103], v[168:171], v[192:195], v[100:103]
	v_mfma_f32_16x16x32_bf16 v[96:99], v[176:179], v[192:195], v[96:99]
	s_barrier
	v_mfma_f32_16x16x32_bf16 v[84:87], v[168:171], v[200:203], v[84:87]
	v_mfma_f32_16x16x32_bf16 v[80:83], v[176:179], v[200:203], v[80:83]
	v_mfma_f32_16x16x32_bf16 v[68:71], v[168:171], v[218:221], v[68:71]
	v_mfma_f32_16x16x32_bf16 v[64:67], v[176:179], v[218:221], v[64:67]
	s_setprio 0
	s_add_i32 s48, s50, s26
	v_lshl_add_u64 v[140:141], s[20:21], 0, v[134:135]
	s_mov_b32 m0, s48
	ds_read_b128 v[180:183], v142 offset:16384
	ds_read_b128 v[184:187], v142 offset:17408
	ds_read_b128 v[188:191], v142 offset:18432
	ds_read_b128 v[192:195], v142 offset:19456
	ds_read_b128 v[196:199], v142 offset:20480
	ds_read_b128 v[200:203], v142 offset:21504
	ds_read_b128 v[204:207], v142 offset:22528
	ds_read_b128 v[218:221], v142 offset:23552
	global_load_lds_dwordx4 v[140:141], off
	s_add_i32 m0, s48, 0x2000
	s_add_u32 s48, s20, 0x20000
	v_lshl_add_u64 v[222:223], s[20:21], 0, v[132:133]
	s_addc_u32 s49, s21, 0
	s_add_i32 s50, s51, s26
	global_load_lds_dwordx4 v[222:223], off
	v_lshl_add_u64 v[224:225], s[48:49], 0, v[134:135]
	s_mov_b32 m0, s50
	s_nop 0
	global_load_lds_dwordx4 v[224:225], off
	v_lshl_add_u64 v[224:225], s[48:49], 0, v[132:133]
	s_add_i32 m0, s50, 0x2000
	s_nop 0
	global_load_lds_dwordx4 v[224:225], off
	v_lshl_add_u64 v[224:225], s[22:23], 0, v[128:129]
	s_mov_b32 m0, s27
	s_nop 0
	global_load_lds_dwordx4 v[224:225], off
	v_lshl_add_u64 v[224:225], s[22:23], 0, v[130:131]
	s_mov_b32 m0, s28
	s_nop 0
	global_load_lds_dwordx4 v[224:225], off
	s_waitcnt vmcnt(8)
	s_waitcnt lgkmcnt(0)
	s_barrier
;     __device__ __forceinline__ size_t hstep() const { return (size_t)HALF * K * 2; }
;     __device__ __forceinline__ const char* tile(const Unit& u, int t) const { return A + (size_t)u.pm * 2 * hstep() + (size_t)t * (BK * 2); }
;     __device__ __forceinline__ size_t hstep() const { return (size_t)HALF * 512; }
; #define PG8_STAGE(bufoff, gbase, voff) do { _Pragma("unroll") for (int _i = 0; _i < 2; ++_i) \
;         __builtin_amdgcn_global_load_lds((const unsigned*)((const char*)(gbase) + (voff)[_i]), (PG8_LAS unsigned*)(lds + (bufoff) + ldsw + _i * 8192), 16, 0, 0); } while (0)
; #define PG8_LDA(dst, b, h) do { _Pragma("unroll") for (int m = 0; m < 4; ++m) _Pragma("unroll") for (int k = 0; k < 2; ++k) dst[m][k] = *(const PG8_LAS bf16x8*)(lds + PG8_SA(b, h) + aoff + m * 2048 + k * 1024); } while (0)
; #define PG8_LDB(dst, b, h) do { _Pragma("unroll") for (int n = 0; n < 2; ++n) _Pragma("unroll") for (int k = 0; k < 2; ++k) dst[n][k] = *(const PG8_LAS bf16x8*)(lds + PG8_SB(b, h) + boff + n * 2048 + k * 1024); } while (0)
; #define PG8_MMA(ai, bj, At, Bt) do { __builtin_amdgcn_s_setprio(1); _Pragma("unroll") for (int m = 0; m < 4; ++m) _Pragma("unroll") for (int n = 0; n < 2; ++n) _Pragma("unroll") for (int k = 0; k < 2; ++k) \
;         acc[ai][bj][m][n] = __builtin_amdgcn_mfma_f32_16x16x32_bf16(Bt[n][k], At[m][k], acc[ai][bj][m][n], 0, 0, 0); __builtin_amdgcn_s_setprio(0); } while (0)
; #define PG8_WAIT_V(n) asm volatile("s_waitcnt vmcnt(" #n ")" ::: "memory")
; #define PG8_WAIT_L(n) asm volatile("s_waitcnt lgkmcnt(" #n ")" ::: "memory")
; #define PG8_BAR __builtin_amdgcn_s_barrier()
; #define PG8_SCHED __builtin_amdgcn_sched_barrier(0)
;     __device__ __forceinline__ const char* tile(const Unit& u, int t) const { return U + (long)(t >> 2) * xoff + (size_t)u.pn * (1024 * 512) + (size_t)u.pm * 2 * hstep() + (size_t)(t & 3) * (BK * 2); }
;     ...
;             PG8_WAIT_V(8); PG8_WAIT_L(0); PG8_BAR; PG8_MMA(1, 0, At, B0); PG8_MMA(1, 1, At, B1); PG8_BAR; PG8_SCHED;
;             PG8_LDB(B0, 1, 0); PG8_LDB(B1, 1, 1); PG8_SCHED; PG8_LDA(At, 1, 0); PG8_STAGE(PG8_SA(0, 1), a2 + hstepA, voffA);
;             PG8_WAIT_V(8); PG8_WAIT_L(0); PG8_BAR; PG8_MMA(0, 0, At, B0); PG8_MMA(0, 1, At, B1); PG8_BAR; PG8_SCHED;
	s_setprio 1
	s_waitcnt lgkmcnt(0)
	v_mfma_f32_16x16x32_bf16 v[60:63], v[148:151], v[180:183], v[60:63]
	v_mfma_f32_16x16x32_bf16 v[56:59], v[156:159], v[180:183], v[56:59]
	v_mfma_f32_16x16x32_bf16 v[44:47], v[148:151], v[188:191], v[44:47]
	v_mfma_f32_16x16x32_bf16 v[40:43], v[156:159], v[188:191], v[40:43]
	v_mfma_f32_16x16x32_bf16 v[28:31], v[148:151], v[196:199], v[28:31]
	v_mfma_f32_16x16x32_bf16 v[24:27], v[156:159], v[196:199], v[24:27]
	v_mfma_f32_16x16x32_bf16 v[12:15], v[148:151], v[204:207], v[12:15]
	v_mfma_f32_16x16x32_bf16 v[8:11], v[156:159], v[204:207], v[8:11]
	v_mfma_f32_16x16x32_bf16 v[60:63], v[152:155], v[184:187], v[60:63]
	v_mfma_f32_16x16x32_bf16 v[56:59], v[160:163], v[184:187], v[56:59]
	v_mfma_f32_16x16x32_bf16 v[44:47], v[152:155], v[192:195], v[44:47]
	v_mfma_f32_16x16x32_bf16 v[40:43], v[160:163], v[192:195], v[40:43]
	v_mfma_f32_16x16x32_bf16 v[28:31], v[152:155], v[200:203], v[28:31]
	v_mfma_f32_16x16x32_bf16 v[24:27], v[160:163], v[200:203], v[24:27]
	v_mfma_f32_16x16x32_bf16 v[12:15], v[152:155], v[218:221], v[12:15]
	v_mfma_f32_16x16x32_bf16 v[8:11], v[160:163], v[218:221], v[8:11]
	s_setprio 0
	s_setprio 1
	v_mfma_f32_16x16x32_bf16 v[52:55], v[164:167], v[180:183], v[52:55]
	v_mfma_f32_16x16x32_bf16 v[48:51], v[172:175], v[180:183], v[48:51]
	v_mfma_f32_16x16x32_bf16 v[36:39], v[164:167], v[188:191], v[36:39]
	v_mfma_f32_16x16x32_bf16 v[32:35], v[172:175], v[188:191], v[32:35]
	v_mfma_f32_16x16x32_bf16 v[20:23], v[164:167], v[196:199], v[20:23]
	v_mfma_f32_16x16x32_bf16 v[16:19], v[172:175], v[196:199], v[16:19]
	v_mfma_f32_16x16x32_bf16 v[4:7], v[164:167], v[204:207], v[4:7]
	v_mfma_f32_16x16x32_bf16 v[0:3], v[172:175], v[204:207], v[0:3]
	v_mfma_f32_16x16x32_bf16 v[52:55], v[168:171], v[184:187], v[52:55]
	v_mfma_f32_16x16x32_bf16 v[48:51], v[176:179], v[184:187], v[48:51]
	v_mfma_f32_16x16x32_bf16 v[36:39], v[168:171], v[192:195], v[36:39]
	v_mfma_f32_16x16x32_bf16 v[32:35], v[176:179], v[192:195], v[32:35]
	s_barrier
	v_mfma_f32_16x16x32_bf16 v[20:23], v[168:171], v[200:203], v[20:23]
	v_mfma_f32_16x16x32_bf16 v[16:19], v[176:179], v[200:203], v[16:19]
	v_mfma_f32_16x16x32_bf16 v[4:7], v[168:171], v[218:221], v[4:7]
	v_mfma_f32_16x16x32_bf16 v[0:3], v[176:179], v[218:221], v[0:3]
	s_setprio 0
	s_add_i32 s48, 0, 0x18000
	v_add_u32_e32 v137, s48, v144
	s_add_i32 s49, 0, 0x1c000
	ds_read_b128 v[148:151], v137
	ds_read_b128 v[152:155], v137 offset:1024
	ds_read_b128 v[156:159], v137 offset:2048
	ds_read_b128 v[160:163], v137 offset:3072
	v_add_u32_e32 v137, s49, v144
	ds_read_b128 v[164:167], v137
	ds_read_b128 v[168:171], v137 offset:1024
	ds_read_b128 v[172:175], v137 offset:2048
	ds_read_b128 v[176:179], v137 offset:3072
	s_add_u32 s22, s22, 0x10000
	s_addc_u32 s23, s23, 0
	s_mov_b32 m0, s29
	v_lshl_add_u64 v[224:225], s[22:23], 0, v[128:129]
	ds_read_b128 v[180:183], v142 offset:32768
	ds_read_b128 v[184:187], v142 offset:33792
	ds_read_b128 v[188:191], v142 offset:34816
	ds_read_b128 v[192:195], v142 offset:35840
	ds_read_b128 v[196:199], v142 offset:36864
	ds_read_b128 v[200:203], v142 offset:37888
	ds_read_b128 v[204:207], v142 offset:38912
	ds_read_b128 v[218:221], v142 offset:39936
	global_load_lds_dwordx4 v[224:225], off
	v_lshl_add_u64 v[224:225], s[22:23], 0, v[130:131]
	s_mov_b32 m0, s30
	s_nop 0
	global_load_lds_dwordx4 v[224:225], off
	s_waitcnt vmcnt(8)
	s_waitcnt lgkmcnt(0)
	s_barrier
	s_setprio 1
	s_waitcnt lgkmcnt(0)
	v_mfma_f32_16x16x32_bf16 v[124:127], v[148:151], v[180:183], v[124:127]
	v_mfma_f32_16x16x32_bf16 v[120:123], v[156:159], v[180:183], v[120:123]
	v_mfma_f32_16x16x32_bf16 v[108:111], v[148:151], v[188:191], v[108:111]
	v_mfma_f32_16x16x32_bf16 v[104:107], v[156:159], v[188:191], v[104:107]
	v_mfma_f32_16x16x32_bf16 v[92:95], v[148:151], v[196:199], v[92:95]
	v_mfma_f32_16x16x32_bf16 v[88:91], v[156:159], v[196:199], v[88:91]
	v_mfma_f32_16x16x32_bf16 v[76:79], v[148:151], v[204:207], v[76:79]
	v_mfma_f32_16x16x32_bf16 v[72:75], v[156:159], v[204:207], v[72:75]
	v_mfma_f32_16x16x32_bf16 v[124:127], v[152:155], v[184:187], v[124:127]
	v_mfma_f32_16x16x32_bf16 v[120:123], v[160:163], v[184:187], v[120:123]
	v_mfma_f32_16x16x32_bf16 v[108:111], v[152:155], v[192:195], v[108:111]
	v_mfma_f32_16x16x32_bf16 v[104:107], v[160:163], v[192:195], v[104:107]
	v_mfma_f32_16x16x32_bf16 v[92:95], v[152:155], v[200:203], v[92:95]
	v_mfma_f32_16x16x32_bf16 v[88:91], v[160:163], v[200:203], v[88:91]
	v_mfma_f32_16x16x32_bf16 v[76:79], v[152:155], v[218:221], v[76:79]
	v_mfma_f32_16x16x32_bf16 v[72:75], v[160:163], v[218:221], v[72:75]
	s_setprio 0
	s_setprio 1
	v_mfma_f32_16x16x32_bf16 v[116:119], v[164:167], v[180:183], v[116:119]
	v_mfma_f32_16x16x32_bf16 v[112:115], v[172:175], v[180:183], v[112:115]
	v_mfma_f32_16x16x32_bf16 v[100:103], v[164:167], v[188:191], v[100:103]
	v_mfma_f32_16x16x32_bf16 v[96:99], v[172:175], v[188:191], v[96:99]
	v_mfma_f32_16x16x32_bf16 v[84:87], v[164:167], v[196:199], v[84:87]
	v_mfma_f32_16x16x32_bf16 v[80:83], v[172:175], v[196:199], v[80:83]
	v_mfma_f32_16x16x32_bf16 v[68:71], v[164:167], v[204:207], v[68:71]
	v_mfma_f32_16x16x32_bf16 v[64:67], v[172:175], v[204:207], v[64:67]
	v_mfma_f32_16x16x32_bf16 v[116:119], v[168:171], v[184:187], v[116:119]
	v_mfma_f32_16x16x32_bf16 v[112:115], v[176:179], v[184:187], v[112:115]
	v_mfma_f32_16x16x32_bf16 v[100:103], v[168:171], v[192:195], v[100:103]
	v_mfma_f32_16x16x32_bf16 v[96:99], v[176:179], v[192:195], v[96:99]
	s_barrier
; #define PG8_STAGE(bufoff, gbase, voff) do { _Pragma("unroll") for (int _i = 0; _i < 2; ++_i) \
;         __builtin_amdgcn_global_load_lds((const unsigned*)((const char*)(gbase) + (voff)[_i]), (PG8_LAS unsigned*)(lds + (bufoff) + ldsw + _i * 8192), 16, 0, 0); } while (0)
; #define PG8_LDA(dst, b, h) do { _Pragma("unroll") for (int m = 0; m < 4; ++m) _Pragma("unroll") for (int k = 0; k < 2; ++k) dst[m][k] = *(const PG8_LAS bf16x8*)(lds + PG8_SA(b, h) + aoff + m * 2048 + k * 1024); } while (0)
; #define PG8_MMA(ai, bj, At, Bt) do { __builtin_amdgcn_s_setprio(1); _Pragma("unroll") for (int m = 0; m < 4; ++m) _Pragma("unroll") for (int n = 0; n < 2; ++n) _Pragma("unroll") for (int k = 0; k < 2; ++k) \
;         acc[ai][bj][m][n] = __builtin_amdgcn_mfma_f32_16x16x32_bf16(Bt[n][k], At[m][k], acc[ai][bj][m][n], 0, 0, 0); __builtin_amdgcn_s_setprio(0); } while (0)
; #define PG8_WAIT_V(n) asm volatile("s_waitcnt vmcnt(" #n ")" ::: "memory")
; #define PG8_WAIT_L(n) asm volatile("s_waitcnt lgkmcnt(" #n ")" ::: "memory")
; #define PG8_BAR __builtin_amdgcn_s_barrier()
; #define PG8_SCHED __builtin_amdgcn_sched_barrier(0)
;     ...
;             PG8_LDA(At, 1, 1); PG8_STAGE(PG8_SB(1, 0), b3, voffB); PG8_STAGE(PG8_SB(1, 1), b3 + hstepB, voffB); PG8_STAGE(PG8_SA(1, 0), a3, voffA);
;             PG8_WAIT_V(8); PG8_WAIT_L(0); PG8_BAR; PG8_MMA(1, 0, At, B0); PG8_MMA(1, 1, At, B1); PG8_BAR; PG8_SCHED;
;         }
;         if (wr == 0) PG8_BAR;
;         if (!has_next && wmat && gtid * 128u < wbytes) asm volatile("global_load_dword %0, %1, off" : "+v"(warmm) : "v"(wmat + (size_t)gtid * 128u) : "memory");
;         if (!has_next && warm) warmv = *(const volatile unsigned*)(warm + ((size_t)(tid & 255) * wK + (size_t)(tid >> 8) * BK) * 2);
;         if (ui == 0) hook();
	v_mfma_f32_16x16x32_bf16 v[84:87], v[168:171], v[200:203], v[84:87]
	v_mfma_f32_16x16x32_bf16 v[80:83], v[176:179], v[200:203], v[80:83]
	v_mfma_f32_16x16x32_bf16 v[68:71], v[168:171], v[218:221], v[68:71]
	v_mfma_f32_16x16x32_bf16 v[64:67], v[176:179], v[218:221], v[64:67]
	s_setprio 0
	s_mov_b64 s[50:51], 0x80
	s_add_i32 s22, s48, s26
	v_lshl_add_u64 v[140:141], v[140:141], 0, s[50:51]
	s_mov_b32 m0, s22
	ds_read_b128 v[180:183], v142 offset:49152
	ds_read_b128 v[184:187], v142 offset:50176
	ds_read_b128 v[188:191], v142 offset:51200
	ds_read_b128 v[192:195], v142 offset:52224
	ds_read_b128 v[196:199], v142 offset:53248
	ds_read_b128 v[200:203], v142 offset:54272
	ds_read_b128 v[204:207], v142 offset:55296
	ds_read_b128 v[218:221], v142 offset:56320
	global_load_lds_dwordx4 v[140:141], off
	s_add_i32 m0, s22, 0x2000
	s_add_u32 s20, s20, 0x20080
	v_lshl_add_u64 v[140:141], v[222:223], 0, s[50:51]
	s_addc_u32 s21, s21, 0
	s_add_i32 s22, s49, s26
	global_load_lds_dwordx4 v[140:141], off
	v_lshl_add_u64 v[140:141], s[20:21], 0, v[134:135]
	s_mov_b32 m0, s22
	s_nop 0
	global_load_lds_dwordx4 v[140:141], off
	v_lshl_add_u64 v[140:141], s[20:21], 0, v[132:133]
	s_add_i32 m0, s22, 0x2000
	s_nop 0
	global_load_lds_dwordx4 v[140:141], off
	v_lshl_add_u64 v[140:141], s[18:19], 0, v[128:129]
	s_mov_b32 m0, s31
	s_nop 0
	global_load_lds_dwordx4 v[140:141], off
	v_lshl_add_u64 v[140:141], s[18:19], 0, v[130:131]
	s_mov_b32 m0, s34
	s_nop 0
	global_load_lds_dwordx4 v[140:141], off
	s_waitcnt vmcnt(8)
	s_waitcnt lgkmcnt(0)
	s_barrier
	s_setprio 1
	s_waitcnt lgkmcnt(0)
	v_mfma_f32_16x16x32_bf16 v[60:63], v[148:151], v[180:183], v[60:63]
	v_mfma_f32_16x16x32_bf16 v[56:59], v[156:159], v[180:183], v[56:59]
	v_mfma_f32_16x16x32_bf16 v[44:47], v[148:151], v[188:191], v[44:47]
	v_mfma_f32_16x16x32_bf16 v[40:43], v[156:159], v[188:191], v[40:43]
	v_mfma_f32_16x16x32_bf16 v[28:31], v[148:151], v[196:199], v[28:31]
	v_mfma_f32_16x16x32_bf16 v[24:27], v[156:159], v[196:199], v[24:27]
	v_mfma_f32_16x16x32_bf16 v[12:15], v[148:151], v[204:207], v[12:15]
	v_mfma_f32_16x16x32_bf16 v[8:11], v[156:159], v[204:207], v[8:11]
	v_mfma_f32_16x16x32_bf16 v[60:63], v[152:155], v[184:187], v[60:63]
	v_mfma_f32_16x16x32_bf16 v[56:59], v[160:163], v[184:187], v[56:59]
	v_mfma_f32_16x16x32_bf16 v[44:47], v[152:155], v[192:195], v[44:47]
	v_mfma_f32_16x16x32_bf16 v[40:43], v[160:163], v[192:195], v[40:43]
	v_mfma_f32_16x16x32_bf16 v[28:31], v[152:155], v[200:203], v[28:31]
	v_mfma_f32_16x16x32_bf16 v[24:27], v[160:163], v[200:203], v[24:27]
	v_mfma_f32_16x16x32_bf16 v[12:15], v[152:155], v[218:221], v[12:15]
	v_mfma_f32_16x16x32_bf16 v[8:11], v[160:163], v[218:221], v[8:11]
	s_setprio 0
	s_setprio 1
	v_mfma_f32_16x16x32_bf16 v[52:55], v[164:167], v[180:183], v[52:55]
	v_mfma_f32_16x16x32_bf16 v[48:51], v[172:175], v[180:183], v[48:51]
	v_mfma_f32_16x16x32_bf16 v[36:39], v[164:167], v[188:191], v[36:39]
	v_mfma_f32_16x16x32_bf16 v[32:35], v[172:175], v[188:191], v[32:35]
	v_mfma_f32_16x16x32_bf16 v[20:23], v[164:167], v[196:199], v[20:23]
	v_mfma_f32_16x16x32_bf16 v[16:19], v[172:175], v[196:199], v[16:19]
	v_mfma_f32_16x16x32_bf16 v[4:7], v[164:167], v[204:207], v[4:7]
	v_mfma_f32_16x16x32_bf16 v[0:3], v[172:175], v[204:207], v[0:3]
	v_mfma_f32_16x16x32_bf16 v[52:55], v[168:171], v[184:187], v[52:55]
	v_mfma_f32_16x16x32_bf16 v[48:51], v[176:179], v[184:187], v[48:51]
	v_mfma_f32_16x16x32_bf16 v[36:39], v[168:171], v[192:195], v[36:39]
	v_mfma_f32_16x16x32_bf16 v[32:35], v[176:179], v[192:195], v[32:35]
	s_barrier
	v_mfma_f32_16x16x32_bf16 v[20:23], v[168:171], v[200:203], v[20:23]
	v_mfma_f32_16x16x32_bf16 v[16:19], v[176:179], v[200:203], v[16:19]
	v_mfma_f32_16x16x32_bf16 v[4:7], v[168:171], v[218:221], v[4:7]
	v_mfma_f32_16x16x32_bf16 v[0:3], v[176:179], v[218:221], v[0:3]
	s_setprio 0
	s_add_u32 s16, s16, 0x100
	s_addc_u32 s17, s17, 0
	s_add_i32 s46, s46, 2
	s_cmp_gt_u32 s47, 5
	s_cbranch_scc1 .LBB0_838
